# GEMM main loops: all per-segment s_setprio flips removed (priority sensitivity test)
# speedup vs baseline: 1.0040x; 1.0040x over previous
; #define PG8_STAGE(bufoff, gbase, voff) do { _Pragma("unroll") for (int _i = 0; _i < 2; ++_i) \
;         __builtin_amdgcn_global_load_lds((const unsigned*)((const char*)(gbase) + (voff)[_i]), (LAS unsigned*)(lds + (bufoff) + ldsw + _i * 8192), 16, 0, 0); } while (0)
; #define PG8_LDA(dst, b, h) do { _Pragma("unroll") for (int m = 0; m < 4; ++m) _Pragma("unroll") for (int k = 0; k < 2; ++k) dst[m][k] = *(const LAS bf16x8*)(lds + PG8_SA(b, h) + aoff + m * 2048 + k * 1024); } while (0)
; #define PG8_LDB(dst, b, h) do { _Pragma("unroll") for (int n = 0; n < 2; ++n) _Pragma("unroll") for (int k = 0; k < 2; ++k) dst[n][k] = *(const LAS bf16x8*)(lds + PG8_SB(b, h) + boff + n * 2048 + k * 1024); } while (0)
; #define PG8_MMA(ai, bj, At, Bt) do { __builtin_amdgcn_s_setprio(1); _Pragma("unroll") for (int m = 0; m < 4; ++m) _Pragma("unroll") for (int n = 0; n < 2; ++n) _Pragma("unroll") for (int k = 0; k < 2; ++k) \
;         acc[ai][bj][m][n] = mma16<I8>(Bt[n][k], At[m][k], acc[ai][bj][m][n]); __builtin_amdgcn_s_setprio(0); } while (0)
; #define PG8_WAIT_V(n) asm volatile("s_waitcnt vmcnt(" #n ")" ::: "memory")
; #define PG8_WAIT_L(n) asm volatile("s_waitcnt lgkmcnt(" #n ")" ::: "memory")
; #define PG8_BAR __builtin_amdgcn_s_barrier()
; #define PG8_SCHED __builtin_amdgcn_sched_barrier(0)
; template <class Epi, class Sched, bool I8 = false>
; __device__ __forceinline__ void gemm_phase(LAS unsigned char* lds, const Gemm g, const Sched& S, const Epi& E) {
;     ...
;             PG8_LDB(B0, 0, 0); PG8_LDB(B1, 0, 1); PG8_SCHED; PG8_LDA(At, 0, 0); PG8_STAGE(PG8_SA(1, 1), a1 + hstepA, voffA);
;             PG8_WAIT_V(8); PG8_WAIT_L(0); PG8_BAR; PG8_MMA(0, 0, At, B0); PG8_MMA(0, 1, At, B1); PG8_BAR; PG8_SCHED;
;             PG8_LDA(At, 0, 1); PG8_STAGE(PG8_SB(0, 0), b2, voffB); PG8_STAGE(PG8_SB(0, 1), b2 + hstepB, voffB); PG8_STAGE(PG8_SA(0, 0), a2, voffA);
;             PG8_WAIT_V(8); PG8_WAIT_L(0); PG8_BAR; PG8_MMA(1, 0, At, B0); PG8_MMA(1, 1, At, B1); PG8_BAR; PG8_SCHED;
.LBB0_281:
	s_add_i32 s4, s0, 0xff840080
	s_cmp_lg_u32 s24, 28
	s_cselect_b32 s4, s4, 0
	s_add_u32 s6, s34, s4
	s_addc_u32 s7, s35, 0
	s_add_i32 s25, 0, 0x10000
	s_add_u32 s4, s30, s4
	s_addc_u32 s5, s31, 0
	s_add_i32 s29, 0, 0x14000
	v_add_u32_e32 v158, s25, v144
	v_add_u32_e32 v174, s29, v144
	ds_read_b128 v[146:149], v158
	ds_read_b128 v[150:153], v158 offset:1024
	ds_read_b128 v[154:157], v158 offset:2048
	ds_read_b128 v[158:161], v158 offset:3072
	ds_read_b128 v[162:165], v174
	ds_read_b128 v[166:169], v174 offset:1024
	ds_read_b128 v[170:173], v174 offset:2048
	ds_read_b128 v[174:177], v174 offset:3072
	v_lshl_add_u64 v[202:203], v[138:139], 0, s[0:1]
	s_add_i32 m0, s8, 0xc000
	ds_read_b128 v[178:181], v145
	ds_read_b128 v[182:185], v145 offset:1024
	ds_read_b128 v[186:189], v145 offset:2048
	ds_read_b128 v[190:193], v145 offset:3072
	ds_read_b128 v[194:197], v145 offset:4096
	ds_read_b128 v[198:201], v145 offset:5120
	ds_read_b128 v[212:215], v145 offset:6144
	ds_read_b128 v[216:219], v145 offset:7168
	global_load_lds_dwordx4 v[202:203], off
	v_lshl_add_u64 v[202:203], v[140:141], 0, s[0:1]
	s_add_i32 m0, s8, 0xe000
	s_nop 0
	global_load_lds_dwordx4 v[202:203], off
	s_waitcnt vmcnt(8)
	s_waitcnt lgkmcnt(0)
	s_barrier
	s_waitcnt lgkmcnt(0)
	v_mfma_f32_16x16x32_bf16 v[126:129], v[146:149], v[178:181], v[126:129]
	v_mfma_f32_16x16x32_bf16 v[122:125], v[154:157], v[178:181], v[122:125]
	v_mfma_f32_16x16x32_bf16 v[110:113], v[146:149], v[186:189], v[110:113]
	v_mfma_f32_16x16x32_bf16 v[106:109], v[154:157], v[186:189], v[106:109]
	v_mfma_f32_16x16x32_bf16 v[94:97], v[146:149], v[194:197], v[94:97]
	v_mfma_f32_16x16x32_bf16 v[90:93], v[154:157], v[194:197], v[90:93]
	v_mfma_f32_16x16x32_bf16 v[78:81], v[146:149], v[212:215], v[78:81]
	v_mfma_f32_16x16x32_bf16 v[74:77], v[154:157], v[212:215], v[74:77]
	v_mfma_f32_16x16x32_bf16 v[126:129], v[150:153], v[182:185], v[126:129]
	v_mfma_f32_16x16x32_bf16 v[122:125], v[158:161], v[182:185], v[122:125]
	v_mfma_f32_16x16x32_bf16 v[110:113], v[150:153], v[190:193], v[110:113]
	v_mfma_f32_16x16x32_bf16 v[106:109], v[158:161], v[190:193], v[106:109]
	v_mfma_f32_16x16x32_bf16 v[94:97], v[150:153], v[198:201], v[94:97]
	v_mfma_f32_16x16x32_bf16 v[90:93], v[158:161], v[198:201], v[90:93]
	v_mfma_f32_16x16x32_bf16 v[78:81], v[150:153], v[216:219], v[78:81]
	v_mfma_f32_16x16x32_bf16 v[74:77], v[158:161], v[216:219], v[74:77]
	v_mfma_f32_16x16x32_bf16 v[118:121], v[162:165], v[178:181], v[118:121]
	v_mfma_f32_16x16x32_bf16 v[114:117], v[170:173], v[178:181], v[114:117]
	v_mfma_f32_16x16x32_bf16 v[102:105], v[162:165], v[186:189], v[102:105]
	v_mfma_f32_16x16x32_bf16 v[98:101], v[170:173], v[186:189], v[98:101]
	v_mfma_f32_16x16x32_bf16 v[86:89], v[162:165], v[194:197], v[86:89]
	v_mfma_f32_16x16x32_bf16 v[82:85], v[170:173], v[194:197], v[82:85]
	v_mfma_f32_16x16x32_bf16 v[70:73], v[162:165], v[212:215], v[70:73]
	v_mfma_f32_16x16x32_bf16 v[66:69], v[170:173], v[212:215], v[66:69]
	v_mfma_f32_16x16x32_bf16 v[118:121], v[166:169], v[182:185], v[118:121]
	v_mfma_f32_16x16x32_bf16 v[114:117], v[174:177], v[182:185], v[114:117]
	v_mfma_f32_16x16x32_bf16 v[102:105], v[166:169], v[190:193], v[102:105]
	v_mfma_f32_16x16x32_bf16 v[98:101], v[174:177], v[190:193], v[98:101]
	v_mfma_f32_16x16x32_bf16 v[86:89], v[166:169], v[198:201], v[86:89]
	v_mfma_f32_16x16x32_bf16 v[82:85], v[174:177], v[198:201], v[82:85]
	v_mfma_f32_16x16x32_bf16 v[70:73], v[166:169], v[216:219], v[70:73]
	v_mfma_f32_16x16x32_bf16 v[66:69], v[174:177], v[216:219], v[66:69]
	s_barrier
	s_add_i32 s25, s25, s3
	v_lshl_add_u64 v[202:203], s[4:5], 0, v[130:131]
	s_mov_b32 m0, s25
	ds_read_b128 v[178:181], v145 offset:16384
	ds_read_b128 v[182:185], v145 offset:17408
	ds_read_b128 v[186:189], v145 offset:18432
	ds_read_b128 v[190:193], v145 offset:19456
	ds_read_b128 v[194:197], v145 offset:20480
	ds_read_b128 v[198:201], v145 offset:21504
	ds_read_b128 v[212:215], v145 offset:22528
	ds_read_b128 v[216:219], v145 offset:23552
	global_load_lds_dwordx4 v[202:203], off
	s_add_i32 m0, s25, 0x2000
	s_add_u32 s26, s4, 0x20000
	v_lshl_add_u64 v[220:221], s[4:5], 0, v[132:133]
	s_addc_u32 s27, s5, 0
	s_add_i32 s25, s29, s3
	global_load_lds_dwordx4 v[220:221], off
	v_lshl_add_u64 v[222:223], s[26:27], 0, v[130:131]
	s_mov_b32 m0, s25
	v_lshl_add_u64 v[224:225], s[6:7], 0, v[134:135]
	global_load_lds_dwordx4 v[222:223], off
	v_lshl_add_u64 v[222:223], s[26:27], 0, v[132:133]
	s_add_i32 m0, s25, 0x2000
	s_nop 0
	global_load_lds_dwordx4 v[222:223], off
	v_lshl_add_u64 v[222:223], s[6:7], 0, v[136:137]
	s_mov_b32 m0, s8
	s_nop 0
	global_load_lds_dwordx4 v[222:223], off
	s_mov_b32 m0, s9
	s_nop 0
	global_load_lds_dwordx4 v[224:225], off
	s_waitcnt vmcnt(8)
	s_waitcnt lgkmcnt(0)
	s_barrier
; #define PG8_STAGE(bufoff, gbase, voff) do { _Pragma("unroll") for (int _i = 0; _i < 2; ++_i) \
;         __builtin_amdgcn_global_load_lds((const unsigned*)((const char*)(gbase) + (voff)[_i]), (LAS unsigned*)(lds + (bufoff) + ldsw + _i * 8192), 16, 0, 0); } while (0)
; #define PG8_LDA(dst, b, h) do { _Pragma("unroll") for (int m = 0; m < 4; ++m) _Pragma("unroll") for (int k = 0; k < 2; ++k) dst[m][k] = *(const LAS bf16x8*)(lds + PG8_SA(b, h) + aoff + m * 2048 + k * 1024); } while (0)
; #define PG8_LDB(dst, b, h) do { _Pragma("unroll") for (int n = 0; n < 2; ++n) _Pragma("unroll") for (int k = 0; k < 2; ++k) dst[n][k] = *(const LAS bf16x8*)(lds + PG8_SB(b, h) + boff + n * 2048 + k * 1024); } while (0)
; #define PG8_MMA(ai, bj, At, Bt) do { __builtin_amdgcn_s_setprio(1); _Pragma("unroll") for (int m = 0; m < 4; ++m) _Pragma("unroll") for (int n = 0; n < 2; ++n) _Pragma("unroll") for (int k = 0; k < 2; ++k) \
;         acc[ai][bj][m][n] = mma16<I8>(Bt[n][k], At[m][k], acc[ai][bj][m][n]); __builtin_amdgcn_s_setprio(0); } while (0)
; #define PG8_WAIT_V(n) asm volatile("s_waitcnt vmcnt(" #n ")" ::: "memory")
; #define PG8_WAIT_L(n) asm volatile("s_waitcnt lgkmcnt(" #n ")" ::: "memory")
; #define PG8_BAR __builtin_amdgcn_s_barrier()
; #define PG8_SCHED __builtin_amdgcn_sched_barrier(0)
; template <class Epi, class Sched, bool I8 = false>
; __device__ __forceinline__ void gemm_phase(LAS unsigned char* lds, const Gemm g, const Sched& S, const Epi& E) {
;     ...
;             PG8_WAIT_V(8); PG8_WAIT_L(0); PG8_BAR; PG8_MMA(1, 0, At, B0); PG8_MMA(1, 1, At, B1); PG8_BAR; PG8_SCHED;
;             PG8_LDB(B0, 1, 0); PG8_LDB(B1, 1, 1); PG8_SCHED; PG8_LDA(At, 1, 0); PG8_STAGE(PG8_SA(0, 1), a2 + hstepA, voffA);
;             PG8_WAIT_V(8); PG8_WAIT_L(0); PG8_BAR; PG8_MMA(0, 0, At, B0); PG8_MMA(0, 1, At, B1); PG8_BAR; PG8_SCHED;
	s_waitcnt lgkmcnt(0)
	v_mfma_f32_16x16x32_bf16 v[62:65], v[146:149], v[178:181], v[62:65]
	v_mfma_f32_16x16x32_bf16 v[58:61], v[154:157], v[178:181], v[58:61]
	v_mfma_f32_16x16x32_bf16 v[46:49], v[146:149], v[186:189], v[46:49]
	v_mfma_f32_16x16x32_bf16 v[42:45], v[154:157], v[186:189], v[42:45]
	v_mfma_f32_16x16x32_bf16 v[30:33], v[146:149], v[194:197], v[30:33]
	v_mfma_f32_16x16x32_bf16 v[26:29], v[154:157], v[194:197], v[26:29]
	v_mfma_f32_16x16x32_bf16 v[14:17], v[146:149], v[212:215], v[14:17]
	v_mfma_f32_16x16x32_bf16 v[10:13], v[154:157], v[212:215], v[10:13]
	v_mfma_f32_16x16x32_bf16 v[62:65], v[150:153], v[182:185], v[62:65]
	v_mfma_f32_16x16x32_bf16 v[58:61], v[158:161], v[182:185], v[58:61]
	v_mfma_f32_16x16x32_bf16 v[46:49], v[150:153], v[190:193], v[46:49]
	v_mfma_f32_16x16x32_bf16 v[42:45], v[158:161], v[190:193], v[42:45]
	v_mfma_f32_16x16x32_bf16 v[30:33], v[150:153], v[198:201], v[30:33]
	v_mfma_f32_16x16x32_bf16 v[26:29], v[158:161], v[198:201], v[26:29]
	v_mfma_f32_16x16x32_bf16 v[14:17], v[150:153], v[216:219], v[14:17]
	v_mfma_f32_16x16x32_bf16 v[10:13], v[158:161], v[216:219], v[10:13]
	v_mfma_f32_16x16x32_bf16 v[54:57], v[162:165], v[178:181], v[54:57]
	v_mfma_f32_16x16x32_bf16 v[50:53], v[170:173], v[178:181], v[50:53]
	v_mfma_f32_16x16x32_bf16 v[38:41], v[162:165], v[186:189], v[38:41]
	v_mfma_f32_16x16x32_bf16 v[34:37], v[170:173], v[186:189], v[34:37]
	v_mfma_f32_16x16x32_bf16 v[22:25], v[162:165], v[194:197], v[22:25]
	v_mfma_f32_16x16x32_bf16 v[18:21], v[170:173], v[194:197], v[18:21]
	v_mfma_f32_16x16x32_bf16 v[6:9], v[162:165], v[212:215], v[6:9]
	v_mfma_f32_16x16x32_bf16 v[2:5], v[170:173], v[212:215], v[2:5]
	v_mfma_f32_16x16x32_bf16 v[54:57], v[166:169], v[182:185], v[54:57]
	v_mfma_f32_16x16x32_bf16 v[50:53], v[174:177], v[182:185], v[50:53]
	v_mfma_f32_16x16x32_bf16 v[38:41], v[166:169], v[190:193], v[38:41]
	v_mfma_f32_16x16x32_bf16 v[34:37], v[174:177], v[190:193], v[34:37]
	v_mfma_f32_16x16x32_bf16 v[22:25], v[166:169], v[198:201], v[22:25]
	v_mfma_f32_16x16x32_bf16 v[18:21], v[174:177], v[198:201], v[18:21]
	v_mfma_f32_16x16x32_bf16 v[6:9], v[166:169], v[216:219], v[6:9]
	v_mfma_f32_16x16x32_bf16 v[2:5], v[174:177], v[216:219], v[2:5]
	s_barrier
	s_add_i32 s25, 0, 0x18000
	s_add_i32 s26, 0, 0x1c000
	v_add_u32_e32 v158, s25, v144
	v_add_u32_e32 v174, s26, v144
	ds_read_b128 v[146:149], v158
	ds_read_b128 v[150:153], v158 offset:1024
	ds_read_b128 v[154:157], v158 offset:2048
	ds_read_b128 v[158:161], v158 offset:3072
	ds_read_b128 v[162:165], v174
	ds_read_b128 v[166:169], v174 offset:1024
	ds_read_b128 v[170:173], v174 offset:2048
	ds_read_b128 v[174:177], v174 offset:3072
	s_add_u32 s6, s6, 0x80000
	s_addc_u32 s7, s7, 0
	s_mov_b32 m0, s14
	v_lshl_add_u64 v[226:227], s[6:7], 0, v[136:137]
	ds_read_b128 v[178:181], v145 offset:32768
	ds_read_b128 v[182:185], v145 offset:33792
	ds_read_b128 v[186:189], v145 offset:34816
	ds_read_b128 v[190:193], v145 offset:35840
	ds_read_b128 v[194:197], v145 offset:36864
	ds_read_b128 v[198:201], v145 offset:37888
	ds_read_b128 v[212:215], v145 offset:38912
	ds_read_b128 v[216:219], v145 offset:39936
	global_load_lds_dwordx4 v[226:227], off
	v_lshl_add_u64 v[226:227], s[6:7], 0, v[134:135]
	s_mov_b32 m0, s16
	s_nop 0
	global_load_lds_dwordx4 v[226:227], off
	s_waitcnt vmcnt(8)
	s_waitcnt lgkmcnt(0)
	s_barrier
	s_waitcnt lgkmcnt(0)
	v_mfma_f32_16x16x32_bf16 v[126:129], v[146:149], v[178:181], v[126:129]
	v_mfma_f32_16x16x32_bf16 v[122:125], v[154:157], v[178:181], v[122:125]
	v_mfma_f32_16x16x32_bf16 v[110:113], v[146:149], v[186:189], v[110:113]
	v_mfma_f32_16x16x32_bf16 v[106:109], v[154:157], v[186:189], v[106:109]
	v_mfma_f32_16x16x32_bf16 v[94:97], v[146:149], v[194:197], v[94:97]
	v_mfma_f32_16x16x32_bf16 v[90:93], v[154:157], v[194:197], v[90:93]
	v_mfma_f32_16x16x32_bf16 v[78:81], v[146:149], v[212:215], v[78:81]
	v_mfma_f32_16x16x32_bf16 v[74:77], v[154:157], v[212:215], v[74:77]
	v_mfma_f32_16x16x32_bf16 v[126:129], v[150:153], v[182:185], v[126:129]
	v_mfma_f32_16x16x32_bf16 v[122:125], v[158:161], v[182:185], v[122:125]
	v_mfma_f32_16x16x32_bf16 v[110:113], v[150:153], v[190:193], v[110:113]
	v_mfma_f32_16x16x32_bf16 v[106:109], v[158:161], v[190:193], v[106:109]
	v_mfma_f32_16x16x32_bf16 v[94:97], v[150:153], v[198:201], v[94:97]
	v_mfma_f32_16x16x32_bf16 v[90:93], v[158:161], v[198:201], v[90:93]
	v_mfma_f32_16x16x32_bf16 v[78:81], v[150:153], v[216:219], v[78:81]
	v_mfma_f32_16x16x32_bf16 v[74:77], v[158:161], v[216:219], v[74:77]
	v_mfma_f32_16x16x32_bf16 v[118:121], v[162:165], v[178:181], v[118:121]
	v_mfma_f32_16x16x32_bf16 v[114:117], v[170:173], v[178:181], v[114:117]
	v_mfma_f32_16x16x32_bf16 v[102:105], v[162:165], v[186:189], v[102:105]
	v_mfma_f32_16x16x32_bf16 v[98:101], v[170:173], v[186:189], v[98:101]
	v_mfma_f32_16x16x32_bf16 v[86:89], v[162:165], v[194:197], v[86:89]
	v_mfma_f32_16x16x32_bf16 v[82:85], v[170:173], v[194:197], v[82:85]
	v_mfma_f32_16x16x32_bf16 v[70:73], v[162:165], v[212:215], v[70:73]
	v_mfma_f32_16x16x32_bf16 v[66:69], v[170:173], v[212:215], v[66:69]
	v_mfma_f32_16x16x32_bf16 v[118:121], v[166:169], v[182:185], v[118:121]
	v_mfma_f32_16x16x32_bf16 v[114:117], v[174:177], v[182:185], v[114:117]
	v_mfma_f32_16x16x32_bf16 v[102:105], v[166:169], v[190:193], v[102:105]
	v_mfma_f32_16x16x32_bf16 v[98:101], v[174:177], v[190:193], v[98:101]
	v_mfma_f32_16x16x32_bf16 v[86:89], v[166:169], v[198:201], v[86:89]
	v_mfma_f32_16x16x32_bf16 v[82:85], v[174:177], v[198:201], v[82:85]
	v_mfma_f32_16x16x32_bf16 v[70:73], v[166:169], v[216:219], v[70:73]
	v_mfma_f32_16x16x32_bf16 v[66:69], v[174:177], v[216:219], v[66:69]
	s_barrier
; #define PG8_STAGE(bufoff, gbase, voff) do { _Pragma("unroll") for (int _i = 0; _i < 2; ++_i) \
;         __builtin_amdgcn_global_load_lds((const unsigned*)((const char*)(gbase) + (voff)[_i]), (LAS unsigned*)(lds + (bufoff) + ldsw + _i * 8192), 16, 0, 0); } while (0)
; #define PG8_LDA(dst, b, h) do { _Pragma("unroll") for (int m = 0; m < 4; ++m) _Pragma("unroll") for (int k = 0; k < 2; ++k) dst[m][k] = *(const LAS bf16x8*)(lds + PG8_SA(b, h) + aoff + m * 2048 + k * 1024); } while (0)
; #define PG8_MMA(ai, bj, At, Bt) do { __builtin_amdgcn_s_setprio(1); _Pragma("unroll") for (int m = 0; m < 4; ++m) _Pragma("unroll") for (int n = 0; n < 2; ++n) _Pragma("unroll") for (int k = 0; k < 2; ++k) \
;         acc[ai][bj][m][n] = mma16<I8>(Bt[n][k], At[m][k], acc[ai][bj][m][n]); __builtin_amdgcn_s_setprio(0); } while (0)
; #define PG8_WAIT_V(n) asm volatile("s_waitcnt vmcnt(" #n ")" ::: "memory")
; #define PG8_WAIT_L(n) asm volatile("s_waitcnt lgkmcnt(" #n ")" ::: "memory")
; #define PG8_BAR __builtin_amdgcn_s_barrier()
; #define PG8_SCHED __builtin_amdgcn_sched_barrier(0)
; template <class Epi, class Sched, bool I8 = false>
; __device__ __forceinline__ void gemm_phase(LAS unsigned char* lds, const Gemm g, const Sched& S, const Epi& E) {
;     ...
;             PG8_LDA(At, 1, 1); PG8_STAGE(PG8_SB(1, 0), b3, voffB); PG8_STAGE(PG8_SB(1, 1), b3 + hstepB, voffB); PG8_STAGE(PG8_SA(1, 0), a3, voffA);
;             PG8_WAIT_V(8); PG8_WAIT_L(0); PG8_BAR; PG8_MMA(1, 0, At, B0); PG8_MMA(1, 1, At, B1); PG8_BAR; PG8_SCHED;
;     ...
;         if (PG8_ALIGN) { if (wr == 0) PG8_BAR; }
	s_add_i32 s6, s25, s3
	v_lshl_add_u64 v[202:203], v[202:203], 0, s[12:13]
	s_mov_b32 m0, s6
	ds_read_b128 v[178:181], v145 offset:49152
	ds_read_b128 v[182:185], v145 offset:50176
	ds_read_b128 v[186:189], v145 offset:51200
	ds_read_b128 v[190:193], v145 offset:52224
	ds_read_b128 v[194:197], v145 offset:53248
	ds_read_b128 v[198:201], v145 offset:54272
	ds_read_b128 v[212:215], v145 offset:55296
	ds_read_b128 v[216:219], v145 offset:56320
	global_load_lds_dwordx4 v[202:203], off
	s_add_i32 m0, s6, 0x2000
	s_add_u32 s4, s4, 0x20080
	v_lshl_add_u64 v[202:203], v[220:221], 0, s[12:13]
	s_addc_u32 s5, s5, 0
	s_add_i32 s6, s26, s3
	global_load_lds_dwordx4 v[202:203], off
	v_lshl_add_u64 v[202:203], s[4:5], 0, v[130:131]
	s_mov_b32 m0, s6
	s_nop 0
	global_load_lds_dwordx4 v[202:203], off
	v_lshl_add_u64 v[202:203], s[4:5], 0, v[132:133]
	s_add_i32 m0, s6, 0x2000
	s_nop 0
	global_load_lds_dwordx4 v[202:203], off
	v_lshl_add_u64 v[202:203], v[222:223], 0, s[12:13]
	s_mov_b32 m0, s22
	s_nop 0
	global_load_lds_dwordx4 v[202:203], off
	v_lshl_add_u64 v[202:203], v[224:225], 0, s[12:13]
	s_mov_b32 m0, s23
	s_nop 0
	global_load_lds_dwordx4 v[202:203], off
	s_waitcnt vmcnt(8)
	s_waitcnt lgkmcnt(0)
	s_barrier
	s_waitcnt lgkmcnt(0)
	v_mfma_f32_16x16x32_bf16 v[62:65], v[146:149], v[178:181], v[62:65]
	v_mfma_f32_16x16x32_bf16 v[58:61], v[154:157], v[178:181], v[58:61]
	v_mfma_f32_16x16x32_bf16 v[46:49], v[146:149], v[186:189], v[46:49]
	v_mfma_f32_16x16x32_bf16 v[42:45], v[154:157], v[186:189], v[42:45]
	v_mfma_f32_16x16x32_bf16 v[30:33], v[146:149], v[194:197], v[30:33]
	v_mfma_f32_16x16x32_bf16 v[26:29], v[154:157], v[194:197], v[26:29]
	v_mfma_f32_16x16x32_bf16 v[14:17], v[146:149], v[212:215], v[14:17]
	v_mfma_f32_16x16x32_bf16 v[10:13], v[154:157], v[212:215], v[10:13]
	v_mfma_f32_16x16x32_bf16 v[62:65], v[150:153], v[182:185], v[62:65]
	v_mfma_f32_16x16x32_bf16 v[58:61], v[158:161], v[182:185], v[58:61]
	v_mfma_f32_16x16x32_bf16 v[46:49], v[150:153], v[190:193], v[46:49]
	v_mfma_f32_16x16x32_bf16 v[42:45], v[158:161], v[190:193], v[42:45]
	v_mfma_f32_16x16x32_bf16 v[30:33], v[150:153], v[198:201], v[30:33]
	v_mfma_f32_16x16x32_bf16 v[26:29], v[158:161], v[198:201], v[26:29]
	v_mfma_f32_16x16x32_bf16 v[14:17], v[150:153], v[216:219], v[14:17]
	v_mfma_f32_16x16x32_bf16 v[10:13], v[158:161], v[216:219], v[10:13]
	v_mfma_f32_16x16x32_bf16 v[54:57], v[162:165], v[178:181], v[54:57]
	v_mfma_f32_16x16x32_bf16 v[50:53], v[170:173], v[178:181], v[50:53]
	v_mfma_f32_16x16x32_bf16 v[38:41], v[162:165], v[186:189], v[38:41]
	v_mfma_f32_16x16x32_bf16 v[34:37], v[170:173], v[186:189], v[34:37]
	v_mfma_f32_16x16x32_bf16 v[22:25], v[162:165], v[194:197], v[22:25]
	v_mfma_f32_16x16x32_bf16 v[18:21], v[170:173], v[194:197], v[18:21]
	v_mfma_f32_16x16x32_bf16 v[6:9], v[162:165], v[212:215], v[6:9]
	v_mfma_f32_16x16x32_bf16 v[2:5], v[170:173], v[212:215], v[2:5]
	v_mfma_f32_16x16x32_bf16 v[54:57], v[166:169], v[182:185], v[54:57]
	v_mfma_f32_16x16x32_bf16 v[50:53], v[174:177], v[182:185], v[50:53]
	v_mfma_f32_16x16x32_bf16 v[38:41], v[166:169], v[190:193], v[38:41]
	v_mfma_f32_16x16x32_bf16 v[34:37], v[174:177], v[190:193], v[34:37]
	v_mfma_f32_16x16x32_bf16 v[22:25], v[166:169], v[198:201], v[22:25]
	v_mfma_f32_16x16x32_bf16 v[18:21], v[174:177], v[198:201], v[18:21]
	v_mfma_f32_16x16x32_bf16 v[6:9], v[166:169], v[216:219], v[6:9]
	v_mfma_f32_16x16x32_bf16 v[2:5], v[174:177], v[216:219], v[2:5]
	s_barrier
	s_add_i32 s24, s24, 2
	s_add_u32 s0, s0, 0x100
	s_addc_u32 s1, s1, 0
	s_cmp_gt_u32 s24, 29
	s_cbranch_scc0 .LBB0_281
	s_cmpk_lt_u32 s2, 0x100
	v_readlane_b32 s22, v249, 31
	v_readlane_b32 s23, v249, 32
	s_cbranch_scc0 .LBB0_284
	s_barrier

;     __device__ __forceinline__ bool next(int i, Unit& u) const { u.seg = 0; u.ks = -1; u.nt = ntk; u.koff = 0; return unit(i, u); }
;     __device__ __forceinline__ bool next(int i, Unit& u) const { const int t = i / 3; u.seg = i - 3 * t; u.ks = -1; u.nt = ntk; u.koff = 0; return unit(t, u); }
;     __device__ __forceinline__ bool next(int i, Unit& u) const { if (i > 0 || c < 80 || c >= 144) return false; const int k = c - 80; u.pm = k & 1; u.pn = k >> 1; u.seg = 0; u.ks = -1; u.nt = DM / BK; u.koff = 0; return true; }
; #define PG8_STAGE(bufoff, gbase, voff) do { _Pragma("unroll") for (int _i = 0; _i < 2; ++_i) \
;         __builtin_amdgcn_global_load_lds((const unsigned*)((const char*)(gbase) + (voff)[_i]), (LAS unsigned*)(lds + (bufoff) + ldsw + _i * 8192), 16, 0, 0); } while (0)
; #define PG8_LDA(dst, b, h) do { _Pragma("unroll") for (int m = 0; m < 4; ++m) _Pragma("unroll") for (int k = 0; k < 2; ++k) dst[m][k] = *(const LAS bf16x8*)(lds + PG8_SA(b, h) + aoff + m * 2048 + k * 1024); } while (0)
; template <class Epi, class Sched, bool I8 = false>
; __device__ __forceinline__ void gemm_phase(LAS unsigned char* lds, const Gemm g, const Sched& S, const Epi& E) {
;     ...
;         const bool has_next = S.next(ui + 1, nxt);
;         const char* nA = has_next ? g.A + (size_t)nxt.seg * g.segA + (size_t)nxt.pm * tstepA + nxt.koff : cA; const char* nB = has_next ? g.Bt + (size_t)nxt.seg * g.segB + (size_t)nxt.pn * tstepB + nxt.koff : cB;
;         const int nt = cur.nt;
;         for (int t = 0; t < nt; t += 2) {
;             const bool last = (t == nt - 2);
;             const char* a1 = cA + (size_t)(t + 1) * kstep;
;             const char* a2 = last ? nA : cA + (size_t)(t + 2) * kstep; const char* b2 = last ? nB : cB + (size_t)(t + 2) * kstep;
;             const char* a3 = a2 + kstep; const char* b3 = b2 + kstep;
;             if (PG8_SP2) {
;             PG8_LDB(B0, 0, 0); PG8_LDB(B1, 0, 1); PG8_SCHED; PG8_LDA(At, 0, 0); PG8_STAGE(PG8_SA(1, 1), a1 + hstepA, voffA);
;             PG8_WAIT_V(8); PG8_WAIT_L(0); PG8_BAR; PG8_MMA(0, 0, At, B0); PG8_MMA(0, 1, At, B1); PG8_BAR; PG8_SCHED;
;             PG8_LDA(At, 0, 1); PG8_STAGE(PG8_SB(0, 0), b2, voffB); PG8_STAGE(PG8_SB(0, 1), b2 + hstepB, voffB); PG8_STAGE(PG8_SA(0, 0), a2, voffA);
;             PG8_WAIT_V(8); PG8_WAIT_L(0); PG8_BAR; PG8_MMA(1, 0, At, B0); PG8_MMA(1, 1, At, B1); PG8_BAR; PG8_SCHED;
.LBB0_356:
	s_add_u32 s4, s0, 0xfff80080
	s_addc_u32 s5, s1, -1
	s_add_i32 s30, 0, 0x10000
	s_cmp_eq_u32 s29, 28
	s_cselect_b32 s7, s14, s5
	s_cselect_b32 s6, s21, s4
	v_add_u32_e32 v130, s30, v141
	s_cselect_b32 s5, s22, s25
	s_cselect_b32 s4, s23, s24
	s_add_i32 s34, 0, 0x14000
	ds_read_b128 v[150:153], v130
	ds_read_b128 v[154:157], v130 offset:1024
	ds_read_b128 v[158:161], v130 offset:2048
	ds_read_b128 v[162:165], v130 offset:3072
	v_add_u32_e32 v130, s34, v141
	ds_read_b128 v[166:169], v130
	ds_read_b128 v[170:173], v130 offset:1024
	ds_read_b128 v[174:177], v130 offset:2048
	ds_read_b128 v[178:181], v130 offset:3072
	v_lshl_add_u64 v[202:203], s[0:1], 0, v[146:147]
	s_add_i32 m0, s41, 0xc000
	ds_read_b128 v[182:185], v143
	ds_read_b128 v[186:189], v143 offset:1024
	ds_read_b128 v[190:193], v143 offset:2048
	ds_read_b128 v[194:197], v143 offset:3072
	ds_read_b128 v[198:201], v143 offset:4096
	ds_read_b128 v[212:215], v143 offset:5120
	ds_read_b128 v[216:219], v143 offset:6144
	ds_read_b128 v[220:223], v143 offset:7168
	global_load_lds_dwordx4 v[202:203], off
	v_lshl_add_u64 v[202:203], s[0:1], 0, v[148:149]
	s_add_i32 m0, s41, 0xe000
	s_nop 0
	global_load_lds_dwordx4 v[202:203], off
	s_waitcnt vmcnt(8)
	s_waitcnt lgkmcnt(0)
	s_barrier
	s_waitcnt lgkmcnt(0)
	v_mfma_f32_16x16x32_bf16 v[126:129], v[150:153], v[182:185], v[126:129]
	v_mfma_f32_16x16x32_bf16 v[122:125], v[158:161], v[182:185], v[122:125]
	v_mfma_f32_16x16x32_bf16 v[110:113], v[150:153], v[190:193], v[110:113]
	v_mfma_f32_16x16x32_bf16 v[106:109], v[158:161], v[190:193], v[106:109]
	v_mfma_f32_16x16x32_bf16 v[94:97], v[150:153], v[198:201], v[94:97]
	v_mfma_f32_16x16x32_bf16 v[90:93], v[158:161], v[198:201], v[90:93]
	v_mfma_f32_16x16x32_bf16 v[78:81], v[150:153], v[216:219], v[78:81]
	v_mfma_f32_16x16x32_bf16 v[74:77], v[158:161], v[216:219], v[74:77]
	v_mfma_f32_16x16x32_bf16 v[126:129], v[154:157], v[186:189], v[126:129]
	v_mfma_f32_16x16x32_bf16 v[122:125], v[162:165], v[186:189], v[122:125]
	v_mfma_f32_16x16x32_bf16 v[110:113], v[154:157], v[194:197], v[110:113]
	v_mfma_f32_16x16x32_bf16 v[106:109], v[162:165], v[194:197], v[106:109]
	v_mfma_f32_16x16x32_bf16 v[94:97], v[154:157], v[212:215], v[94:97]
	v_mfma_f32_16x16x32_bf16 v[90:93], v[162:165], v[212:215], v[90:93]
	v_mfma_f32_16x16x32_bf16 v[78:81], v[154:157], v[220:223], v[78:81]
	v_mfma_f32_16x16x32_bf16 v[74:77], v[162:165], v[220:223], v[74:77]
	v_mfma_f32_16x16x32_bf16 v[118:121], v[166:169], v[182:185], v[118:121]
	v_mfma_f32_16x16x32_bf16 v[114:117], v[174:177], v[182:185], v[114:117]
	v_mfma_f32_16x16x32_bf16 v[102:105], v[166:169], v[190:193], v[102:105]
	v_mfma_f32_16x16x32_bf16 v[98:101], v[174:177], v[190:193], v[98:101]
	v_mfma_f32_16x16x32_bf16 v[86:89], v[166:169], v[198:201], v[86:89]
	v_mfma_f32_16x16x32_bf16 v[82:85], v[174:177], v[198:201], v[82:85]
	v_mfma_f32_16x16x32_bf16 v[70:73], v[166:169], v[216:219], v[70:73]
	v_mfma_f32_16x16x32_bf16 v[66:69], v[174:177], v[216:219], v[66:69]
	v_mfma_f32_16x16x32_bf16 v[118:121], v[170:173], v[186:189], v[118:121]
	v_mfma_f32_16x16x32_bf16 v[114:117], v[178:181], v[186:189], v[114:117]
	v_mfma_f32_16x16x32_bf16 v[102:105], v[170:173], v[194:197], v[102:105]
	v_mfma_f32_16x16x32_bf16 v[98:101], v[178:181], v[194:197], v[98:101]
	v_mfma_f32_16x16x32_bf16 v[86:89], v[170:173], v[212:215], v[86:89]
	v_mfma_f32_16x16x32_bf16 v[82:85], v[178:181], v[212:215], v[82:85]
	v_mfma_f32_16x16x32_bf16 v[70:73], v[170:173], v[220:223], v[70:73]
	v_mfma_f32_16x16x32_bf16 v[66:69], v[178:181], v[220:223], v[66:69]
	s_barrier
	s_add_i32 s30, s30, s40
	v_lshl_add_u64 v[202:203], s[4:5], 0, v[136:137]
	s_mov_b32 m0, s30
	ds_read_b128 v[182:185], v143 offset:16384
	ds_read_b128 v[186:189], v143 offset:17408
	ds_read_b128 v[190:193], v143 offset:18432
	ds_read_b128 v[194:197], v143 offset:19456
	ds_read_b128 v[198:201], v143 offset:20480
	ds_read_b128 v[212:215], v143 offset:21504
	ds_read_b128 v[216:219], v143 offset:22528
	ds_read_b128 v[220:223], v143 offset:23552
	global_load_lds_dwordx4 v[202:203], off
	s_add_i32 m0, s30, 0x2000
	s_add_u32 s30, s4, 0x20000
	v_lshl_add_u64 v[224:225], s[4:5], 0, v[132:133]
	s_addc_u32 s31, s5, 0
	s_add_i32 s34, s34, s40
	global_load_lds_dwordx4 v[224:225], off
	v_lshl_add_u64 v[226:227], s[30:31], 0, v[136:137]
	s_mov_b32 m0, s34
	v_lshl_add_u64 v[228:229], s[6:7], 0, v[134:135]
	global_load_lds_dwordx4 v[226:227], off
	v_lshl_add_u64 v[226:227], s[30:31], 0, v[132:133]
	s_add_i32 m0, s34, 0x2000
	s_nop 0
	global_load_lds_dwordx4 v[226:227], off
	v_lshl_add_u64 v[226:227], s[6:7], 0, v[138:139]
	s_mov_b32 m0, s41
	s_nop 0
	global_load_lds_dwordx4 v[226:227], off
	s_mov_b32 m0, s42
	s_nop 0
	global_load_lds_dwordx4 v[228:229], off
	s_waitcnt vmcnt(8)
	s_waitcnt lgkmcnt(0)
	s_barrier
; #define PG8_STAGE(bufoff, gbase, voff) do { _Pragma("unroll") for (int _i = 0; _i < 2; ++_i) \
;         __builtin_amdgcn_global_load_lds((const unsigned*)((const char*)(gbase) + (voff)[_i]), (LAS unsigned*)(lds + (bufoff) + ldsw + _i * 8192), 16, 0, 0); } while (0)
; #define PG8_LDA(dst, b, h) do { _Pragma("unroll") for (int m = 0; m < 4; ++m) _Pragma("unroll") for (int k = 0; k < 2; ++k) dst[m][k] = *(const LAS bf16x8*)(lds + PG8_SA(b, h) + aoff + m * 2048 + k * 1024); } while (0)
; #define PG8_LDB(dst, b, h) do { _Pragma("unroll") for (int n = 0; n < 2; ++n) _Pragma("unroll") for (int k = 0; k < 2; ++k) dst[n][k] = *(const LAS bf16x8*)(lds + PG8_SB(b, h) + boff + n * 2048 + k * 1024); } while (0)
; #define PG8_MMA(ai, bj, At, Bt) do { __builtin_amdgcn_s_setprio(1); _Pragma("unroll") for (int m = 0; m < 4; ++m) _Pragma("unroll") for (int n = 0; n < 2; ++n) _Pragma("unroll") for (int k = 0; k < 2; ++k) \
;         acc[ai][bj][m][n] = mma16<I8>(Bt[n][k], At[m][k], acc[ai][bj][m][n]); __builtin_amdgcn_s_setprio(0); } while (0)
; #define PG8_WAIT_V(n) asm volatile("s_waitcnt vmcnt(" #n ")" ::: "memory")
; #define PG8_WAIT_L(n) asm volatile("s_waitcnt lgkmcnt(" #n ")" ::: "memory")
; #define PG8_BAR __builtin_amdgcn_s_barrier()
; #define PG8_SCHED __builtin_amdgcn_sched_barrier(0)
; template <class Epi, class Sched, bool I8 = false>
; __device__ __forceinline__ void gemm_phase(LAS unsigned char* lds, const Gemm g, const Sched& S, const Epi& E) {
;     ...
;             PG8_WAIT_V(8); PG8_WAIT_L(0); PG8_BAR; PG8_MMA(1, 0, At, B0); PG8_MMA(1, 1, At, B1); PG8_BAR; PG8_SCHED;
;             PG8_LDB(B0, 1, 0); PG8_LDB(B1, 1, 1); PG8_SCHED; PG8_LDA(At, 1, 0); PG8_STAGE(PG8_SA(0, 1), a2 + hstepA, voffA);
;             PG8_WAIT_V(8); PG8_WAIT_L(0); PG8_BAR; PG8_MMA(0, 0, At, B0); PG8_MMA(0, 1, At, B1); PG8_BAR; PG8_SCHED;
	s_waitcnt lgkmcnt(0)
	v_mfma_f32_16x16x32_bf16 v[62:65], v[150:153], v[182:185], v[62:65]
	v_mfma_f32_16x16x32_bf16 v[58:61], v[158:161], v[182:185], v[58:61]
	v_mfma_f32_16x16x32_bf16 v[46:49], v[150:153], v[190:193], v[46:49]
	v_mfma_f32_16x16x32_bf16 v[42:45], v[158:161], v[190:193], v[42:45]
	v_mfma_f32_16x16x32_bf16 v[30:33], v[150:153], v[198:201], v[30:33]
	v_mfma_f32_16x16x32_bf16 v[26:29], v[158:161], v[198:201], v[26:29]
	v_mfma_f32_16x16x32_bf16 v[14:17], v[150:153], v[216:219], v[14:17]
	v_mfma_f32_16x16x32_bf16 v[10:13], v[158:161], v[216:219], v[10:13]
	v_mfma_f32_16x16x32_bf16 v[62:65], v[154:157], v[186:189], v[62:65]
	v_mfma_f32_16x16x32_bf16 v[58:61], v[162:165], v[186:189], v[58:61]
	v_mfma_f32_16x16x32_bf16 v[46:49], v[154:157], v[194:197], v[46:49]
	v_mfma_f32_16x16x32_bf16 v[42:45], v[162:165], v[194:197], v[42:45]
	v_mfma_f32_16x16x32_bf16 v[30:33], v[154:157], v[212:215], v[30:33]
	v_mfma_f32_16x16x32_bf16 v[26:29], v[162:165], v[212:215], v[26:29]
	v_mfma_f32_16x16x32_bf16 v[14:17], v[154:157], v[220:223], v[14:17]
	v_mfma_f32_16x16x32_bf16 v[10:13], v[162:165], v[220:223], v[10:13]
	v_mfma_f32_16x16x32_bf16 v[54:57], v[166:169], v[182:185], v[54:57]
	v_mfma_f32_16x16x32_bf16 v[50:53], v[174:177], v[182:185], v[50:53]
	v_mfma_f32_16x16x32_bf16 v[38:41], v[166:169], v[190:193], v[38:41]
	v_mfma_f32_16x16x32_bf16 v[34:37], v[174:177], v[190:193], v[34:37]
	v_mfma_f32_16x16x32_bf16 v[22:25], v[166:169], v[198:201], v[22:25]
	v_mfma_f32_16x16x32_bf16 v[18:21], v[174:177], v[198:201], v[18:21]
	v_mfma_f32_16x16x32_bf16 v[6:9], v[166:169], v[216:219], v[6:9]
	v_mfma_f32_16x16x32_bf16 v[2:5], v[174:177], v[216:219], v[2:5]
	v_mfma_f32_16x16x32_bf16 v[54:57], v[170:173], v[186:189], v[54:57]
	v_mfma_f32_16x16x32_bf16 v[50:53], v[178:181], v[186:189], v[50:53]
	v_mfma_f32_16x16x32_bf16 v[38:41], v[170:173], v[194:197], v[38:41]
	v_mfma_f32_16x16x32_bf16 v[34:37], v[178:181], v[194:197], v[34:37]
	v_mfma_f32_16x16x32_bf16 v[22:25], v[170:173], v[212:215], v[22:25]
	v_mfma_f32_16x16x32_bf16 v[18:21], v[178:181], v[212:215], v[18:21]
	v_mfma_f32_16x16x32_bf16 v[6:9], v[170:173], v[220:223], v[6:9]
	v_mfma_f32_16x16x32_bf16 v[2:5], v[178:181], v[220:223], v[2:5]
	s_barrier
	s_add_i32 s30, 0, 0x18000
	v_add_u32_e32 v130, s30, v141
	s_add_i32 s31, 0, 0x1c000
	ds_read_b128 v[150:153], v130
	ds_read_b128 v[154:157], v130 offset:1024
	ds_read_b128 v[158:161], v130 offset:2048
	ds_read_b128 v[162:165], v130 offset:3072
	v_add_u32_e32 v130, s31, v141
	ds_read_b128 v[166:169], v130
	ds_read_b128 v[170:173], v130 offset:1024
	ds_read_b128 v[174:177], v130 offset:2048
	ds_read_b128 v[178:181], v130 offset:3072
	s_add_u32 s6, s6, 0x80000
	s_addc_u32 s7, s7, 0
	s_mov_b32 m0, s43
	v_lshl_add_u64 v[230:231], s[6:7], 0, v[138:139]
	ds_read_b128 v[182:185], v143 offset:32768
	ds_read_b128 v[186:189], v143 offset:33792
	ds_read_b128 v[190:193], v143 offset:34816
	ds_read_b128 v[194:197], v143 offset:35840
	ds_read_b128 v[198:201], v143 offset:36864
	ds_read_b128 v[212:215], v143 offset:37888
	ds_read_b128 v[216:219], v143 offset:38912
	ds_read_b128 v[220:223], v143 offset:39936
	global_load_lds_dwordx4 v[230:231], off
	v_lshl_add_u64 v[230:231], s[6:7], 0, v[134:135]
	s_mov_b32 m0, s44
	s_nop 0
	global_load_lds_dwordx4 v[230:231], off
	s_waitcnt vmcnt(8)
	s_waitcnt lgkmcnt(0)
	s_barrier
	s_waitcnt lgkmcnt(0)
	v_mfma_f32_16x16x32_bf16 v[126:129], v[150:153], v[182:185], v[126:129]
	v_mfma_f32_16x16x32_bf16 v[122:125], v[158:161], v[182:185], v[122:125]
	v_mfma_f32_16x16x32_bf16 v[110:113], v[150:153], v[190:193], v[110:113]
	v_mfma_f32_16x16x32_bf16 v[106:109], v[158:161], v[190:193], v[106:109]
	v_mfma_f32_16x16x32_bf16 v[94:97], v[150:153], v[198:201], v[94:97]
	v_mfma_f32_16x16x32_bf16 v[90:93], v[158:161], v[198:201], v[90:93]
	v_mfma_f32_16x16x32_bf16 v[78:81], v[150:153], v[216:219], v[78:81]
	v_mfma_f32_16x16x32_bf16 v[74:77], v[158:161], v[216:219], v[74:77]
	v_mfma_f32_16x16x32_bf16 v[126:129], v[154:157], v[186:189], v[126:129]
	v_mfma_f32_16x16x32_bf16 v[122:125], v[162:165], v[186:189], v[122:125]
	v_mfma_f32_16x16x32_bf16 v[110:113], v[154:157], v[194:197], v[110:113]
	v_mfma_f32_16x16x32_bf16 v[106:109], v[162:165], v[194:197], v[106:109]
	v_mfma_f32_16x16x32_bf16 v[94:97], v[154:157], v[212:215], v[94:97]
	v_mfma_f32_16x16x32_bf16 v[90:93], v[162:165], v[212:215], v[90:93]
	v_mfma_f32_16x16x32_bf16 v[78:81], v[154:157], v[220:223], v[78:81]
	v_mfma_f32_16x16x32_bf16 v[74:77], v[162:165], v[220:223], v[74:77]
	v_mfma_f32_16x16x32_bf16 v[118:121], v[166:169], v[182:185], v[118:121]
	v_mfma_f32_16x16x32_bf16 v[114:117], v[174:177], v[182:185], v[114:117]
	v_mfma_f32_16x16x32_bf16 v[102:105], v[166:169], v[190:193], v[102:105]
	v_mfma_f32_16x16x32_bf16 v[98:101], v[174:177], v[190:193], v[98:101]
	v_mfma_f32_16x16x32_bf16 v[86:89], v[166:169], v[198:201], v[86:89]
	v_mfma_f32_16x16x32_bf16 v[82:85], v[174:177], v[198:201], v[82:85]
	v_mfma_f32_16x16x32_bf16 v[70:73], v[166:169], v[216:219], v[70:73]
	v_mfma_f32_16x16x32_bf16 v[66:69], v[174:177], v[216:219], v[66:69]
	v_mfma_f32_16x16x32_bf16 v[118:121], v[170:173], v[186:189], v[118:121]
	v_mfma_f32_16x16x32_bf16 v[114:117], v[178:181], v[186:189], v[114:117]
	v_mfma_f32_16x16x32_bf16 v[102:105], v[170:173], v[194:197], v[102:105]
	v_mfma_f32_16x16x32_bf16 v[98:101], v[178:181], v[194:197], v[98:101]
	v_mfma_f32_16x16x32_bf16 v[86:89], v[170:173], v[212:215], v[86:89]
	v_mfma_f32_16x16x32_bf16 v[82:85], v[178:181], v[212:215], v[82:85]
	v_mfma_f32_16x16x32_bf16 v[70:73], v[170:173], v[220:223], v[70:73]
	v_mfma_f32_16x16x32_bf16 v[66:69], v[178:181], v[220:223], v[66:69]
	s_barrier
; #define PG8_STAGE(bufoff, gbase, voff) do { _Pragma("unroll") for (int _i = 0; _i < 2; ++_i) \
;         __builtin_amdgcn_global_load_lds((const unsigned*)((const char*)(gbase) + (voff)[_i]), (LAS unsigned*)(lds + (bufoff) + ldsw + _i * 8192), 16, 0, 0); } while (0)
; #define PG8_LDA(dst, b, h) do { _Pragma("unroll") for (int m = 0; m < 4; ++m) _Pragma("unroll") for (int k = 0; k < 2; ++k) dst[m][k] = *(const LAS bf16x8*)(lds + PG8_SA(b, h) + aoff + m * 2048 + k * 1024); } while (0)
; #define PG8_MMA(ai, bj, At, Bt) do { __builtin_amdgcn_s_setprio(1); _Pragma("unroll") for (int m = 0; m < 4; ++m) _Pragma("unroll") for (int n = 0; n < 2; ++n) _Pragma("unroll") for (int k = 0; k < 2; ++k) \
;         acc[ai][bj][m][n] = mma16<I8>(Bt[n][k], At[m][k], acc[ai][bj][m][n]); __builtin_amdgcn_s_setprio(0); } while (0)
; #define PG8_WAIT_V(n) asm volatile("s_waitcnt vmcnt(" #n ")" ::: "memory")
; #define PG8_WAIT_L(n) asm volatile("s_waitcnt lgkmcnt(" #n ")" ::: "memory")
; #define PG8_BAR __builtin_amdgcn_s_barrier()
; #define PG8_SCHED __builtin_amdgcn_sched_barrier(0)
; template <class Epi, class Sched, bool I8 = false>
; __device__ __forceinline__ void gemm_phase(LAS unsigned char* lds, const Gemm g, const Sched& S, const Epi& E) {
;     ...
;             PG8_LDA(At, 1, 1); PG8_STAGE(PG8_SB(1, 0), b3, voffB); PG8_STAGE(PG8_SB(1, 1), b3 + hstepB, voffB); PG8_STAGE(PG8_SA(1, 0), a3, voffA);
;             PG8_WAIT_V(8); PG8_WAIT_L(0); PG8_BAR; PG8_MMA(1, 0, At, B0); PG8_MMA(1, 1, At, B1); PG8_BAR; PG8_SCHED;
;     ...
;         if (PG8_ALIGN) { if (wr == 0) PG8_BAR; }
	s_add_i32 s6, s30, s40
	v_lshl_add_u64 v[202:203], v[202:203], 0, s[12:13]
	s_mov_b32 m0, s6
	ds_read_b128 v[182:185], v143 offset:49152
	ds_read_b128 v[186:189], v143 offset:50176
	ds_read_b128 v[190:193], v143 offset:51200
	ds_read_b128 v[194:197], v143 offset:52224
	ds_read_b128 v[198:201], v143 offset:53248
	ds_read_b128 v[212:215], v143 offset:54272
	ds_read_b128 v[216:219], v143 offset:55296
	ds_read_b128 v[220:223], v143 offset:56320
	global_load_lds_dwordx4 v[202:203], off
	s_add_i32 m0, s6, 0x2000
	s_add_u32 s4, s4, 0x20080
	v_lshl_add_u64 v[202:203], v[224:225], 0, s[12:13]
	s_addc_u32 s5, s5, 0
	s_add_i32 s6, s31, s40
	global_load_lds_dwordx4 v[202:203], off
	v_lshl_add_u64 v[202:203], s[4:5], 0, v[136:137]
	s_mov_b32 m0, s6
	s_nop 0
	global_load_lds_dwordx4 v[202:203], off
	v_lshl_add_u64 v[202:203], s[4:5], 0, v[132:133]
	s_add_i32 m0, s6, 0x2000
	s_nop 0
	global_load_lds_dwordx4 v[202:203], off
	v_lshl_add_u64 v[202:203], v[226:227], 0, s[12:13]
	s_mov_b32 m0, s80
	s_nop 0
	global_load_lds_dwordx4 v[202:203], off
	v_lshl_add_u64 v[202:203], v[228:229], 0, s[12:13]
	s_mov_b32 m0, s82
	s_nop 0
	global_load_lds_dwordx4 v[202:203], off
	s_waitcnt vmcnt(8)
	s_waitcnt lgkmcnt(0)
	s_barrier
	s_waitcnt lgkmcnt(0)
	v_mfma_f32_16x16x32_bf16 v[62:65], v[150:153], v[182:185], v[62:65]
	v_mfma_f32_16x16x32_bf16 v[58:61], v[158:161], v[182:185], v[58:61]
	v_mfma_f32_16x16x32_bf16 v[46:49], v[150:153], v[190:193], v[46:49]
	v_mfma_f32_16x16x32_bf16 v[42:45], v[158:161], v[190:193], v[42:45]
	v_mfma_f32_16x16x32_bf16 v[30:33], v[150:153], v[198:201], v[30:33]
	v_mfma_f32_16x16x32_bf16 v[26:29], v[158:161], v[198:201], v[26:29]
	v_mfma_f32_16x16x32_bf16 v[14:17], v[150:153], v[216:219], v[14:17]
	v_mfma_f32_16x16x32_bf16 v[10:13], v[158:161], v[216:219], v[10:13]
	v_mfma_f32_16x16x32_bf16 v[62:65], v[154:157], v[186:189], v[62:65]
	v_mfma_f32_16x16x32_bf16 v[58:61], v[162:165], v[186:189], v[58:61]
	v_mfma_f32_16x16x32_bf16 v[46:49], v[154:157], v[194:197], v[46:49]
	v_mfma_f32_16x16x32_bf16 v[42:45], v[162:165], v[194:197], v[42:45]
	v_mfma_f32_16x16x32_bf16 v[30:33], v[154:157], v[212:215], v[30:33]
	v_mfma_f32_16x16x32_bf16 v[26:29], v[162:165], v[212:215], v[26:29]
	v_mfma_f32_16x16x32_bf16 v[14:17], v[154:157], v[220:223], v[14:17]
	v_mfma_f32_16x16x32_bf16 v[10:13], v[162:165], v[220:223], v[10:13]
	v_mfma_f32_16x16x32_bf16 v[54:57], v[166:169], v[182:185], v[54:57]
	v_mfma_f32_16x16x32_bf16 v[50:53], v[174:177], v[182:185], v[50:53]
	v_mfma_f32_16x16x32_bf16 v[38:41], v[166:169], v[190:193], v[38:41]
	v_mfma_f32_16x16x32_bf16 v[34:37], v[174:177], v[190:193], v[34:37]
	v_mfma_f32_16x16x32_bf16 v[22:25], v[166:169], v[198:201], v[22:25]
	v_mfma_f32_16x16x32_bf16 v[18:21], v[174:177], v[198:201], v[18:21]
	v_mfma_f32_16x16x32_bf16 v[6:9], v[166:169], v[216:219], v[6:9]
	v_mfma_f32_16x16x32_bf16 v[2:5], v[174:177], v[216:219], v[2:5]
	v_mfma_f32_16x16x32_bf16 v[54:57], v[170:173], v[186:189], v[54:57]
	v_mfma_f32_16x16x32_bf16 v[50:53], v[178:181], v[186:189], v[50:53]
	v_mfma_f32_16x16x32_bf16 v[38:41], v[170:173], v[194:197], v[38:41]
	v_mfma_f32_16x16x32_bf16 v[34:37], v[178:181], v[194:197], v[34:37]
	v_mfma_f32_16x16x32_bf16 v[22:25], v[170:173], v[212:215], v[22:25]
	v_mfma_f32_16x16x32_bf16 v[18:21], v[178:181], v[212:215], v[18:21]
	v_mfma_f32_16x16x32_bf16 v[6:9], v[170:173], v[220:223], v[6:9]
	v_mfma_f32_16x16x32_bf16 v[2:5], v[178:181], v[220:223], v[2:5]
	s_barrier
	s_add_i32 s29, s29, 2
	s_add_u32 s0, s0, 0x100
	s_addc_u32 s1, s1, 0
	s_add_u32 s24, s24, 0x100
	s_addc_u32 s25, s25, 0
	s_cmp_gt_u32 s29, 29
	s_cbranch_scc0 .LBB0_356
	s_and_b64 vcc, exec, s[8:9]
	s_cbranch_vccz .LBB0_359
	s_barrier

;     __device__ __forceinline__ bool next(int i, Unit& u) const { u.seg = 0; u.ks = -1; u.nt = ntk; u.koff = 0; return unit(i, u); }
;     __device__ __forceinline__ bool next(int i, Unit& u) const { const int t = i / 3; u.seg = i - 3 * t; u.ks = -1; u.nt = ntk; u.koff = 0; return unit(t, u); }
;     __device__ __forceinline__ bool next(int i, Unit& u) const { if (i > 0 || c < 80 || c >= 144) return false; const int k = c - 80; u.pm = k & 1; u.pn = k >> 1; u.seg = 0; u.ks = -1; u.nt = DM / BK; u.koff = 0; return true; }
; #define PG8_STAGE(bufoff, gbase, voff) do { _Pragma("unroll") for (int _i = 0; _i < 2; ++_i) \
;         __builtin_amdgcn_global_load_lds((const unsigned*)((const char*)(gbase) + (voff)[_i]), (LAS unsigned*)(lds + (bufoff) + ldsw + _i * 8192), 16, 0, 0); } while (0)
; #define PG8_LDA(dst, b, h) do { _Pragma("unroll") for (int m = 0; m < 4; ++m) _Pragma("unroll") for (int k = 0; k < 2; ++k) dst[m][k] = *(const LAS bf16x8*)(lds + PG8_SA(b, h) + aoff + m * 2048 + k * 1024); } while (0)
; template <class Epi, class Sched, bool I8 = false>
; __device__ __forceinline__ void gemm_phase(LAS unsigned char* lds, const Gemm g, const Sched& S, const Epi& E) {
;     ...
;         const bool has_next = S.next(ui + 1, nxt);
;         const char* nA = has_next ? g.A + (size_t)nxt.seg * g.segA + (size_t)nxt.pm * tstepA + nxt.koff : cA; const char* nB = has_next ? g.Bt + (size_t)nxt.seg * g.segB + (size_t)nxt.pn * tstepB + nxt.koff : cB;
;         const int nt = cur.nt;
;         for (int t = 0; t < nt; t += 2) {
;             const bool last = (t == nt - 2);
;             const char* a1 = cA + (size_t)(t + 1) * kstep;
;             const char* a2 = last ? nA : cA + (size_t)(t + 2) * kstep; const char* b2 = last ? nB : cB + (size_t)(t + 2) * kstep;
;             const char* a3 = a2 + kstep; const char* b3 = b2 + kstep;
;             if (PG8_SP2) {
;             PG8_LDB(B0, 0, 0); PG8_LDB(B1, 0, 1); PG8_SCHED; PG8_LDA(At, 0, 0); PG8_STAGE(PG8_SA(1, 1), a1 + hstepA, voffA);
;             PG8_WAIT_V(8); PG8_WAIT_L(0); PG8_BAR; PG8_MMA(0, 0, At, B0); PG8_MMA(0, 1, At, B1); PG8_BAR; PG8_SCHED;
;             PG8_LDA(At, 0, 1); PG8_STAGE(PG8_SB(0, 0), b2, voffB); PG8_STAGE(PG8_SB(0, 1), b2 + hstepB, voffB); PG8_STAGE(PG8_SA(0, 0), a2, voffA);
;             PG8_WAIT_V(8); PG8_WAIT_L(0); PG8_BAR; PG8_MMA(1, 0, At, B0); PG8_MMA(1, 1, At, B1); PG8_BAR; PG8_SCHED;
.LBB0_539:
	s_add_u32 s6, s0, 0xfffc0080
	s_addc_u32 s7, s1, -1
	s_add_i32 s31, 0, 0x10000
	s_cmp_eq_u32 s30, 12
	s_cselect_b32 s27, s14, s7
	s_cselect_b32 s26, s21, s6
	v_add_u32_e32 v149, s31, v175
	s_cselect_b32 s7, s22, s25
	s_cselect_b32 s6, s23, s24
	s_add_i32 s38, 0, 0x14000
	ds_read_b128 v[152:155], v149
	ds_read_b128 v[156:159], v149 offset:1024
	ds_read_b128 v[160:163], v149 offset:2048
	ds_read_b128 v[164:167], v149 offset:3072
	v_add_u32_e32 v149, s38, v175
	ds_read_b128 v[168:171], v149
	ds_read_b128 v[180:183], v149 offset:1024
	ds_read_b128 v[184:187], v149 offset:2048
	ds_read_b128 v[188:191], v149 offset:3072
	v_lshl_add_u64 v[172:173], s[0:1], 0, v[144:145]
	s_add_i32 m0, s43, 0xc000
	ds_read_b128 v[192:195], v179
	ds_read_b128 v[196:199], v179 offset:1024
	ds_read_b128 v[200:203], v179 offset:2048
	ds_read_b128 v[212:215], v179 offset:3072
	ds_read_b128 v[216:219], v179 offset:4096
	ds_read_b128 v[220:223], v179 offset:5120
	ds_read_b128 v[224:227], v179 offset:6144
	ds_read_b128 v[228:231], v179 offset:7168
	global_load_lds_dwordx4 v[172:173], off
	v_lshl_add_u64 v[172:173], s[0:1], 0, v[146:147]
	s_add_i32 m0, s43, 0xe000
	s_nop 0
	global_load_lds_dwordx4 v[172:173], off
	s_waitcnt vmcnt(8)
	s_waitcnt lgkmcnt(0)
	s_barrier
	s_waitcnt lgkmcnt(0)
	v_mfma_i32_16x16x64_i8 v[126:129], v[152:155], v[192:195], v[126:129]
	v_mfma_i32_16x16x64_i8 v[122:125], v[160:163], v[192:195], v[122:125]
	v_mfma_i32_16x16x64_i8 v[118:121], v[152:155], v[200:203], v[118:121]
	v_mfma_i32_16x16x64_i8 v[114:117], v[160:163], v[200:203], v[114:117]
	v_mfma_i32_16x16x64_i8 v[102:105], v[152:155], v[216:219], v[102:105]
	v_mfma_i32_16x16x64_i8 v[98:101], v[160:163], v[216:219], v[98:101]
	v_mfma_i32_16x16x64_i8 v[86:89], v[152:155], v[224:227], v[86:89]
	v_mfma_i32_16x16x64_i8 v[82:85], v[160:163], v[224:227], v[82:85]
	v_mfma_i32_16x16x64_i8 v[126:129], v[156:159], v[196:199], v[126:129]
	v_mfma_i32_16x16x64_i8 v[122:125], v[164:167], v[196:199], v[122:125]
	v_mfma_i32_16x16x64_i8 v[118:121], v[156:159], v[212:215], v[118:121]
	v_mfma_i32_16x16x64_i8 v[114:117], v[164:167], v[212:215], v[114:117]
	v_mfma_i32_16x16x64_i8 v[102:105], v[156:159], v[220:223], v[102:105]
	v_mfma_i32_16x16x64_i8 v[98:101], v[164:167], v[220:223], v[98:101]
	v_mfma_i32_16x16x64_i8 v[86:89], v[156:159], v[228:231], v[86:89]
	v_mfma_i32_16x16x64_i8 v[82:85], v[164:167], v[228:231], v[82:85]
	v_mfma_i32_16x16x64_i8 v[110:113], v[168:171], v[192:195], v[110:113]
	v_mfma_i32_16x16x64_i8 v[106:109], v[184:187], v[192:195], v[106:109]
	v_mfma_i32_16x16x64_i8 v[94:97], v[168:171], v[200:203], v[94:97]
	v_mfma_i32_16x16x64_i8 v[90:93], v[184:187], v[200:203], v[90:93]
	v_mfma_i32_16x16x64_i8 v[78:81], v[168:171], v[216:219], v[78:81]
	v_mfma_i32_16x16x64_i8 v[74:77], v[184:187], v[216:219], v[74:77]
	v_mfma_i32_16x16x64_i8 v[70:73], v[168:171], v[224:227], v[70:73]
	v_mfma_i32_16x16x64_i8 v[66:69], v[184:187], v[224:227], v[66:69]
	v_mfma_i32_16x16x64_i8 v[110:113], v[180:183], v[196:199], v[110:113]
	v_mfma_i32_16x16x64_i8 v[106:109], v[188:191], v[196:199], v[106:109]
	v_mfma_i32_16x16x64_i8 v[94:97], v[180:183], v[212:215], v[94:97]
	v_mfma_i32_16x16x64_i8 v[90:93], v[188:191], v[212:215], v[90:93]
	v_mfma_i32_16x16x64_i8 v[78:81], v[180:183], v[220:223], v[78:81]
	v_mfma_i32_16x16x64_i8 v[74:77], v[188:191], v[220:223], v[74:77]
	v_mfma_i32_16x16x64_i8 v[70:73], v[180:183], v[228:231], v[70:73]
	v_mfma_i32_16x16x64_i8 v[66:69], v[188:191], v[228:231], v[66:69]
	s_barrier
	s_add_i32 s31, s31, s42
	v_lshl_add_u64 v[172:173], s[6:7], 0, v[136:137]
	s_mov_b32 m0, s31
	ds_read_b128 v[192:195], v179 offset:16384
	ds_read_b128 v[196:199], v179 offset:17408
	ds_read_b128 v[200:203], v179 offset:18432
	ds_read_b128 v[212:215], v179 offset:19456
	ds_read_b128 v[216:219], v179 offset:20480
	ds_read_b128 v[220:223], v179 offset:21504
	ds_read_b128 v[224:227], v179 offset:22528
	ds_read_b128 v[228:231], v179 offset:23552
	global_load_lds_dwordx4 v[172:173], off
	s_add_i32 m0, s31, 0x2000
	s_add_u32 s34, s6, 0x10000
	v_lshl_add_u64 v[232:233], s[6:7], 0, v[132:133]
	s_addc_u32 s35, s7, 0
	s_add_i32 s31, s38, s42
	global_load_lds_dwordx4 v[232:233], off
	v_lshl_add_u64 v[234:235], s[34:35], 0, v[136:137]
	s_mov_b32 m0, s31
	v_lshl_add_u64 v[236:237], s[26:27], 0, v[134:135]
	global_load_lds_dwordx4 v[234:235], off
	v_lshl_add_u64 v[234:235], s[34:35], 0, v[132:133]
	s_add_i32 m0, s31, 0x2000
	s_nop 0
	global_load_lds_dwordx4 v[234:235], off
	v_lshl_add_u64 v[234:235], s[26:27], 0, v[138:139]
	s_mov_b32 m0, s43
	s_nop 0
	global_load_lds_dwordx4 v[234:235], off
	s_mov_b32 m0, s44
	s_nop 0
	global_load_lds_dwordx4 v[236:237], off
	s_waitcnt vmcnt(8)
	s_waitcnt lgkmcnt(0)
	s_barrier
; #define PG8_STAGE(bufoff, gbase, voff) do { _Pragma("unroll") for (int _i = 0; _i < 2; ++_i) \
;         __builtin_amdgcn_global_load_lds((const unsigned*)((const char*)(gbase) + (voff)[_i]), (LAS unsigned*)(lds + (bufoff) + ldsw + _i * 8192), 16, 0, 0); } while (0)
; #define PG8_LDA(dst, b, h) do { _Pragma("unroll") for (int m = 0; m < 4; ++m) _Pragma("unroll") for (int k = 0; k < 2; ++k) dst[m][k] = *(const LAS bf16x8*)(lds + PG8_SA(b, h) + aoff + m * 2048 + k * 1024); } while (0)
; #define PG8_LDB(dst, b, h) do { _Pragma("unroll") for (int n = 0; n < 2; ++n) _Pragma("unroll") for (int k = 0; k < 2; ++k) dst[n][k] = *(const LAS bf16x8*)(lds + PG8_SB(b, h) + boff + n * 2048 + k * 1024); } while (0)
; #define PG8_MMA(ai, bj, At, Bt) do { __builtin_amdgcn_s_setprio(1); _Pragma("unroll") for (int m = 0; m < 4; ++m) _Pragma("unroll") for (int n = 0; n < 2; ++n) _Pragma("unroll") for (int k = 0; k < 2; ++k) \
;         acc[ai][bj][m][n] = mma16<I8>(Bt[n][k], At[m][k], acc[ai][bj][m][n]); __builtin_amdgcn_s_setprio(0); } while (0)
; #define PG8_WAIT_V(n) asm volatile("s_waitcnt vmcnt(" #n ")" ::: "memory")
; #define PG8_WAIT_L(n) asm volatile("s_waitcnt lgkmcnt(" #n ")" ::: "memory")
; #define PG8_BAR __builtin_amdgcn_s_barrier()
; #define PG8_SCHED __builtin_amdgcn_sched_barrier(0)
; template <class Epi, class Sched, bool I8 = false>
; __device__ __forceinline__ void gemm_phase(LAS unsigned char* lds, const Gemm g, const Sched& S, const Epi& E) {
;     ...
;             PG8_WAIT_V(8); PG8_WAIT_L(0); PG8_BAR; PG8_MMA(1, 0, At, B0); PG8_MMA(1, 1, At, B1); PG8_BAR; PG8_SCHED;
;             PG8_LDB(B0, 1, 0); PG8_LDB(B1, 1, 1); PG8_SCHED; PG8_LDA(At, 1, 0); PG8_STAGE(PG8_SA(0, 1), a2 + hstepA, voffA);
;             PG8_WAIT_V(8); PG8_WAIT_L(0); PG8_BAR; PG8_MMA(0, 0, At, B0); PG8_MMA(0, 1, At, B1); PG8_BAR; PG8_SCHED;
	s_waitcnt lgkmcnt(0)
	v_mfma_i32_16x16x64_i8 v[62:65], v[152:155], v[192:195], v[62:65]
	v_mfma_i32_16x16x64_i8 v[58:61], v[160:163], v[192:195], v[58:61]
	v_mfma_i32_16x16x64_i8 v[54:57], v[152:155], v[200:203], v[54:57]
	v_mfma_i32_16x16x64_i8 v[50:53], v[160:163], v[200:203], v[50:53]
	v_mfma_i32_16x16x64_i8 v[30:33], v[152:155], v[216:219], v[30:33]
	v_mfma_i32_16x16x64_i8 v[26:29], v[160:163], v[216:219], v[26:29]
	v_mfma_i32_16x16x64_i8 v[14:17], v[152:155], v[224:227], v[14:17]
	v_mfma_i32_16x16x64_i8 v[10:13], v[160:163], v[224:227], v[10:13]
	v_mfma_i32_16x16x64_i8 v[62:65], v[156:159], v[196:199], v[62:65]
	v_mfma_i32_16x16x64_i8 v[58:61], v[164:167], v[196:199], v[58:61]
	v_mfma_i32_16x16x64_i8 v[54:57], v[156:159], v[212:215], v[54:57]
	v_mfma_i32_16x16x64_i8 v[50:53], v[164:167], v[212:215], v[50:53]
	v_mfma_i32_16x16x64_i8 v[30:33], v[156:159], v[220:223], v[30:33]
	v_mfma_i32_16x16x64_i8 v[26:29], v[164:167], v[220:223], v[26:29]
	v_mfma_i32_16x16x64_i8 v[14:17], v[156:159], v[228:231], v[14:17]
	v_mfma_i32_16x16x64_i8 v[10:13], v[164:167], v[228:231], v[10:13]
	v_mfma_i32_16x16x64_i8 v[46:49], v[168:171], v[192:195], v[46:49]
	v_mfma_i32_16x16x64_i8 v[42:45], v[184:187], v[192:195], v[42:45]
	v_mfma_i32_16x16x64_i8 v[38:41], v[168:171], v[200:203], v[38:41]
	v_mfma_i32_16x16x64_i8 v[34:37], v[184:187], v[200:203], v[34:37]
	v_mfma_i32_16x16x64_i8 v[22:25], v[168:171], v[216:219], v[22:25]
	v_mfma_i32_16x16x64_i8 v[18:21], v[184:187], v[216:219], v[18:21]
	v_mfma_i32_16x16x64_i8 v[6:9], v[168:171], v[224:227], v[6:9]
	v_mfma_i32_16x16x64_i8 v[2:5], v[184:187], v[224:227], v[2:5]
	v_mfma_i32_16x16x64_i8 v[46:49], v[180:183], v[196:199], v[46:49]
	v_mfma_i32_16x16x64_i8 v[42:45], v[188:191], v[196:199], v[42:45]
	v_mfma_i32_16x16x64_i8 v[38:41], v[180:183], v[212:215], v[38:41]
	v_mfma_i32_16x16x64_i8 v[34:37], v[188:191], v[212:215], v[34:37]
	v_mfma_i32_16x16x64_i8 v[22:25], v[180:183], v[220:223], v[22:25]
	v_mfma_i32_16x16x64_i8 v[18:21], v[188:191], v[220:223], v[18:21]
	v_mfma_i32_16x16x64_i8 v[6:9], v[180:183], v[228:231], v[6:9]
	v_mfma_i32_16x16x64_i8 v[2:5], v[188:191], v[228:231], v[2:5]
	s_barrier
	s_add_i32 s31, 0, 0x18000
	v_add_u32_e32 v149, s31, v175
	s_add_i32 s34, 0, 0x1c000
	ds_read_b128 v[152:155], v149
	ds_read_b128 v[156:159], v149 offset:1024
	ds_read_b128 v[160:163], v149 offset:2048
	ds_read_b128 v[164:167], v149 offset:3072
	v_add_u32_e32 v149, s34, v175
	ds_read_b128 v[168:171], v149
	ds_read_b128 v[180:183], v149 offset:1024
	ds_read_b128 v[184:187], v149 offset:2048
	ds_read_b128 v[188:191], v149 offset:3072
	s_add_u32 s26, s26, 0x40000
	s_addc_u32 s27, s27, 0
	s_mov_b32 m0, s45
	v_lshl_add_u64 v[238:239], s[26:27], 0, v[138:139]
	ds_read_b128 v[192:195], v179 offset:32768
	ds_read_b128 v[196:199], v179 offset:33792
	ds_read_b128 v[200:203], v179 offset:34816
	ds_read_b128 v[212:215], v179 offset:35840
	ds_read_b128 v[216:219], v179 offset:36864
	ds_read_b128 v[220:223], v179 offset:37888
	ds_read_b128 v[224:227], v179 offset:38912
	ds_read_b128 v[228:231], v179 offset:39936
	global_load_lds_dwordx4 v[238:239], off
	v_lshl_add_u64 v[238:239], s[26:27], 0, v[134:135]
	s_mov_b32 m0, s82
	s_nop 0
	global_load_lds_dwordx4 v[238:239], off
	s_waitcnt vmcnt(8)
	s_waitcnt lgkmcnt(0)
	s_barrier
	s_waitcnt lgkmcnt(0)
	v_mfma_i32_16x16x64_i8 v[126:129], v[152:155], v[192:195], v[126:129]
	v_mfma_i32_16x16x64_i8 v[122:125], v[160:163], v[192:195], v[122:125]
	v_mfma_i32_16x16x64_i8 v[118:121], v[152:155], v[200:203], v[118:121]
	v_mfma_i32_16x16x64_i8 v[114:117], v[160:163], v[200:203], v[114:117]
	v_mfma_i32_16x16x64_i8 v[102:105], v[152:155], v[216:219], v[102:105]
	v_mfma_i32_16x16x64_i8 v[98:101], v[160:163], v[216:219], v[98:101]
	v_mfma_i32_16x16x64_i8 v[86:89], v[152:155], v[224:227], v[86:89]
	v_mfma_i32_16x16x64_i8 v[82:85], v[160:163], v[224:227], v[82:85]
	v_mfma_i32_16x16x64_i8 v[126:129], v[156:159], v[196:199], v[126:129]
	v_mfma_i32_16x16x64_i8 v[122:125], v[164:167], v[196:199], v[122:125]
	v_mfma_i32_16x16x64_i8 v[118:121], v[156:159], v[212:215], v[118:121]
	v_mfma_i32_16x16x64_i8 v[114:117], v[164:167], v[212:215], v[114:117]
	v_mfma_i32_16x16x64_i8 v[102:105], v[156:159], v[220:223], v[102:105]
	v_mfma_i32_16x16x64_i8 v[98:101], v[164:167], v[220:223], v[98:101]
	v_mfma_i32_16x16x64_i8 v[86:89], v[156:159], v[228:231], v[86:89]
	v_mfma_i32_16x16x64_i8 v[82:85], v[164:167], v[228:231], v[82:85]
	v_mfma_i32_16x16x64_i8 v[110:113], v[168:171], v[192:195], v[110:113]
	v_mfma_i32_16x16x64_i8 v[106:109], v[184:187], v[192:195], v[106:109]
	v_mfma_i32_16x16x64_i8 v[94:97], v[168:171], v[200:203], v[94:97]
	v_mfma_i32_16x16x64_i8 v[90:93], v[184:187], v[200:203], v[90:93]
	v_mfma_i32_16x16x64_i8 v[78:81], v[168:171], v[216:219], v[78:81]
	v_mfma_i32_16x16x64_i8 v[74:77], v[184:187], v[216:219], v[74:77]
	v_mfma_i32_16x16x64_i8 v[70:73], v[168:171], v[224:227], v[70:73]
	v_mfma_i32_16x16x64_i8 v[66:69], v[184:187], v[224:227], v[66:69]
	v_mfma_i32_16x16x64_i8 v[110:113], v[180:183], v[196:199], v[110:113]
	v_mfma_i32_16x16x64_i8 v[106:109], v[188:191], v[196:199], v[106:109]
	v_mfma_i32_16x16x64_i8 v[94:97], v[180:183], v[212:215], v[94:97]
	v_mfma_i32_16x16x64_i8 v[90:93], v[188:191], v[212:215], v[90:93]
	v_mfma_i32_16x16x64_i8 v[78:81], v[180:183], v[220:223], v[78:81]
	v_mfma_i32_16x16x64_i8 v[74:77], v[188:191], v[220:223], v[74:77]
	v_mfma_i32_16x16x64_i8 v[70:73], v[180:183], v[228:231], v[70:73]
	v_mfma_i32_16x16x64_i8 v[66:69], v[188:191], v[228:231], v[66:69]
	s_barrier
; #define PG8_STAGE(bufoff, gbase, voff) do { _Pragma("unroll") for (int _i = 0; _i < 2; ++_i) \
;         __builtin_amdgcn_global_load_lds((const unsigned*)((const char*)(gbase) + (voff)[_i]), (LAS unsigned*)(lds + (bufoff) + ldsw + _i * 8192), 16, 0, 0); } while (0)
; #define PG8_LDA(dst, b, h) do { _Pragma("unroll") for (int m = 0; m < 4; ++m) _Pragma("unroll") for (int k = 0; k < 2; ++k) dst[m][k] = *(const LAS bf16x8*)(lds + PG8_SA(b, h) + aoff + m * 2048 + k * 1024); } while (0)
; #define PG8_MMA(ai, bj, At, Bt) do { __builtin_amdgcn_s_setprio(1); _Pragma("unroll") for (int m = 0; m < 4; ++m) _Pragma("unroll") for (int n = 0; n < 2; ++n) _Pragma("unroll") for (int k = 0; k < 2; ++k) \
;         acc[ai][bj][m][n] = mma16<I8>(Bt[n][k], At[m][k], acc[ai][bj][m][n]); __builtin_amdgcn_s_setprio(0); } while (0)
; #define PG8_WAIT_V(n) asm volatile("s_waitcnt vmcnt(" #n ")" ::: "memory")
; #define PG8_WAIT_L(n) asm volatile("s_waitcnt lgkmcnt(" #n ")" ::: "memory")
; #define PG8_BAR __builtin_amdgcn_s_barrier()
; #define PG8_SCHED __builtin_amdgcn_sched_barrier(0)
; template <class Epi, class Sched, bool I8 = false>
; __device__ __forceinline__ void gemm_phase(LAS unsigned char* lds, const Gemm g, const Sched& S, const Epi& E) {
;     ...
;             PG8_LDA(At, 1, 1); PG8_STAGE(PG8_SB(1, 0), b3, voffB); PG8_STAGE(PG8_SB(1, 1), b3 + hstepB, voffB); PG8_STAGE(PG8_SA(1, 0), a3, voffA);
;             PG8_WAIT_V(8); PG8_WAIT_L(0); PG8_BAR; PG8_MMA(1, 0, At, B0); PG8_MMA(1, 1, At, B1); PG8_BAR; PG8_SCHED;
;     ...
;         if (PG8_ALIGN) { if (wr == 0) PG8_BAR; }
	s_add_i32 s26, s31, s42
	v_lshl_add_u64 v[172:173], v[172:173], 0, s[12:13]
	s_mov_b32 m0, s26
	ds_read_b128 v[192:195], v179 offset:49152
	ds_read_b128 v[196:199], v179 offset:50176
	ds_read_b128 v[200:203], v179 offset:51200
	ds_read_b128 v[212:215], v179 offset:52224
	ds_read_b128 v[216:219], v179 offset:53248
	ds_read_b128 v[220:223], v179 offset:54272
	ds_read_b128 v[224:227], v179 offset:55296
	ds_read_b128 v[228:231], v179 offset:56320
	global_load_lds_dwordx4 v[172:173], off
	s_add_i32 m0, s26, 0x2000
	s_add_u32 s6, s6, 0x10080
	v_lshl_add_u64 v[172:173], v[232:233], 0, s[12:13]
	s_addc_u32 s7, s7, 0
	s_add_i32 s26, s34, s42
	global_load_lds_dwordx4 v[172:173], off
	v_lshl_add_u64 v[172:173], s[6:7], 0, v[136:137]
	s_mov_b32 m0, s26
	s_nop 0
	global_load_lds_dwordx4 v[172:173], off
	v_lshl_add_u64 v[172:173], s[6:7], 0, v[132:133]
	s_add_i32 m0, s26, 0x2000
	s_nop 0
	global_load_lds_dwordx4 v[172:173], off
	v_lshl_add_u64 v[172:173], v[234:235], 0, s[12:13]
	s_mov_b32 m0, s83
	s_nop 0
	global_load_lds_dwordx4 v[172:173], off
	v_lshl_add_u64 v[172:173], v[236:237], 0, s[12:13]
	s_mov_b32 m0, s94
	s_nop 0
	global_load_lds_dwordx4 v[172:173], off
	s_waitcnt vmcnt(8)
	s_waitcnt lgkmcnt(0)
	s_barrier
	s_waitcnt lgkmcnt(0)
	v_mfma_i32_16x16x64_i8 v[62:65], v[152:155], v[192:195], v[62:65]
	v_mfma_i32_16x16x64_i8 v[58:61], v[160:163], v[192:195], v[58:61]
	v_mfma_i32_16x16x64_i8 v[54:57], v[152:155], v[200:203], v[54:57]
	v_mfma_i32_16x16x64_i8 v[50:53], v[160:163], v[200:203], v[50:53]
	v_mfma_i32_16x16x64_i8 v[30:33], v[152:155], v[216:219], v[30:33]
	v_mfma_i32_16x16x64_i8 v[26:29], v[160:163], v[216:219], v[26:29]
	v_mfma_i32_16x16x64_i8 v[14:17], v[152:155], v[224:227], v[14:17]
	v_mfma_i32_16x16x64_i8 v[10:13], v[160:163], v[224:227], v[10:13]
	v_mfma_i32_16x16x64_i8 v[62:65], v[156:159], v[196:199], v[62:65]
	v_mfma_i32_16x16x64_i8 v[58:61], v[164:167], v[196:199], v[58:61]
	v_mfma_i32_16x16x64_i8 v[54:57], v[156:159], v[212:215], v[54:57]
	v_mfma_i32_16x16x64_i8 v[50:53], v[164:167], v[212:215], v[50:53]
	v_mfma_i32_16x16x64_i8 v[30:33], v[156:159], v[220:223], v[30:33]
	v_mfma_i32_16x16x64_i8 v[26:29], v[164:167], v[220:223], v[26:29]
	v_mfma_i32_16x16x64_i8 v[14:17], v[156:159], v[228:231], v[14:17]
	v_mfma_i32_16x16x64_i8 v[10:13], v[164:167], v[228:231], v[10:13]
	v_mfma_i32_16x16x64_i8 v[46:49], v[168:171], v[192:195], v[46:49]
	v_mfma_i32_16x16x64_i8 v[42:45], v[184:187], v[192:195], v[42:45]
	v_mfma_i32_16x16x64_i8 v[38:41], v[168:171], v[200:203], v[38:41]
	v_mfma_i32_16x16x64_i8 v[34:37], v[184:187], v[200:203], v[34:37]
	v_mfma_i32_16x16x64_i8 v[22:25], v[168:171], v[216:219], v[22:25]
	v_mfma_i32_16x16x64_i8 v[18:21], v[184:187], v[216:219], v[18:21]
	v_mfma_i32_16x16x64_i8 v[6:9], v[168:171], v[224:227], v[6:9]
	v_mfma_i32_16x16x64_i8 v[2:5], v[184:187], v[224:227], v[2:5]
	v_mfma_i32_16x16x64_i8 v[46:49], v[180:183], v[196:199], v[46:49]
	v_mfma_i32_16x16x64_i8 v[42:45], v[188:191], v[196:199], v[42:45]
	v_mfma_i32_16x16x64_i8 v[38:41], v[180:183], v[212:215], v[38:41]
	v_mfma_i32_16x16x64_i8 v[34:37], v[188:191], v[212:215], v[34:37]
	v_mfma_i32_16x16x64_i8 v[22:25], v[180:183], v[220:223], v[22:25]
	v_mfma_i32_16x16x64_i8 v[18:21], v[188:191], v[220:223], v[18:21]
	v_mfma_i32_16x16x64_i8 v[6:9], v[180:183], v[228:231], v[6:9]
	v_mfma_i32_16x16x64_i8 v[2:5], v[188:191], v[228:231], v[2:5]
	s_barrier
	s_add_i32 s30, s30, 2
	s_add_u32 s0, s0, 0x100
	s_addc_u32 s1, s1, 0
	s_add_u32 s24, s24, 0x100
	s_addc_u32 s25, s25, 0
	s_cmp_gt_u32 s30, 13
	s_cbranch_scc0 .LBB0_539
	s_and_b64 vcc, exec, s[36:37]
	s_cbranch_vccz .LBB0_542
	s_barrier

;     __device__ __forceinline__ bool next(int i, Unit& u) const { u.seg = 0; u.ks = -1; u.nt = ntk; u.koff = 0; return unit(i, u); }
;     __device__ __forceinline__ bool next(int i, Unit& u) const { const int t = i / 3; u.seg = i - 3 * t; u.ks = -1; u.nt = ntk; u.koff = 0; return unit(t, u); }
;     __device__ __forceinline__ bool next(int i, Unit& u) const { if (i > 0 || c < 80 || c >= 144) return false; const int k = c - 80; u.pm = k & 1; u.pn = k >> 1; u.seg = 0; u.ks = -1; u.nt = DM / BK; u.koff = 0; return true; }
; #define PG8_STAGE(bufoff, gbase, voff) do { _Pragma("unroll") for (int _i = 0; _i < 2; ++_i) \
;         __builtin_amdgcn_global_load_lds((const unsigned*)((const char*)(gbase) + (voff)[_i]), (LAS unsigned*)(lds + (bufoff) + ldsw + _i * 8192), 16, 0, 0); } while (0)
; #define PG8_LDA(dst, b, h) do { _Pragma("unroll") for (int m = 0; m < 4; ++m) _Pragma("unroll") for (int k = 0; k < 2; ++k) dst[m][k] = *(const LAS bf16x8*)(lds + PG8_SA(b, h) + aoff + m * 2048 + k * 1024); } while (0)
; template <class Epi, class Sched, bool I8 = false>
; __device__ __forceinline__ void gemm_phase(LAS unsigned char* lds, const Gemm g, const Sched& S, const Epi& E) {
;     ...
;         const bool has_next = S.next(ui + 1, nxt);
;         const char* nA = has_next ? g.A + (size_t)nxt.seg * g.segA + (size_t)nxt.pm * tstepA + nxt.koff : cA; const char* nB = has_next ? g.Bt + (size_t)nxt.seg * g.segB + (size_t)nxt.pn * tstepB + nxt.koff : cB;
;         const int nt = cur.nt;
;         for (int t = 0; t < nt; t += 2) {
;             const bool last = (t == nt - 2);
;             const char* a1 = cA + (size_t)(t + 1) * kstep;
;             const char* a2 = last ? nA : cA + (size_t)(t + 2) * kstep; const char* b2 = last ? nB : cB + (size_t)(t + 2) * kstep;
;             const char* a3 = a2 + kstep; const char* b3 = b2 + kstep;
;             if (PG8_SP2) {
;             PG8_LDB(B0, 0, 0); PG8_LDB(B1, 0, 1); PG8_SCHED; PG8_LDA(At, 0, 0); PG8_STAGE(PG8_SA(1, 1), a1 + hstepA, voffA);
;             PG8_WAIT_V(8); PG8_WAIT_L(0); PG8_BAR; PG8_MMA(0, 0, At, B0); PG8_MMA(0, 1, At, B1); PG8_BAR; PG8_SCHED;
;             PG8_LDA(At, 0, 1); PG8_STAGE(PG8_SB(0, 0), b2, voffB); PG8_STAGE(PG8_SB(0, 1), b2 + hstepB, voffB); PG8_STAGE(PG8_SA(0, 0), a2, voffA);
;             PG8_WAIT_V(8); PG8_WAIT_L(0); PG8_BAR; PG8_MMA(1, 0, At, B0); PG8_MMA(1, 1, At, B1); PG8_BAR; PG8_SCHED;
.LBB0_768:
	s_add_u32 s40, s0, 0xfffc0080
	s_addc_u32 s41, s1, -1
	s_add_i32 s46, 0, 0x10000
	s_cmp_eq_u32 s45, 12
	s_cselect_b32 s43, s37, s41
	s_cselect_b32 s42, s36, s40
	s_cselect_b32 s41, s9, s44
	s_cselect_b32 s40, s17, s27
	s_add_i32 s49, 0, 0x14000
	v_add_u32_e32 v14, s46, v163
	v_add_u32_e32 v130, s49, v163
	ds_read_b128 v[2:5], v14
	ds_read_b128 v[6:9], v14 offset:1024
	ds_read_b128 v[10:13], v14 offset:2048
	ds_read_b128 v[14:17], v14 offset:3072
	ds_read_b128 v[132:135], v130
	ds_read_b128 v[174:177], v130 offset:1024
	ds_read_b128 v[178:181], v130 offset:2048
	ds_read_b128 v[182:185], v130 offset:3072
	v_lshl_add_u64 v[136:137], s[0:1], 0, v[170:171]
	s_add_i32 m0, s14, 0xc000
	ds_read_b128 v[186:189], v167
	ds_read_b128 v[190:193], v167 offset:1024
	ds_read_b128 v[194:197], v167 offset:2048
	ds_read_b128 v[198:201], v167 offset:3072
	ds_read_b128 v[212:215], v167 offset:4096
	ds_read_b128 v[216:219], v167 offset:5120
	ds_read_b128 v[220:223], v167 offset:6144
	ds_read_b128 v[224:227], v167 offset:7168
	global_load_lds_dwordx4 v[136:137], off
	v_lshl_add_u64 v[136:137], s[0:1], 0, v[172:173]
	s_add_i32 m0, s14, 0xe000
	s_nop 0
	global_load_lds_dwordx4 v[136:137], off
	s_waitcnt vmcnt(8)
	s_waitcnt lgkmcnt(0)
	s_barrier
	s_waitcnt lgkmcnt(0)
	v_mfma_f32_16x16x32_bf16 v[150:153], v[2:5], v[186:189], v[150:153]
	v_mfma_f32_16x16x32_bf16 v[146:149], v[10:13], v[186:189], v[146:149]
	v_mfma_f32_16x16x32_bf16 v[142:145], v[2:5], v[194:197], v[142:145]
	v_mfma_f32_16x16x32_bf16 v[136:139], v[10:13], v[194:197], v[138:141]
	v_mfma_f32_16x16x32_bf16 v[126:129], v[2:5], v[212:215], v[126:129]
	v_mfma_f32_16x16x32_bf16 v[122:125], v[10:13], v[212:215], v[122:125]
	v_mfma_f32_16x16x32_bf16 v[118:121], v[2:5], v[220:223], v[118:121]
	v_mfma_f32_16x16x32_bf16 v[114:117], v[10:13], v[220:223], v[114:117]
	v_mfma_f32_16x16x32_bf16 v[150:153], v[6:9], v[190:193], v[150:153]
	v_mfma_f32_16x16x32_bf16 v[146:149], v[14:17], v[190:193], v[146:149]
	v_mfma_f32_16x16x32_bf16 v[142:145], v[6:9], v[198:201], v[142:145]
	v_mfma_f32_16x16x32_bf16 v[136:139], v[14:17], v[198:201], v[136:139]
	v_mfma_f32_16x16x32_bf16 v[126:129], v[6:9], v[216:219], v[126:129]
	v_mfma_f32_16x16x32_bf16 v[122:125], v[14:17], v[216:219], v[122:125]
	v_mfma_f32_16x16x32_bf16 v[118:121], v[6:9], v[224:227], v[118:121]
	v_mfma_f32_16x16x32_bf16 v[114:117], v[14:17], v[224:227], v[114:117]
	v_mfma_f32_16x16x32_bf16 v[110:113], v[132:135], v[186:189], v[110:113]
	v_mfma_f32_16x16x32_bf16 v[106:109], v[178:181], v[186:189], v[106:109]
	v_mfma_f32_16x16x32_bf16 v[102:105], v[132:135], v[194:197], v[102:105]
	v_mfma_f32_16x16x32_bf16 v[98:101], v[178:181], v[194:197], v[98:101]
	v_mfma_f32_16x16x32_bf16 v[94:97], v[132:135], v[212:215], v[94:97]
	v_mfma_f32_16x16x32_bf16 v[90:93], v[178:181], v[212:215], v[90:93]
	v_mfma_f32_16x16x32_bf16 v[86:89], v[132:135], v[220:223], v[86:89]
	v_mfma_f32_16x16x32_bf16 v[82:85], v[178:181], v[220:223], v[82:85]
	v_mfma_f32_16x16x32_bf16 v[110:113], v[174:177], v[190:193], v[110:113]
	v_mfma_f32_16x16x32_bf16 v[106:109], v[182:185], v[190:193], v[106:109]
	v_mfma_f32_16x16x32_bf16 v[102:105], v[174:177], v[198:201], v[102:105]
	v_mfma_f32_16x16x32_bf16 v[98:101], v[182:185], v[198:201], v[98:101]
	v_mfma_f32_16x16x32_bf16 v[94:97], v[174:177], v[216:219], v[94:97]
	v_mfma_f32_16x16x32_bf16 v[90:93], v[182:185], v[216:219], v[90:93]
	v_mfma_f32_16x16x32_bf16 v[86:89], v[174:177], v[224:227], v[86:89]
	v_mfma_f32_16x16x32_bf16 v[82:85], v[182:185], v[224:227], v[82:85]
	s_barrier
	s_add_i32 s46, s46, s21
	v_lshl_add_u64 v[202:203], s[40:41], 0, v[158:159]
	s_mov_b32 m0, s46
	ds_read_b128 v[186:189], v167 offset:16384
	ds_read_b128 v[190:193], v167 offset:17408
	ds_read_b128 v[194:197], v167 offset:18432
	ds_read_b128 v[198:201], v167 offset:19456
	ds_read_b128 v[212:215], v167 offset:20480
	ds_read_b128 v[216:219], v167 offset:21504
	ds_read_b128 v[220:223], v167 offset:22528
	ds_read_b128 v[224:227], v167 offset:23552
	global_load_lds_dwordx4 v[202:203], off
	s_add_i32 m0, s46, 0x2000
	s_add_u32 s46, s40, 0x10000
	v_lshl_add_u64 v[232:233], s[40:41], 0, v[154:155]
	s_addc_u32 s47, s41, 0
	s_add_i32 s49, s49, s21
	global_load_lds_dwordx4 v[232:233], off
	v_lshl_add_u64 v[140:141], s[46:47], 0, v[158:159]
	s_mov_b32 m0, s49
	v_lshl_add_u64 v[234:235], s[42:43], 0, v[160:161]
	global_load_lds_dwordx4 v[140:141], off
	v_lshl_add_u64 v[140:141], s[46:47], 0, v[154:155]
	s_add_i32 m0, s49, 0x2000
	v_lshl_add_u64 v[236:237], s[42:43], 0, v[156:157]
	global_load_lds_dwordx4 v[140:141], off
	s_mov_b32 m0, s14
	s_nop 0
	global_load_lds_dwordx4 v[234:235], off
	s_mov_b32 m0, s22
	s_nop 0
	global_load_lds_dwordx4 v[236:237], off
	s_waitcnt vmcnt(8)
	s_waitcnt lgkmcnt(0)
	s_barrier
; #define PG8_STAGE(bufoff, gbase, voff) do { _Pragma("unroll") for (int _i = 0; _i < 2; ++_i) \
;         __builtin_amdgcn_global_load_lds((const unsigned*)((const char*)(gbase) + (voff)[_i]), (LAS unsigned*)(lds + (bufoff) + ldsw + _i * 8192), 16, 0, 0); } while (0)
; #define PG8_LDA(dst, b, h) do { _Pragma("unroll") for (int m = 0; m < 4; ++m) _Pragma("unroll") for (int k = 0; k < 2; ++k) dst[m][k] = *(const LAS bf16x8*)(lds + PG8_SA(b, h) + aoff + m * 2048 + k * 1024); } while (0)
; #define PG8_LDB(dst, b, h) do { _Pragma("unroll") for (int n = 0; n < 2; ++n) _Pragma("unroll") for (int k = 0; k < 2; ++k) dst[n][k] = *(const LAS bf16x8*)(lds + PG8_SB(b, h) + boff + n * 2048 + k * 1024); } while (0)
; #define PG8_MMA(ai, bj, At, Bt) do { __builtin_amdgcn_s_setprio(1); _Pragma("unroll") for (int m = 0; m < 4; ++m) _Pragma("unroll") for (int n = 0; n < 2; ++n) _Pragma("unroll") for (int k = 0; k < 2; ++k) \
;         acc[ai][bj][m][n] = mma16<I8>(Bt[n][k], At[m][k], acc[ai][bj][m][n]); __builtin_amdgcn_s_setprio(0); } while (0)
; #define PG8_WAIT_V(n) asm volatile("s_waitcnt vmcnt(" #n ")" ::: "memory")
; #define PG8_WAIT_L(n) asm volatile("s_waitcnt lgkmcnt(" #n ")" ::: "memory")
; #define PG8_BAR __builtin_amdgcn_s_barrier()
; #define PG8_SCHED __builtin_amdgcn_sched_barrier(0)
; template <class Epi, class Sched, bool I8 = false>
; __device__ __forceinline__ void gemm_phase(LAS unsigned char* lds, const Gemm g, const Sched& S, const Epi& E) {
;     ...
;             PG8_WAIT_V(8); PG8_WAIT_L(0); PG8_BAR; PG8_MMA(1, 0, At, B0); PG8_MMA(1, 1, At, B1); PG8_BAR; PG8_SCHED;
;             PG8_LDB(B0, 1, 0); PG8_LDB(B1, 1, 1); PG8_SCHED; PG8_LDA(At, 1, 0); PG8_STAGE(PG8_SA(0, 1), a2 + hstepA, voffA);
;             PG8_WAIT_V(8); PG8_WAIT_L(0); PG8_BAR; PG8_MMA(0, 0, At, B0); PG8_MMA(0, 1, At, B1); PG8_BAR; PG8_SCHED;
	s_waitcnt lgkmcnt(0)
	v_mfma_f32_16x16x32_bf16 v[78:81], v[2:5], v[186:189], v[78:81]
	v_mfma_f32_16x16x32_bf16 v[74:77], v[10:13], v[186:189], v[74:77]
	v_mfma_f32_16x16x32_bf16 v[70:73], v[2:5], v[194:197], v[70:73]
	v_mfma_f32_16x16x32_bf16 v[66:69], v[10:13], v[194:197], v[66:69]
	v_mfma_f32_16x16x32_bf16 v[62:65], v[2:5], v[212:215], v[62:65]
	v_mfma_f32_16x16x32_bf16 v[58:61], v[10:13], v[212:215], v[58:61]
	v_mfma_f32_16x16x32_bf16 v[2:5], v[2:5], v[220:223], v[54:57]
	v_mfma_f32_16x16x32_bf16 v[78:81], v[6:9], v[190:193], v[78:81]
	v_mfma_f32_16x16x32_bf16 v[74:77], v[14:17], v[190:193], v[74:77]
	v_mfma_f32_16x16x32_bf16 v[70:73], v[6:9], v[198:201], v[70:73]
	v_mfma_f32_16x16x32_bf16 v[66:69], v[14:17], v[198:201], v[66:69]
	v_mfma_f32_16x16x32_bf16 v[62:65], v[6:9], v[216:219], v[62:65]
	v_mfma_f32_16x16x32_bf16 v[58:61], v[14:17], v[216:219], v[58:61]
	v_mfma_f32_16x16x32_bf16 v[2:5], v[6:9], v[224:227], v[2:5]
	v_mfma_f32_16x16x32_bf16 v[6:9], v[10:13], v[220:223], v[50:53]
	v_mfma_f32_16x16x32_bf16 v[6:9], v[14:17], v[224:227], v[6:9]
	v_mfma_f32_16x16x32_bf16 v[38:41], v[132:135], v[194:197], v[38:41]
	v_mfma_f32_16x16x32_bf16 v[34:37], v[178:181], v[194:197], v[34:37]
	v_mfma_f32_16x16x32_bf16 v[30:33], v[132:135], v[212:215], v[30:33]
	v_mfma_f32_16x16x32_bf16 v[26:29], v[178:181], v[212:215], v[26:29]
	v_mfma_f32_16x16x32_bf16 v[22:25], v[132:135], v[220:223], v[22:25]
	v_mfma_f32_16x16x32_bf16 v[18:21], v[178:181], v[220:223], v[18:21]
	v_mfma_f32_16x16x32_bf16 v[10:13], v[132:135], v[186:189], v[46:49]
	v_mfma_f32_16x16x32_bf16 v[14:17], v[178:181], v[186:189], v[42:45]
	v_mfma_f32_16x16x32_bf16 v[38:41], v[174:177], v[198:201], v[38:41]
	v_mfma_f32_16x16x32_bf16 v[34:37], v[182:185], v[198:201], v[34:37]
	v_mfma_f32_16x16x32_bf16 v[30:33], v[174:177], v[216:219], v[30:33]
	v_mfma_f32_16x16x32_bf16 v[26:29], v[182:185], v[216:219], v[26:29]
	v_mfma_f32_16x16x32_bf16 v[22:25], v[174:177], v[224:227], v[22:25]
	v_mfma_f32_16x16x32_bf16 v[18:21], v[182:185], v[224:227], v[18:21]
	v_mfma_f32_16x16x32_bf16 v[10:13], v[174:177], v[190:193], v[10:13]
	v_mfma_f32_16x16x32_bf16 v[14:17], v[182:185], v[190:193], v[14:17]
	s_barrier
	s_add_i32 s46, 0, 0x18000
	v_add_u32_e32 v54, s46, v163
	s_add_i32 s47, 0, 0x1c000
	ds_read_b128 v[42:45], v54
	ds_read_b128 v[46:49], v54 offset:1024
	ds_read_b128 v[50:53], v54 offset:2048
	ds_read_b128 v[132:135], v54 offset:3072
	v_add_u32_e32 v54, s47, v163
	ds_read_b128 v[174:177], v54
	ds_read_b128 v[178:181], v54 offset:1024
	ds_read_b128 v[182:185], v54 offset:2048
	ds_read_b128 v[186:189], v54 offset:3072
	s_add_u32 s42, s42, 0x40000
	s_addc_u32 s43, s43, 0
	s_mov_b32 m0, s23
	v_lshl_add_u64 v[140:141], s[42:43], 0, v[160:161]
	ds_read_b128 v[54:57], v167 offset:32768
	ds_read_b128 v[190:193], v167 offset:33792
	ds_read_b128 v[194:197], v167 offset:34816
	ds_read_b128 v[198:201], v167 offset:35840
	ds_read_b128 v[212:215], v167 offset:36864
	ds_read_b128 v[216:219], v167 offset:37888
	ds_read_b128 v[220:223], v167 offset:38912
	ds_read_b128 v[224:227], v167 offset:39936
	global_load_lds_dwordx4 v[140:141], off
	v_lshl_add_u64 v[140:141], s[42:43], 0, v[156:157]
	s_mov_b32 m0, s24
	s_nop 0
	global_load_lds_dwordx4 v[140:141], off
	s_waitcnt vmcnt(8)
	s_waitcnt lgkmcnt(0)
	s_barrier
	s_waitcnt lgkmcnt(0)
	v_mfma_f32_16x16x32_bf16 v[150:153], v[42:45], v[54:57], v[150:153]
	v_mfma_f32_16x16x32_bf16 v[146:149], v[50:53], v[54:57], v[146:149]
	v_mfma_f32_16x16x32_bf16 v[140:143], v[42:45], v[194:197], v[142:145]
	v_mfma_f32_16x16x32_bf16 v[136:139], v[50:53], v[194:197], v[136:139]
	v_mfma_f32_16x16x32_bf16 v[126:129], v[42:45], v[212:215], v[126:129]
	v_mfma_f32_16x16x32_bf16 v[122:125], v[50:53], v[212:215], v[122:125]
	v_mfma_f32_16x16x32_bf16 v[118:121], v[42:45], v[220:223], v[118:121]
	v_mfma_f32_16x16x32_bf16 v[114:117], v[50:53], v[220:223], v[114:117]
	v_mfma_f32_16x16x32_bf16 v[150:153], v[46:49], v[190:193], v[150:153]
	v_mfma_f32_16x16x32_bf16 v[146:149], v[132:135], v[190:193], v[146:149]
	v_mfma_f32_16x16x32_bf16 v[142:145], v[46:49], v[198:201], v[140:143]
	v_mfma_f32_16x16x32_bf16 v[138:141], v[132:135], v[198:201], v[136:139]
	v_mfma_f32_16x16x32_bf16 v[126:129], v[46:49], v[216:219], v[126:129]
	v_mfma_f32_16x16x32_bf16 v[122:125], v[132:135], v[216:219], v[122:125]
	v_mfma_f32_16x16x32_bf16 v[118:121], v[46:49], v[224:227], v[118:121]
	v_mfma_f32_16x16x32_bf16 v[114:117], v[132:135], v[224:227], v[114:117]
	v_mfma_f32_16x16x32_bf16 v[110:113], v[174:177], v[54:57], v[110:113]
	v_mfma_f32_16x16x32_bf16 v[54:57], v[182:185], v[54:57], v[106:109]
	v_mfma_f32_16x16x32_bf16 v[106:109], v[186:189], v[190:193], v[54:57]
	v_mfma_f32_16x16x32_bf16 v[54:57], v[174:177], v[194:197], v[102:105]
	v_mfma_f32_16x16x32_bf16 v[102:105], v[178:181], v[198:201], v[54:57]
	v_mfma_f32_16x16x32_bf16 v[54:57], v[182:185], v[194:197], v[98:101]
	v_mfma_f32_16x16x32_bf16 v[98:101], v[186:189], v[198:201], v[54:57]
	v_mfma_f32_16x16x32_bf16 v[54:57], v[174:177], v[212:215], v[94:97]
	v_mfma_f32_16x16x32_bf16 v[94:97], v[178:181], v[216:219], v[54:57]
	v_mfma_f32_16x16x32_bf16 v[54:57], v[182:185], v[212:215], v[90:93]
	v_mfma_f32_16x16x32_bf16 v[90:93], v[186:189], v[216:219], v[54:57]
	v_mfma_f32_16x16x32_bf16 v[54:57], v[174:177], v[220:223], v[86:89]
	v_mfma_f32_16x16x32_bf16 v[86:89], v[178:181], v[224:227], v[54:57]
	v_mfma_f32_16x16x32_bf16 v[54:57], v[182:185], v[220:223], v[82:85]
	v_mfma_f32_16x16x32_bf16 v[110:113], v[178:181], v[190:193], v[110:113]
	v_mfma_f32_16x16x32_bf16 v[82:85], v[186:189], v[224:227], v[54:57]
	s_barrier
; #define PG8_STAGE(bufoff, gbase, voff) do { _Pragma("unroll") for (int _i = 0; _i < 2; ++_i) \
;         __builtin_amdgcn_global_load_lds((const unsigned*)((const char*)(gbase) + (voff)[_i]), (LAS unsigned*)(lds + (bufoff) + ldsw + _i * 8192), 16, 0, 0); } while (0)
; #define PG8_LDA(dst, b, h) do { _Pragma("unroll") for (int m = 0; m < 4; ++m) _Pragma("unroll") for (int k = 0; k < 2; ++k) dst[m][k] = *(const LAS bf16x8*)(lds + PG8_SA(b, h) + aoff + m * 2048 + k * 1024); } while (0)
; #define PG8_MMA(ai, bj, At, Bt) do { __builtin_amdgcn_s_setprio(1); _Pragma("unroll") for (int m = 0; m < 4; ++m) _Pragma("unroll") for (int n = 0; n < 2; ++n) _Pragma("unroll") for (int k = 0; k < 2; ++k) \
;         acc[ai][bj][m][n] = mma16<I8>(Bt[n][k], At[m][k], acc[ai][bj][m][n]); __builtin_amdgcn_s_setprio(0); } while (0)
; #define PG8_WAIT_V(n) asm volatile("s_waitcnt vmcnt(" #n ")" ::: "memory")
; #define PG8_WAIT_L(n) asm volatile("s_waitcnt lgkmcnt(" #n ")" ::: "memory")
; #define PG8_BAR __builtin_amdgcn_s_barrier()
; #define PG8_SCHED __builtin_amdgcn_sched_barrier(0)
; template <class Epi, class Sched, bool I8 = false>
; __device__ __forceinline__ void gemm_phase(LAS unsigned char* lds, const Gemm g, const Sched& S, const Epi& E) {
;     ...
;             PG8_LDA(At, 1, 1); PG8_STAGE(PG8_SB(1, 0), b3, voffB); PG8_STAGE(PG8_SB(1, 1), b3 + hstepB, voffB); PG8_STAGE(PG8_SA(1, 0), a3, voffA);
;             PG8_WAIT_V(8); PG8_WAIT_L(0); PG8_BAR; PG8_MMA(1, 0, At, B0); PG8_MMA(1, 1, At, B1); PG8_BAR; PG8_SCHED;
	s_add_i32 s42, s46, s21
	s_nop 2
	v_lshl_add_u64 v[54:55], v[202:203], 0, s[12:13]
	s_mov_b32 m0, s42
	ds_read_b128 v[190:193], v167 offset:49152
	ds_read_b128 v[194:197], v167 offset:50176
	ds_read_b128 v[198:201], v167 offset:51200
	ds_read_b128 v[212:215], v167 offset:52224
	ds_read_b128 v[216:219], v167 offset:53248
	ds_read_b128 v[220:223], v167 offset:54272
	ds_read_b128 v[224:227], v167 offset:55296
	ds_read_b128 v[228:231], v167 offset:56320
	global_load_lds_dwordx4 v[54:55], off
	s_add_i32 m0, s42, 0x2000
	s_add_u32 s40, s40, 0x10080
	v_lshl_add_u64 v[54:55], v[232:233], 0, s[12:13]
	s_addc_u32 s41, s41, 0
	s_add_i32 s42, s47, s21
	global_load_lds_dwordx4 v[54:55], off
	v_lshl_add_u64 v[54:55], s[40:41], 0, v[158:159]
	s_mov_b32 m0, s42
	s_nop 0
	global_load_lds_dwordx4 v[54:55], off
	v_lshl_add_u64 v[54:55], s[40:41], 0, v[154:155]
	s_add_i32 m0, s42, 0x2000
	s_nop 0
	global_load_lds_dwordx4 v[54:55], off
	v_lshl_add_u64 v[54:55], v[234:235], 0, s[12:13]
	s_mov_b32 m0, s29
	s_nop 0
	global_load_lds_dwordx4 v[54:55], off
	v_lshl_add_u64 v[54:55], v[236:237], 0, s[12:13]
	s_mov_b32 m0, s30
	s_nop 0
	global_load_lds_dwordx4 v[54:55], off
	s_waitcnt vmcnt(8)
	s_waitcnt lgkmcnt(0)
	s_barrier
	s_waitcnt lgkmcnt(0)
	v_mfma_f32_16x16x32_bf16 v[54:57], v[42:45], v[190:193], v[78:81]
	v_mfma_f32_16x16x32_bf16 v[78:81], v[46:49], v[194:197], v[54:57]
	v_mfma_f32_16x16x32_bf16 v[54:57], v[50:53], v[190:193], v[74:77]
	v_mfma_f32_16x16x32_bf16 v[74:77], v[132:135], v[194:197], v[54:57]
	v_mfma_f32_16x16x32_bf16 v[54:57], v[42:45], v[198:201], v[70:73]
	v_mfma_f32_16x16x32_bf16 v[70:73], v[46:49], v[212:215], v[54:57]
	v_mfma_f32_16x16x32_bf16 v[54:57], v[50:53], v[198:201], v[66:69]
	v_mfma_f32_16x16x32_bf16 v[66:69], v[132:135], v[212:215], v[54:57]
	v_mfma_f32_16x16x32_bf16 v[54:57], v[42:45], v[216:219], v[62:65]
	v_mfma_f32_16x16x32_bf16 v[62:65], v[46:49], v[220:223], v[54:57]
	v_mfma_f32_16x16x32_bf16 v[54:57], v[50:53], v[216:219], v[58:61]
	v_mfma_f32_16x16x32_bf16 v[2:5], v[42:45], v[224:227], v[2:5]
	v_mfma_f32_16x16x32_bf16 v[58:61], v[132:135], v[220:223], v[54:57]
	v_mfma_f32_16x16x32_bf16 v[54:57], v[46:49], v[228:231], v[2:5]
	v_mfma_f32_16x16x32_bf16 v[2:5], v[50:53], v[224:227], v[6:9]
	v_mfma_f32_16x16x32_bf16 v[50:53], v[132:135], v[228:231], v[2:5]
	v_mfma_f32_16x16x32_bf16 v[2:5], v[174:177], v[190:193], v[10:13]
	v_mfma_f32_16x16x32_bf16 v[46:49], v[178:181], v[194:197], v[2:5]
	v_mfma_f32_16x16x32_bf16 v[2:5], v[182:185], v[190:193], v[14:17]
	v_mfma_f32_16x16x32_bf16 v[42:45], v[186:189], v[194:197], v[2:5]
	v_mfma_f32_16x16x32_bf16 v[2:5], v[174:177], v[198:201], v[38:41]
	v_mfma_f32_16x16x32_bf16 v[38:41], v[178:181], v[212:215], v[2:5]
	v_mfma_f32_16x16x32_bf16 v[2:5], v[182:185], v[198:201], v[34:37]
	v_mfma_f32_16x16x32_bf16 v[34:37], v[186:189], v[212:215], v[2:5]
	v_mfma_f32_16x16x32_bf16 v[2:5], v[174:177], v[216:219], v[30:33]
	v_mfma_f32_16x16x32_bf16 v[30:33], v[178:181], v[220:223], v[2:5]
	v_mfma_f32_16x16x32_bf16 v[2:5], v[182:185], v[216:219], v[26:29]
	v_mfma_f32_16x16x32_bf16 v[26:29], v[186:189], v[220:223], v[2:5]
	v_mfma_f32_16x16x32_bf16 v[2:5], v[174:177], v[224:227], v[22:25]
	v_mfma_f32_16x16x32_bf16 v[22:25], v[178:181], v[228:231], v[2:5]
	v_mfma_f32_16x16x32_bf16 v[2:5], v[182:185], v[224:227], v[18:21]
	v_mfma_f32_16x16x32_bf16 v[18:21], v[186:189], v[228:231], v[2:5]
	s_barrier
	s_add_i32 s45, s45, 2
	s_add_u32 s0, s0, 0x100
	s_addc_u32 s1, s1, 0
	s_add_u32 s27, s27, 0x100
	s_addc_u32 s44, s44, 0
	s_cmp_gt_u32 s45, 13
	s_cbranch_scc0 .LBB0_768
	s_and_b64 vcc, exec, s[6:7]
	s_cbranch_vccz .LBB0_771
	s_barrier

;     __device__ __forceinline__ bool next(int i, Unit& u) const { u.seg = 0; u.ks = -1; u.nt = ntk; u.koff = 0; return unit(i, u); }
;     __device__ __forceinline__ bool next(int i, Unit& u) const { const int t = i / 3; u.seg = i - 3 * t; u.ks = -1; u.nt = ntk; u.koff = 0; return unit(t, u); }
;     __device__ __forceinline__ bool next(int i, Unit& u) const { if (i > 0 || c < 80 || c >= 144) return false; const int k = c - 80; u.pm = k & 1; u.pn = k >> 1; u.seg = 0; u.ks = -1; u.nt = DM / BK; u.koff = 0; return true; }
; #define PG8_STAGE(bufoff, gbase, voff) do { _Pragma("unroll") for (int _i = 0; _i < 2; ++_i) \
;         __builtin_amdgcn_global_load_lds((const unsigned*)((const char*)(gbase) + (voff)[_i]), (LAS unsigned*)(lds + (bufoff) + ldsw + _i * 8192), 16, 0, 0); } while (0)
; #define PG8_LDA(dst, b, h) do { _Pragma("unroll") for (int m = 0; m < 4; ++m) _Pragma("unroll") for (int k = 0; k < 2; ++k) dst[m][k] = *(const LAS bf16x8*)(lds + PG8_SA(b, h) + aoff + m * 2048 + k * 1024); } while (0)
; template <class Epi, class Sched, bool I8 = false>
; __device__ __forceinline__ void gemm_phase(LAS unsigned char* lds, const Gemm g, const Sched& S, const Epi& E) {
;     ...
;         const bool has_next = S.next(ui + 1, nxt);
;         const char* nA = has_next ? g.A + (size_t)nxt.seg * g.segA + (size_t)nxt.pm * tstepA + nxt.koff : cA; const char* nB = has_next ? g.Bt + (size_t)nxt.seg * g.segB + (size_t)nxt.pn * tstepB + nxt.koff : cB;
;         const int nt = cur.nt;
;         for (int t = 0; t < nt; t += 2) {
;             const bool last = (t == nt - 2);
;             const char* a1 = cA + (size_t)(t + 1) * kstep;
;             const char* a2 = last ? nA : cA + (size_t)(t + 2) * kstep; const char* b2 = last ? nB : cB + (size_t)(t + 2) * kstep;
;             const char* a3 = a2 + kstep; const char* b3 = b2 + kstep;
;             if (PG8_SP2) {
;             PG8_LDB(B0, 0, 0); PG8_LDB(B1, 0, 1); PG8_SCHED; PG8_LDA(At, 0, 0); PG8_STAGE(PG8_SA(1, 1), a1 + hstepA, voffA);
;             PG8_WAIT_V(8); PG8_WAIT_L(0); PG8_BAR; PG8_MMA(0, 0, At, B0); PG8_MMA(0, 1, At, B1); PG8_BAR; PG8_SCHED;
;             PG8_LDA(At, 0, 1); PG8_STAGE(PG8_SB(0, 0), b2, voffB); PG8_STAGE(PG8_SB(0, 1), b2 + hstepB, voffB); PG8_STAGE(PG8_SA(0, 0), a2, voffA);
;             PG8_WAIT_V(8); PG8_WAIT_L(0); PG8_BAR; PG8_MMA(1, 0, At, B0); PG8_MMA(1, 1, At, B1); PG8_BAR; PG8_SCHED;
.LBB0_901:
	s_add_u32 s6, s4, 0x100
	s_addc_u32 s7, s5, 0
	s_cmp_lg_u32 s29, 12
	s_cselect_b32 s8, s6, 0
	s_add_u32 s16, s40, s8
	s_addc_u32 s17, s41, 0
	s_add_i32 s30, 0, 0x10000
	s_add_u32 s8, s0, s8
	s_addc_u32 s9, s1, 0
	s_add_i32 s31, 0, 0x14000
	v_add_u32_e32 v158, s30, v144
	v_add_u32_e32 v174, s31, v144
	ds_read_b128 v[146:149], v158
	ds_read_b128 v[150:153], v158 offset:1024
	ds_read_b128 v[154:157], v158 offset:2048
	ds_read_b128 v[158:161], v158 offset:3072
	ds_read_b128 v[162:165], v174
	ds_read_b128 v[166:169], v174 offset:1024
	ds_read_b128 v[170:173], v174 offset:2048
	ds_read_b128 v[174:177], v174 offset:3072
	v_lshl_add_u64 v[202:203], v[138:139], 0, s[4:5]
	s_add_i32 m0, s2, 0xc000
	ds_read_b128 v[178:181], v145
	ds_read_b128 v[182:185], v145 offset:1024
	ds_read_b128 v[186:189], v145 offset:2048
	ds_read_b128 v[190:193], v145 offset:3072
	ds_read_b128 v[194:197], v145 offset:4096
	ds_read_b128 v[198:201], v145 offset:5120
	ds_read_b128 v[212:215], v145 offset:6144
	ds_read_b128 v[216:219], v145 offset:7168
	global_load_lds_dwordx4 v[202:203], off
	v_lshl_add_u64 v[202:203], v[140:141], 0, s[4:5]
	s_add_i32 m0, s2, 0xe000
	s_nop 0
	global_load_lds_dwordx4 v[202:203], off
	s_waitcnt vmcnt(8)
	s_waitcnt lgkmcnt(0)
	s_barrier
	s_waitcnt lgkmcnt(0)
	v_mfma_f32_16x16x32_bf16 v[126:129], v[146:149], v[178:181], v[126:129]
	v_mfma_f32_16x16x32_bf16 v[122:125], v[154:157], v[178:181], v[122:125]
	v_mfma_f32_16x16x32_bf16 v[118:121], v[146:149], v[186:189], v[118:121]
	v_mfma_f32_16x16x32_bf16 v[114:117], v[154:157], v[186:189], v[114:117]
	v_mfma_f32_16x16x32_bf16 v[110:113], v[146:149], v[194:197], v[110:113]
	v_mfma_f32_16x16x32_bf16 v[102:105], v[154:157], v[194:197], v[102:105]
	v_mfma_f32_16x16x32_bf16 v[94:97], v[146:149], v[212:215], v[94:97]
	v_mfma_f32_16x16x32_bf16 v[86:89], v[154:157], v[212:215], v[86:89]
	v_mfma_f32_16x16x32_bf16 v[126:129], v[150:153], v[182:185], v[126:129]
	v_mfma_f32_16x16x32_bf16 v[122:125], v[158:161], v[182:185], v[122:125]
	v_mfma_f32_16x16x32_bf16 v[118:121], v[150:153], v[190:193], v[118:121]
	v_mfma_f32_16x16x32_bf16 v[114:117], v[158:161], v[190:193], v[114:117]
	v_mfma_f32_16x16x32_bf16 v[110:113], v[150:153], v[198:201], v[110:113]
	v_mfma_f32_16x16x32_bf16 v[102:105], v[158:161], v[198:201], v[102:105]
	v_mfma_f32_16x16x32_bf16 v[94:97], v[150:153], v[216:219], v[94:97]
	v_mfma_f32_16x16x32_bf16 v[86:89], v[158:161], v[216:219], v[86:89]
	v_mfma_f32_16x16x32_bf16 v[106:109], v[162:165], v[178:181], v[106:109]
	v_mfma_f32_16x16x32_bf16 v[98:101], v[170:173], v[178:181], v[98:101]
	v_mfma_f32_16x16x32_bf16 v[90:93], v[162:165], v[186:189], v[90:93]
	v_mfma_f32_16x16x32_bf16 v[82:85], v[170:173], v[186:189], v[82:85]
	v_mfma_f32_16x16x32_bf16 v[78:81], v[162:165], v[194:197], v[78:81]
	v_mfma_f32_16x16x32_bf16 v[74:77], v[170:173], v[194:197], v[74:77]
	v_mfma_f32_16x16x32_bf16 v[70:73], v[162:165], v[212:215], v[70:73]
	v_mfma_f32_16x16x32_bf16 v[66:69], v[170:173], v[212:215], v[66:69]
	v_mfma_f32_16x16x32_bf16 v[106:109], v[166:169], v[182:185], v[106:109]
	v_mfma_f32_16x16x32_bf16 v[98:101], v[174:177], v[182:185], v[98:101]
	v_mfma_f32_16x16x32_bf16 v[90:93], v[166:169], v[190:193], v[90:93]
	v_mfma_f32_16x16x32_bf16 v[82:85], v[174:177], v[190:193], v[82:85]
	v_mfma_f32_16x16x32_bf16 v[78:81], v[166:169], v[198:201], v[78:81]
	v_mfma_f32_16x16x32_bf16 v[74:77], v[174:177], v[198:201], v[74:77]
	v_mfma_f32_16x16x32_bf16 v[70:73], v[166:169], v[216:219], v[70:73]
	v_mfma_f32_16x16x32_bf16 v[66:69], v[174:177], v[216:219], v[66:69]
	s_barrier
	s_add_i32 s4, s30, s21
	v_lshl_add_u64 v[202:203], s[8:9], 0, v[130:131]
	s_mov_b32 m0, s4
	ds_read_b128 v[178:181], v145 offset:16384
	ds_read_b128 v[182:185], v145 offset:17408
	ds_read_b128 v[186:189], v145 offset:18432
	ds_read_b128 v[190:193], v145 offset:19456
	ds_read_b128 v[194:197], v145 offset:20480
	ds_read_b128 v[198:201], v145 offset:21504
	ds_read_b128 v[212:215], v145 offset:22528
	ds_read_b128 v[216:219], v145 offset:23552
	global_load_lds_dwordx4 v[202:203], off
	s_add_i32 m0, s4, 0x2000
	s_add_u32 s4, s8, 0x10000
	v_lshl_add_u64 v[220:221], s[8:9], 0, v[132:133]
	s_addc_u32 s5, s9, 0
	s_add_i32 s30, s31, s21
	global_load_lds_dwordx4 v[220:221], off
	v_lshl_add_u64 v[222:223], s[4:5], 0, v[130:131]
	s_mov_b32 m0, s30
	v_lshl_add_u64 v[224:225], s[16:17], 0, v[134:135]
	global_load_lds_dwordx4 v[222:223], off
	v_lshl_add_u64 v[222:223], s[4:5], 0, v[132:133]
	s_add_i32 m0, s30, 0x2000
	s_nop 0
	global_load_lds_dwordx4 v[222:223], off
	v_lshl_add_u64 v[222:223], s[16:17], 0, v[136:137]
	s_mov_b32 m0, s2
	s_nop 0
	global_load_lds_dwordx4 v[222:223], off
	s_mov_b32 m0, s3
	s_nop 0
	global_load_lds_dwordx4 v[224:225], off
	s_waitcnt vmcnt(8)
	s_waitcnt lgkmcnt(0)
	s_barrier
; #define PG8_STAGE(bufoff, gbase, voff) do { _Pragma("unroll") for (int _i = 0; _i < 2; ++_i) \
;         __builtin_amdgcn_global_load_lds((const unsigned*)((const char*)(gbase) + (voff)[_i]), (LAS unsigned*)(lds + (bufoff) + ldsw + _i * 8192), 16, 0, 0); } while (0)
; #define PG8_LDA(dst, b, h) do { _Pragma("unroll") for (int m = 0; m < 4; ++m) _Pragma("unroll") for (int k = 0; k < 2; ++k) dst[m][k] = *(const LAS bf16x8*)(lds + PG8_SA(b, h) + aoff + m * 2048 + k * 1024); } while (0)
; #define PG8_LDB(dst, b, h) do { _Pragma("unroll") for (int n = 0; n < 2; ++n) _Pragma("unroll") for (int k = 0; k < 2; ++k) dst[n][k] = *(const LAS bf16x8*)(lds + PG8_SB(b, h) + boff + n * 2048 + k * 1024); } while (0)
; #define PG8_MMA(ai, bj, At, Bt) do { __builtin_amdgcn_s_setprio(1); _Pragma("unroll") for (int m = 0; m < 4; ++m) _Pragma("unroll") for (int n = 0; n < 2; ++n) _Pragma("unroll") for (int k = 0; k < 2; ++k) \
;         acc[ai][bj][m][n] = mma16<I8>(Bt[n][k], At[m][k], acc[ai][bj][m][n]); __builtin_amdgcn_s_setprio(0); } while (0)
; #define PG8_WAIT_V(n) asm volatile("s_waitcnt vmcnt(" #n ")" ::: "memory")
; #define PG8_WAIT_L(n) asm volatile("s_waitcnt lgkmcnt(" #n ")" ::: "memory")
; #define PG8_BAR __builtin_amdgcn_s_barrier()
; #define PG8_SCHED __builtin_amdgcn_sched_barrier(0)
; template <class Epi, class Sched, bool I8 = false>
; __device__ __forceinline__ void gemm_phase(LAS unsigned char* lds, const Gemm g, const Sched& S, const Epi& E) {
;     ...
;             PG8_WAIT_V(8); PG8_WAIT_L(0); PG8_BAR; PG8_MMA(1, 0, At, B0); PG8_MMA(1, 1, At, B1); PG8_BAR; PG8_SCHED;
;             PG8_LDB(B0, 1, 0); PG8_LDB(B1, 1, 1); PG8_SCHED; PG8_LDA(At, 1, 0); PG8_STAGE(PG8_SA(0, 1), a2 + hstepA, voffA);
;             PG8_WAIT_V(8); PG8_WAIT_L(0); PG8_BAR; PG8_MMA(0, 0, At, B0); PG8_MMA(0, 1, At, B1); PG8_BAR; PG8_SCHED;
	s_waitcnt lgkmcnt(0)
	v_mfma_f32_16x16x32_bf16 v[62:65], v[146:149], v[178:181], v[62:65]
	v_mfma_f32_16x16x32_bf16 v[58:61], v[154:157], v[178:181], v[58:61]
	v_mfma_f32_16x16x32_bf16 v[54:57], v[146:149], v[186:189], v[54:57]
	v_mfma_f32_16x16x32_bf16 v[50:53], v[154:157], v[186:189], v[50:53]
	v_mfma_f32_16x16x32_bf16 v[42:45], v[146:149], v[194:197], v[42:45]
	v_mfma_f32_16x16x32_bf16 v[34:37], v[154:157], v[194:197], v[34:37]
	v_mfma_f32_16x16x32_bf16 v[26:29], v[146:149], v[212:215], v[26:29]
	v_mfma_f32_16x16x32_bf16 v[18:21], v[154:157], v[212:215], v[18:21]
	v_mfma_f32_16x16x32_bf16 v[62:65], v[150:153], v[182:185], v[62:65]
	v_mfma_f32_16x16x32_bf16 v[58:61], v[158:161], v[182:185], v[58:61]
	v_mfma_f32_16x16x32_bf16 v[54:57], v[150:153], v[190:193], v[54:57]
	v_mfma_f32_16x16x32_bf16 v[50:53], v[158:161], v[190:193], v[50:53]
	v_mfma_f32_16x16x32_bf16 v[42:45], v[150:153], v[198:201], v[42:45]
	v_mfma_f32_16x16x32_bf16 v[34:37], v[158:161], v[198:201], v[34:37]
	v_mfma_f32_16x16x32_bf16 v[26:29], v[150:153], v[216:219], v[26:29]
	v_mfma_f32_16x16x32_bf16 v[18:21], v[158:161], v[216:219], v[18:21]
	v_mfma_f32_16x16x32_bf16 v[46:49], v[162:165], v[178:181], v[46:49]
	v_mfma_f32_16x16x32_bf16 v[38:41], v[170:173], v[178:181], v[38:41]
	v_mfma_f32_16x16x32_bf16 v[30:33], v[162:165], v[186:189], v[30:33]
	v_mfma_f32_16x16x32_bf16 v[22:25], v[170:173], v[186:189], v[22:25]
	v_mfma_f32_16x16x32_bf16 v[14:17], v[162:165], v[194:197], v[14:17]
	v_mfma_f32_16x16x32_bf16 v[10:13], v[170:173], v[194:197], v[10:13]
	v_mfma_f32_16x16x32_bf16 v[6:9], v[162:165], v[212:215], v[6:9]
	v_mfma_f32_16x16x32_bf16 v[2:5], v[170:173], v[212:215], v[2:5]
	v_mfma_f32_16x16x32_bf16 v[46:49], v[166:169], v[182:185], v[46:49]
	v_mfma_f32_16x16x32_bf16 v[38:41], v[174:177], v[182:185], v[38:41]
	v_mfma_f32_16x16x32_bf16 v[30:33], v[166:169], v[190:193], v[30:33]
	v_mfma_f32_16x16x32_bf16 v[22:25], v[174:177], v[190:193], v[22:25]
	v_mfma_f32_16x16x32_bf16 v[14:17], v[166:169], v[198:201], v[14:17]
	v_mfma_f32_16x16x32_bf16 v[10:13], v[174:177], v[198:201], v[10:13]
	v_mfma_f32_16x16x32_bf16 v[6:9], v[166:169], v[216:219], v[6:9]
	v_mfma_f32_16x16x32_bf16 v[2:5], v[174:177], v[216:219], v[2:5]
	s_barrier
	s_add_i32 s30, 0, 0x18000
	s_add_i32 s31, 0, 0x1c000
	v_add_u32_e32 v158, s30, v144
	v_add_u32_e32 v174, s31, v144
	ds_read_b128 v[146:149], v158
	ds_read_b128 v[150:153], v158 offset:1024
	ds_read_b128 v[154:157], v158 offset:2048
	ds_read_b128 v[158:161], v158 offset:3072
	ds_read_b128 v[162:165], v174
	ds_read_b128 v[166:169], v174 offset:1024
	ds_read_b128 v[170:173], v174 offset:2048
	ds_read_b128 v[174:177], v174 offset:3072
	s_add_u32 s4, s16, 0x40000
	s_addc_u32 s5, s17, 0
	s_mov_b32 m0, s22
	v_lshl_add_u64 v[226:227], s[4:5], 0, v[136:137]
	ds_read_b128 v[178:181], v145 offset:32768
	ds_read_b128 v[182:185], v145 offset:33792
	ds_read_b128 v[186:189], v145 offset:34816
	ds_read_b128 v[190:193], v145 offset:35840
	ds_read_b128 v[194:197], v145 offset:36864
	ds_read_b128 v[198:201], v145 offset:37888
	ds_read_b128 v[212:215], v145 offset:38912
	ds_read_b128 v[216:219], v145 offset:39936
	global_load_lds_dwordx4 v[226:227], off
	v_lshl_add_u64 v[226:227], s[4:5], 0, v[134:135]
	s_mov_b32 m0, s23
	s_nop 0
	global_load_lds_dwordx4 v[226:227], off
	s_waitcnt vmcnt(8)
	s_waitcnt lgkmcnt(0)
	s_barrier
	s_waitcnt lgkmcnt(0)
	v_mfma_f32_16x16x32_bf16 v[126:129], v[146:149], v[178:181], v[126:129]
	v_mfma_f32_16x16x32_bf16 v[122:125], v[154:157], v[178:181], v[122:125]
	v_mfma_f32_16x16x32_bf16 v[118:121], v[146:149], v[186:189], v[118:121]
	v_mfma_f32_16x16x32_bf16 v[114:117], v[154:157], v[186:189], v[114:117]
	v_mfma_f32_16x16x32_bf16 v[110:113], v[146:149], v[194:197], v[110:113]
	v_mfma_f32_16x16x32_bf16 v[102:105], v[154:157], v[194:197], v[102:105]
	v_mfma_f32_16x16x32_bf16 v[94:97], v[146:149], v[212:215], v[94:97]
	v_mfma_f32_16x16x32_bf16 v[86:89], v[154:157], v[212:215], v[86:89]
	v_mfma_f32_16x16x32_bf16 v[126:129], v[150:153], v[182:185], v[126:129]
	v_mfma_f32_16x16x32_bf16 v[122:125], v[158:161], v[182:185], v[122:125]
	v_mfma_f32_16x16x32_bf16 v[118:121], v[150:153], v[190:193], v[118:121]
	v_mfma_f32_16x16x32_bf16 v[114:117], v[158:161], v[190:193], v[114:117]
	v_mfma_f32_16x16x32_bf16 v[110:113], v[150:153], v[198:201], v[110:113]
	v_mfma_f32_16x16x32_bf16 v[102:105], v[158:161], v[198:201], v[102:105]
	v_mfma_f32_16x16x32_bf16 v[94:97], v[150:153], v[216:219], v[94:97]
	v_mfma_f32_16x16x32_bf16 v[86:89], v[158:161], v[216:219], v[86:89]
	v_mfma_f32_16x16x32_bf16 v[106:109], v[162:165], v[178:181], v[106:109]
	v_mfma_f32_16x16x32_bf16 v[98:101], v[170:173], v[178:181], v[98:101]
	v_mfma_f32_16x16x32_bf16 v[90:93], v[162:165], v[186:189], v[90:93]
	v_mfma_f32_16x16x32_bf16 v[82:85], v[170:173], v[186:189], v[82:85]
	v_mfma_f32_16x16x32_bf16 v[78:81], v[162:165], v[194:197], v[78:81]
	v_mfma_f32_16x16x32_bf16 v[74:77], v[170:173], v[194:197], v[74:77]
	v_mfma_f32_16x16x32_bf16 v[70:73], v[162:165], v[212:215], v[70:73]
	v_mfma_f32_16x16x32_bf16 v[66:69], v[170:173], v[212:215], v[66:69]
	v_mfma_f32_16x16x32_bf16 v[106:109], v[166:169], v[182:185], v[106:109]
	v_mfma_f32_16x16x32_bf16 v[98:101], v[174:177], v[182:185], v[98:101]
	v_mfma_f32_16x16x32_bf16 v[90:93], v[166:169], v[190:193], v[90:93]
	v_mfma_f32_16x16x32_bf16 v[82:85], v[174:177], v[190:193], v[82:85]
	v_mfma_f32_16x16x32_bf16 v[78:81], v[166:169], v[198:201], v[78:81]
	v_mfma_f32_16x16x32_bf16 v[74:77], v[174:177], v[198:201], v[74:77]
	v_mfma_f32_16x16x32_bf16 v[70:73], v[166:169], v[216:219], v[70:73]
	v_mfma_f32_16x16x32_bf16 v[66:69], v[174:177], v[216:219], v[66:69]
	s_barrier
; #define PG8_STAGE(bufoff, gbase, voff) do { _Pragma("unroll") for (int _i = 0; _i < 2; ++_i) \
;         __builtin_amdgcn_global_load_lds((const unsigned*)((const char*)(gbase) + (voff)[_i]), (LAS unsigned*)(lds + (bufoff) + ldsw + _i * 8192), 16, 0, 0); } while (0)
; #define PG8_LDA(dst, b, h) do { _Pragma("unroll") for (int m = 0; m < 4; ++m) _Pragma("unroll") for (int k = 0; k < 2; ++k) dst[m][k] = *(const LAS bf16x8*)(lds + PG8_SA(b, h) + aoff + m * 2048 + k * 1024); } while (0)
; #define PG8_MMA(ai, bj, At, Bt) do { __builtin_amdgcn_s_setprio(1); _Pragma("unroll") for (int m = 0; m < 4; ++m) _Pragma("unroll") for (int n = 0; n < 2; ++n) _Pragma("unroll") for (int k = 0; k < 2; ++k) \
;         acc[ai][bj][m][n] = mma16<I8>(Bt[n][k], At[m][k], acc[ai][bj][m][n]); __builtin_amdgcn_s_setprio(0); } while (0)
; #define PG8_WAIT_V(n) asm volatile("s_waitcnt vmcnt(" #n ")" ::: "memory")
; #define PG8_WAIT_L(n) asm volatile("s_waitcnt lgkmcnt(" #n ")" ::: "memory")
; #define PG8_BAR __builtin_amdgcn_s_barrier()
; #define PG8_SCHED __builtin_amdgcn_sched_barrier(0)
; template <class Epi, class Sched, bool I8 = false>
; __device__ __forceinline__ void gemm_phase(LAS unsigned char* lds, const Gemm g, const Sched& S, const Epi& E) {
;     ...
;             PG8_LDA(At, 1, 1); PG8_STAGE(PG8_SB(1, 0), b3, voffB); PG8_STAGE(PG8_SB(1, 1), b3 + hstepB, voffB); PG8_STAGE(PG8_SA(1, 0), a3, voffA);
;             PG8_WAIT_V(8); PG8_WAIT_L(0); PG8_BAR; PG8_MMA(1, 0, At, B0); PG8_MMA(1, 1, At, B1); PG8_BAR; PG8_SCHED;
	s_add_i32 s4, s30, s21
	v_lshl_add_u64 v[202:203], v[202:203], 0, s[12:13]
	s_mov_b32 m0, s4
	ds_read_b128 v[178:181], v145 offset:49152
	ds_read_b128 v[182:185], v145 offset:50176
	ds_read_b128 v[186:189], v145 offset:51200
	ds_read_b128 v[190:193], v145 offset:52224
	ds_read_b128 v[194:197], v145 offset:53248
	ds_read_b128 v[198:201], v145 offset:54272
	ds_read_b128 v[212:215], v145 offset:55296
	ds_read_b128 v[216:219], v145 offset:56320
	global_load_lds_dwordx4 v[202:203], off
	s_add_i32 m0, s4, 0x2000
	s_add_u32 s4, s8, 0x10080
	v_lshl_add_u64 v[202:203], v[220:221], 0, s[12:13]
	s_addc_u32 s5, s9, 0
	s_add_i32 s8, s31, s21
	global_load_lds_dwordx4 v[202:203], off
	v_lshl_add_u64 v[202:203], s[4:5], 0, v[130:131]
	s_mov_b32 m0, s8
	s_nop 0
	global_load_lds_dwordx4 v[202:203], off
	v_lshl_add_u64 v[202:203], s[4:5], 0, v[132:133]
	s_add_i32 m0, s8, 0x2000
	s_nop 0
	global_load_lds_dwordx4 v[202:203], off
	v_lshl_add_u64 v[202:203], v[222:223], 0, s[12:13]
	s_mov_b32 m0, s26
	s_nop 0
	global_load_lds_dwordx4 v[202:203], off
	v_lshl_add_u64 v[202:203], v[224:225], 0, s[12:13]
	s_mov_b32 m0, s27
	s_nop 0
	global_load_lds_dwordx4 v[202:203], off
	s_waitcnt vmcnt(8)
	s_waitcnt lgkmcnt(0)
	s_barrier
	s_waitcnt lgkmcnt(0)
	v_mfma_f32_16x16x32_bf16 v[62:65], v[146:149], v[178:181], v[62:65]
	v_mfma_f32_16x16x32_bf16 v[58:61], v[154:157], v[178:181], v[58:61]
	v_mfma_f32_16x16x32_bf16 v[54:57], v[146:149], v[186:189], v[54:57]
	v_mfma_f32_16x16x32_bf16 v[50:53], v[154:157], v[186:189], v[50:53]
	v_mfma_f32_16x16x32_bf16 v[42:45], v[146:149], v[194:197], v[42:45]
	v_mfma_f32_16x16x32_bf16 v[34:37], v[154:157], v[194:197], v[34:37]
	v_mfma_f32_16x16x32_bf16 v[26:29], v[146:149], v[212:215], v[26:29]
	v_mfma_f32_16x16x32_bf16 v[18:21], v[154:157], v[212:215], v[18:21]
	v_mfma_f32_16x16x32_bf16 v[62:65], v[150:153], v[182:185], v[62:65]
	v_mfma_f32_16x16x32_bf16 v[58:61], v[158:161], v[182:185], v[58:61]
	v_mfma_f32_16x16x32_bf16 v[54:57], v[150:153], v[190:193], v[54:57]
	v_mfma_f32_16x16x32_bf16 v[50:53], v[158:161], v[190:193], v[50:53]
	v_mfma_f32_16x16x32_bf16 v[42:45], v[150:153], v[198:201], v[42:45]
	v_mfma_f32_16x16x32_bf16 v[34:37], v[158:161], v[198:201], v[34:37]
	v_mfma_f32_16x16x32_bf16 v[26:29], v[150:153], v[216:219], v[26:29]
	v_mfma_f32_16x16x32_bf16 v[18:21], v[158:161], v[216:219], v[18:21]
	v_mfma_f32_16x16x32_bf16 v[46:49], v[162:165], v[178:181], v[46:49]
	v_mfma_f32_16x16x32_bf16 v[38:41], v[170:173], v[178:181], v[38:41]
	v_mfma_f32_16x16x32_bf16 v[30:33], v[162:165], v[186:189], v[30:33]
	v_mfma_f32_16x16x32_bf16 v[22:25], v[170:173], v[186:189], v[22:25]
	v_mfma_f32_16x16x32_bf16 v[14:17], v[162:165], v[194:197], v[14:17]
	v_mfma_f32_16x16x32_bf16 v[10:13], v[170:173], v[194:197], v[10:13]
	v_mfma_f32_16x16x32_bf16 v[6:9], v[162:165], v[212:215], v[6:9]
	v_mfma_f32_16x16x32_bf16 v[2:5], v[170:173], v[212:215], v[2:5]
	v_mfma_f32_16x16x32_bf16 v[46:49], v[166:169], v[182:185], v[46:49]
	v_mfma_f32_16x16x32_bf16 v[38:41], v[174:177], v[182:185], v[38:41]
	v_mfma_f32_16x16x32_bf16 v[30:33], v[166:169], v[190:193], v[30:33]
	v_mfma_f32_16x16x32_bf16 v[22:25], v[174:177], v[190:193], v[22:25]
	v_mfma_f32_16x16x32_bf16 v[14:17], v[166:169], v[198:201], v[14:17]
	v_mfma_f32_16x16x32_bf16 v[10:13], v[174:177], v[198:201], v[10:13]
	v_mfma_f32_16x16x32_bf16 v[6:9], v[166:169], v[216:219], v[6:9]
	v_mfma_f32_16x16x32_bf16 v[2:5], v[174:177], v[216:219], v[2:5]
	s_barrier
	s_add_i32 s29, s29, 2
	s_cmp_gt_u32 s29, 13
	s_mov_b64 s[4:5], s[6:7]
	s_cbranch_scc0 .LBB0_901
	s_cmpk_lt_u32 s14, 0x100
	s_cbranch_scc0 .LBB0_904
	s_barrier

;     __device__ __forceinline__ bool next(int i, Unit& u) const { u.seg = 0; u.ks = -1; u.nt = ntk; u.koff = 0; return unit(i, u); }
;     __device__ __forceinline__ bool next(int i, Unit& u) const { const int t = i / 3; u.seg = i - 3 * t; u.ks = -1; u.nt = ntk; u.koff = 0; return unit(t, u); }
;     __device__ __forceinline__ bool next(int i, Unit& u) const { if (i > 0 || c < 80 || c >= 144) return false; const int k = c - 80; u.pm = k & 1; u.pn = k >> 1; u.seg = 0; u.ks = -1; u.nt = DM / BK; u.koff = 0; return true; }
; #define PG8_STAGE(bufoff, gbase, voff) do { _Pragma("unroll") for (int _i = 0; _i < 2; ++_i) \
;         __builtin_amdgcn_global_load_lds((const unsigned*)((const char*)(gbase) + (voff)[_i]), (LAS unsigned*)(lds + (bufoff) + ldsw + _i * 8192), 16, 0, 0); } while (0)
; #define PG8_LDA(dst, b, h) do { _Pragma("unroll") for (int m = 0; m < 4; ++m) _Pragma("unroll") for (int k = 0; k < 2; ++k) dst[m][k] = *(const LAS bf16x8*)(lds + PG8_SA(b, h) + aoff + m * 2048 + k * 1024); } while (0)
; template <class Epi, class Sched, bool I8 = false>
; __device__ __forceinline__ void gemm_phase(LAS unsigned char* lds, const Gemm g, const Sched& S, const Epi& E) {
;     ...
;         const bool has_next = S.next(ui + 1, nxt);
;         const char* nA = has_next ? g.A + (size_t)nxt.seg * g.segA + (size_t)nxt.pm * tstepA + nxt.koff : cA; const char* nB = has_next ? g.Bt + (size_t)nxt.seg * g.segB + (size_t)nxt.pn * tstepB + nxt.koff : cB;
;         const int nt = cur.nt;
;         for (int t = 0; t < nt; t += 2) {
;             const bool last = (t == nt - 2);
;             const char* a1 = cA + (size_t)(t + 1) * kstep;
;             const char* a2 = last ? nA : cA + (size_t)(t + 2) * kstep; const char* b2 = last ? nB : cB + (size_t)(t + 2) * kstep;
;             const char* a3 = a2 + kstep; const char* b3 = b2 + kstep;
;             if (PG8_SP2) {
;             PG8_LDB(B0, 0, 0); PG8_LDB(B1, 0, 1); PG8_SCHED; PG8_LDA(At, 0, 0); PG8_STAGE(PG8_SA(1, 1), a1 + hstepA, voffA);
;             PG8_WAIT_V(8); PG8_WAIT_L(0); PG8_BAR; PG8_MMA(0, 0, At, B0); PG8_MMA(0, 1, At, B1); PG8_BAR; PG8_SCHED;
;             PG8_LDA(At, 0, 1); PG8_STAGE(PG8_SB(0, 0), b2, voffB); PG8_STAGE(PG8_SB(0, 1), b2 + hstepB, voffB); PG8_STAGE(PG8_SA(0, 0), a2, voffA);
;             PG8_WAIT_V(8); PG8_WAIT_L(0); PG8_BAR; PG8_MMA(1, 0, At, B0); PG8_MMA(1, 1, At, B1); PG8_BAR; PG8_SCHED;
.LBB0_1153:
	s_add_i32 s63, s58, 2
	s_add_u32 s42, s40, 0xfff80080
	s_addc_u32 s43, s41, -1
	s_add_i32 s82, 0, 0x10000
	s_cmp_eq_u32 s47, s58
	s_cselect_b32 s59, s9, s43
	s_cselect_b32 s58, s45, s42
	v_add_u32_e32 v130, s82, v143
	s_cselect_b32 s43, s17, s62
	s_cselect_b32 s42, s46, s49
	s_add_i32 s84, 0, 0x14000
	ds_read_b128 v[150:153], v130
	ds_read_b128 v[154:157], v130 offset:1024
	ds_read_b128 v[158:161], v130 offset:2048
	ds_read_b128 v[162:165], v130 offset:3072
	v_add_u32_e32 v130, s84, v143
	ds_read_b128 v[166:169], v130
	ds_read_b128 v[170:173], v130 offset:1024
	ds_read_b128 v[174:177], v130 offset:2048
	ds_read_b128 v[178:181], v130 offset:3072
	v_lshl_add_u64 v[202:203], s[40:41], 0, v[146:147]
	s_add_i32 m0, s21, 0xc000
	ds_read_b128 v[182:185], v145
	ds_read_b128 v[186:189], v145 offset:1024
	ds_read_b128 v[190:193], v145 offset:2048
	ds_read_b128 v[194:197], v145 offset:3072
	ds_read_b128 v[198:201], v145 offset:4096
	ds_read_b128 v[212:215], v145 offset:5120
	ds_read_b128 v[216:219], v145 offset:6144
	ds_read_b128 v[220:223], v145 offset:7168
	global_load_lds_dwordx4 v[202:203], off
	v_lshl_add_u64 v[202:203], s[40:41], 0, v[148:149]
	s_add_i32 m0, s21, 0xe000
	s_nop 0
	global_load_lds_dwordx4 v[202:203], off
	s_waitcnt vmcnt(8)
	s_waitcnt lgkmcnt(0)
	s_barrier
	s_waitcnt lgkmcnt(0)
	v_mfma_f32_16x16x32_bf16 v[126:129], v[150:153], v[182:185], v[126:129]
	v_mfma_f32_16x16x32_bf16 v[122:125], v[158:161], v[182:185], v[122:125]
	v_mfma_f32_16x16x32_bf16 v[110:113], v[150:153], v[190:193], v[110:113]
	v_mfma_f32_16x16x32_bf16 v[106:109], v[158:161], v[190:193], v[106:109]
	v_mfma_f32_16x16x32_bf16 v[94:97], v[150:153], v[198:201], v[94:97]
	v_mfma_f32_16x16x32_bf16 v[90:93], v[158:161], v[198:201], v[90:93]
	v_mfma_f32_16x16x32_bf16 v[78:81], v[150:153], v[216:219], v[78:81]
	v_mfma_f32_16x16x32_bf16 v[74:77], v[158:161], v[216:219], v[74:77]
	v_mfma_f32_16x16x32_bf16 v[126:129], v[154:157], v[186:189], v[126:129]
	v_mfma_f32_16x16x32_bf16 v[122:125], v[162:165], v[186:189], v[122:125]
	v_mfma_f32_16x16x32_bf16 v[110:113], v[154:157], v[194:197], v[110:113]
	v_mfma_f32_16x16x32_bf16 v[106:109], v[162:165], v[194:197], v[106:109]
	v_mfma_f32_16x16x32_bf16 v[94:97], v[154:157], v[212:215], v[94:97]
	v_mfma_f32_16x16x32_bf16 v[90:93], v[162:165], v[212:215], v[90:93]
	v_mfma_f32_16x16x32_bf16 v[78:81], v[154:157], v[220:223], v[78:81]
	v_mfma_f32_16x16x32_bf16 v[74:77], v[162:165], v[220:223], v[74:77]
	v_mfma_f32_16x16x32_bf16 v[118:121], v[166:169], v[182:185], v[118:121]
	v_mfma_f32_16x16x32_bf16 v[114:117], v[174:177], v[182:185], v[114:117]
	v_mfma_f32_16x16x32_bf16 v[102:105], v[166:169], v[190:193], v[102:105]
	v_mfma_f32_16x16x32_bf16 v[98:101], v[174:177], v[190:193], v[98:101]
	v_mfma_f32_16x16x32_bf16 v[86:89], v[166:169], v[198:201], v[86:89]
	v_mfma_f32_16x16x32_bf16 v[82:85], v[174:177], v[198:201], v[82:85]
	v_mfma_f32_16x16x32_bf16 v[70:73], v[166:169], v[216:219], v[70:73]
	v_mfma_f32_16x16x32_bf16 v[66:69], v[174:177], v[216:219], v[66:69]
	v_mfma_f32_16x16x32_bf16 v[118:121], v[170:173], v[186:189], v[118:121]
	v_mfma_f32_16x16x32_bf16 v[114:117], v[178:181], v[186:189], v[114:117]
	v_mfma_f32_16x16x32_bf16 v[102:105], v[170:173], v[194:197], v[102:105]
	v_mfma_f32_16x16x32_bf16 v[98:101], v[178:181], v[194:197], v[98:101]
	v_mfma_f32_16x16x32_bf16 v[86:89], v[170:173], v[212:215], v[86:89]
	v_mfma_f32_16x16x32_bf16 v[82:85], v[178:181], v[212:215], v[82:85]
	v_mfma_f32_16x16x32_bf16 v[70:73], v[170:173], v[220:223], v[70:73]
	v_mfma_f32_16x16x32_bf16 v[66:69], v[178:181], v[220:223], v[66:69]
	s_barrier
	s_add_i32 s82, s82, s14
	v_lshl_add_u64 v[202:203], s[42:43], 0, v[136:137]
	s_mov_b32 m0, s82
	ds_read_b128 v[182:185], v145 offset:16384
	ds_read_b128 v[186:189], v145 offset:17408
	ds_read_b128 v[190:193], v145 offset:18432
	ds_read_b128 v[194:197], v145 offset:19456
	ds_read_b128 v[198:201], v145 offset:20480
	ds_read_b128 v[212:215], v145 offset:21504
	ds_read_b128 v[216:219], v145 offset:22528
	ds_read_b128 v[220:223], v145 offset:23552
	global_load_lds_dwordx4 v[202:203], off
	s_add_i32 m0, s82, 0x2000
	s_add_u32 s82, s42, 0x20000
	v_lshl_add_u64 v[224:225], s[42:43], 0, v[132:133]
	s_addc_u32 s83, s43, 0
	s_add_i32 s84, s84, s14
	global_load_lds_dwordx4 v[224:225], off
	v_lshl_add_u64 v[226:227], s[82:83], 0, v[136:137]
	s_mov_b32 m0, s84
	v_lshl_add_u64 v[228:229], s[58:59], 0, v[134:135]
	global_load_lds_dwordx4 v[226:227], off
	v_lshl_add_u64 v[226:227], s[82:83], 0, v[132:133]
	s_add_i32 m0, s84, 0x2000
	s_nop 0
	global_load_lds_dwordx4 v[226:227], off
	v_lshl_add_u64 v[226:227], s[58:59], 0, v[138:139]
	s_mov_b32 m0, s21
	s_nop 0
	global_load_lds_dwordx4 v[226:227], off
	s_mov_b32 m0, s22
	s_nop 0
	global_load_lds_dwordx4 v[228:229], off
	s_waitcnt vmcnt(8)
	s_waitcnt lgkmcnt(0)
	s_barrier
; #define PG8_STAGE(bufoff, gbase, voff) do { _Pragma("unroll") for (int _i = 0; _i < 2; ++_i) \
;         __builtin_amdgcn_global_load_lds((const unsigned*)((const char*)(gbase) + (voff)[_i]), (LAS unsigned*)(lds + (bufoff) + ldsw + _i * 8192), 16, 0, 0); } while (0)
; #define PG8_LDA(dst, b, h) do { _Pragma("unroll") for (int m = 0; m < 4; ++m) _Pragma("unroll") for (int k = 0; k < 2; ++k) dst[m][k] = *(const LAS bf16x8*)(lds + PG8_SA(b, h) + aoff + m * 2048 + k * 1024); } while (0)
; #define PG8_LDB(dst, b, h) do { _Pragma("unroll") for (int n = 0; n < 2; ++n) _Pragma("unroll") for (int k = 0; k < 2; ++k) dst[n][k] = *(const LAS bf16x8*)(lds + PG8_SB(b, h) + boff + n * 2048 + k * 1024); } while (0)
; #define PG8_MMA(ai, bj, At, Bt) do { __builtin_amdgcn_s_setprio(1); _Pragma("unroll") for (int m = 0; m < 4; ++m) _Pragma("unroll") for (int n = 0; n < 2; ++n) _Pragma("unroll") for (int k = 0; k < 2; ++k) \
;         acc[ai][bj][m][n] = mma16<I8>(Bt[n][k], At[m][k], acc[ai][bj][m][n]); __builtin_amdgcn_s_setprio(0); } while (0)
; #define PG8_WAIT_V(n) asm volatile("s_waitcnt vmcnt(" #n ")" ::: "memory")
; #define PG8_WAIT_L(n) asm volatile("s_waitcnt lgkmcnt(" #n ")" ::: "memory")
; #define PG8_BAR __builtin_amdgcn_s_barrier()
; #define PG8_SCHED __builtin_amdgcn_sched_barrier(0)
; template <class Epi, class Sched, bool I8 = false>
; __device__ __forceinline__ void gemm_phase(LAS unsigned char* lds, const Gemm g, const Sched& S, const Epi& E) {
;     ...
;             PG8_WAIT_V(8); PG8_WAIT_L(0); PG8_BAR; PG8_MMA(1, 0, At, B0); PG8_MMA(1, 1, At, B1); PG8_BAR; PG8_SCHED;
;             PG8_LDB(B0, 1, 0); PG8_LDB(B1, 1, 1); PG8_SCHED; PG8_LDA(At, 1, 0); PG8_STAGE(PG8_SA(0, 1), a2 + hstepA, voffA);
;             PG8_WAIT_V(8); PG8_WAIT_L(0); PG8_BAR; PG8_MMA(0, 0, At, B0); PG8_MMA(0, 1, At, B1); PG8_BAR; PG8_SCHED;
	s_waitcnt lgkmcnt(0)
	v_mfma_f32_16x16x32_bf16 v[62:65], v[150:153], v[182:185], v[62:65]
	v_mfma_f32_16x16x32_bf16 v[58:61], v[158:161], v[182:185], v[58:61]
	v_mfma_f32_16x16x32_bf16 v[46:49], v[150:153], v[190:193], v[46:49]
	v_mfma_f32_16x16x32_bf16 v[42:45], v[158:161], v[190:193], v[42:45]
	v_mfma_f32_16x16x32_bf16 v[30:33], v[150:153], v[198:201], v[30:33]
	v_mfma_f32_16x16x32_bf16 v[26:29], v[158:161], v[198:201], v[26:29]
	v_mfma_f32_16x16x32_bf16 v[14:17], v[150:153], v[216:219], v[14:17]
	v_mfma_f32_16x16x32_bf16 v[10:13], v[158:161], v[216:219], v[10:13]
	v_mfma_f32_16x16x32_bf16 v[62:65], v[154:157], v[186:189], v[62:65]
	v_mfma_f32_16x16x32_bf16 v[58:61], v[162:165], v[186:189], v[58:61]
	v_mfma_f32_16x16x32_bf16 v[46:49], v[154:157], v[194:197], v[46:49]
	v_mfma_f32_16x16x32_bf16 v[42:45], v[162:165], v[194:197], v[42:45]
	v_mfma_f32_16x16x32_bf16 v[30:33], v[154:157], v[212:215], v[30:33]
	v_mfma_f32_16x16x32_bf16 v[26:29], v[162:165], v[212:215], v[26:29]
	v_mfma_f32_16x16x32_bf16 v[14:17], v[154:157], v[220:223], v[14:17]
	v_mfma_f32_16x16x32_bf16 v[10:13], v[162:165], v[220:223], v[10:13]
	v_mfma_f32_16x16x32_bf16 v[54:57], v[166:169], v[182:185], v[54:57]
	v_mfma_f32_16x16x32_bf16 v[50:53], v[174:177], v[182:185], v[50:53]
	v_mfma_f32_16x16x32_bf16 v[38:41], v[166:169], v[190:193], v[38:41]
	v_mfma_f32_16x16x32_bf16 v[34:37], v[174:177], v[190:193], v[34:37]
	v_mfma_f32_16x16x32_bf16 v[22:25], v[166:169], v[198:201], v[22:25]
	v_mfma_f32_16x16x32_bf16 v[18:21], v[174:177], v[198:201], v[18:21]
	v_mfma_f32_16x16x32_bf16 v[6:9], v[166:169], v[216:219], v[6:9]
	v_mfma_f32_16x16x32_bf16 v[2:5], v[174:177], v[216:219], v[2:5]
	v_mfma_f32_16x16x32_bf16 v[54:57], v[170:173], v[186:189], v[54:57]
	v_mfma_f32_16x16x32_bf16 v[50:53], v[178:181], v[186:189], v[50:53]
	v_mfma_f32_16x16x32_bf16 v[38:41], v[170:173], v[194:197], v[38:41]
	v_mfma_f32_16x16x32_bf16 v[34:37], v[178:181], v[194:197], v[34:37]
	v_mfma_f32_16x16x32_bf16 v[22:25], v[170:173], v[212:215], v[22:25]
	v_mfma_f32_16x16x32_bf16 v[18:21], v[178:181], v[212:215], v[18:21]
	v_mfma_f32_16x16x32_bf16 v[6:9], v[170:173], v[220:223], v[6:9]
	v_mfma_f32_16x16x32_bf16 v[2:5], v[178:181], v[220:223], v[2:5]
	s_barrier
	s_add_i32 s82, 0, 0x18000
	v_add_u32_e32 v130, s82, v143
	s_add_i32 s83, 0, 0x1c000
	ds_read_b128 v[150:153], v130
	ds_read_b128 v[154:157], v130 offset:1024
	ds_read_b128 v[158:161], v130 offset:2048
	ds_read_b128 v[162:165], v130 offset:3072
	v_add_u32_e32 v130, s83, v143
	ds_read_b128 v[166:169], v130
	ds_read_b128 v[170:173], v130 offset:1024
	ds_read_b128 v[174:177], v130 offset:2048
	ds_read_b128 v[178:181], v130 offset:3072
	s_add_u32 s58, s58, 0x80000
	s_addc_u32 s59, s59, 0
	s_mov_b32 m0, s23
	v_lshl_add_u64 v[230:231], s[58:59], 0, v[138:139]
	ds_read_b128 v[182:185], v145 offset:32768
	ds_read_b128 v[186:189], v145 offset:33792
	ds_read_b128 v[190:193], v145 offset:34816
	ds_read_b128 v[194:197], v145 offset:35840
	ds_read_b128 v[198:201], v145 offset:36864
	ds_read_b128 v[212:215], v145 offset:37888
	ds_read_b128 v[216:219], v145 offset:38912
	ds_read_b128 v[220:223], v145 offset:39936
	global_load_lds_dwordx4 v[230:231], off
	v_lshl_add_u64 v[230:231], s[58:59], 0, v[134:135]
	s_mov_b32 m0, s24
	s_nop 0
	global_load_lds_dwordx4 v[230:231], off
	s_waitcnt vmcnt(8)
	s_waitcnt lgkmcnt(0)
	s_barrier
	s_waitcnt lgkmcnt(0)
	v_mfma_f32_16x16x32_bf16 v[126:129], v[150:153], v[182:185], v[126:129]
	v_mfma_f32_16x16x32_bf16 v[122:125], v[158:161], v[182:185], v[122:125]
	v_mfma_f32_16x16x32_bf16 v[110:113], v[150:153], v[190:193], v[110:113]
	v_mfma_f32_16x16x32_bf16 v[106:109], v[158:161], v[190:193], v[106:109]
	v_mfma_f32_16x16x32_bf16 v[94:97], v[150:153], v[198:201], v[94:97]
	v_mfma_f32_16x16x32_bf16 v[90:93], v[158:161], v[198:201], v[90:93]
	v_mfma_f32_16x16x32_bf16 v[78:81], v[150:153], v[216:219], v[78:81]
	v_mfma_f32_16x16x32_bf16 v[74:77], v[158:161], v[216:219], v[74:77]
	v_mfma_f32_16x16x32_bf16 v[126:129], v[154:157], v[186:189], v[126:129]
	v_mfma_f32_16x16x32_bf16 v[122:125], v[162:165], v[186:189], v[122:125]
	v_mfma_f32_16x16x32_bf16 v[110:113], v[154:157], v[194:197], v[110:113]
	v_mfma_f32_16x16x32_bf16 v[106:109], v[162:165], v[194:197], v[106:109]
	v_mfma_f32_16x16x32_bf16 v[94:97], v[154:157], v[212:215], v[94:97]
	v_mfma_f32_16x16x32_bf16 v[90:93], v[162:165], v[212:215], v[90:93]
	v_mfma_f32_16x16x32_bf16 v[78:81], v[154:157], v[220:223], v[78:81]
	v_mfma_f32_16x16x32_bf16 v[74:77], v[162:165], v[220:223], v[74:77]
	v_mfma_f32_16x16x32_bf16 v[118:121], v[166:169], v[182:185], v[118:121]
	v_mfma_f32_16x16x32_bf16 v[114:117], v[174:177], v[182:185], v[114:117]
	v_mfma_f32_16x16x32_bf16 v[102:105], v[166:169], v[190:193], v[102:105]
	v_mfma_f32_16x16x32_bf16 v[98:101], v[174:177], v[190:193], v[98:101]
	v_mfma_f32_16x16x32_bf16 v[86:89], v[166:169], v[198:201], v[86:89]
	v_mfma_f32_16x16x32_bf16 v[82:85], v[174:177], v[198:201], v[82:85]
	v_mfma_f32_16x16x32_bf16 v[70:73], v[166:169], v[216:219], v[70:73]
	v_mfma_f32_16x16x32_bf16 v[66:69], v[174:177], v[216:219], v[66:69]
	v_mfma_f32_16x16x32_bf16 v[118:121], v[170:173], v[186:189], v[118:121]
	v_mfma_f32_16x16x32_bf16 v[114:117], v[178:181], v[186:189], v[114:117]
	v_mfma_f32_16x16x32_bf16 v[102:105], v[170:173], v[194:197], v[102:105]
	v_mfma_f32_16x16x32_bf16 v[98:101], v[178:181], v[194:197], v[98:101]
	v_mfma_f32_16x16x32_bf16 v[86:89], v[170:173], v[212:215], v[86:89]
	v_mfma_f32_16x16x32_bf16 v[82:85], v[178:181], v[212:215], v[82:85]
	v_mfma_f32_16x16x32_bf16 v[70:73], v[170:173], v[220:223], v[70:73]
	v_mfma_f32_16x16x32_bf16 v[66:69], v[178:181], v[220:223], v[66:69]
	s_barrier
; #define PG8_STAGE(bufoff, gbase, voff) do { _Pragma("unroll") for (int _i = 0; _i < 2; ++_i) \
;         __builtin_amdgcn_global_load_lds((const unsigned*)((const char*)(gbase) + (voff)[_i]), (LAS unsigned*)(lds + (bufoff) + ldsw + _i * 8192), 16, 0, 0); } while (0)
; #define PG8_LDA(dst, b, h) do { _Pragma("unroll") for (int m = 0; m < 4; ++m) _Pragma("unroll") for (int k = 0; k < 2; ++k) dst[m][k] = *(const LAS bf16x8*)(lds + PG8_SA(b, h) + aoff + m * 2048 + k * 1024); } while (0)
; #define PG8_MMA(ai, bj, At, Bt) do { __builtin_amdgcn_s_setprio(1); _Pragma("unroll") for (int m = 0; m < 4; ++m) _Pragma("unroll") for (int n = 0; n < 2; ++n) _Pragma("unroll") for (int k = 0; k < 2; ++k) \
;         acc[ai][bj][m][n] = mma16<I8>(Bt[n][k], At[m][k], acc[ai][bj][m][n]); __builtin_amdgcn_s_setprio(0); } while (0)
; #define PG8_WAIT_V(n) asm volatile("s_waitcnt vmcnt(" #n ")" ::: "memory")
; #define PG8_WAIT_L(n) asm volatile("s_waitcnt lgkmcnt(" #n ")" ::: "memory")
; #define PG8_BAR __builtin_amdgcn_s_barrier()
; #define PG8_SCHED __builtin_amdgcn_sched_barrier(0)
; template <class Epi, class Sched, bool I8 = false>
; __device__ __forceinline__ void gemm_phase(LAS unsigned char* lds, const Gemm g, const Sched& S, const Epi& E) {
;     ...
;             PG8_LDA(At, 1, 1); PG8_STAGE(PG8_SB(1, 0), b3, voffB); PG8_STAGE(PG8_SB(1, 1), b3 + hstepB, voffB); PG8_STAGE(PG8_SA(1, 0), a3, voffA);
;             PG8_WAIT_V(8); PG8_WAIT_L(0); PG8_BAR; PG8_MMA(1, 0, At, B0); PG8_MMA(1, 1, At, B1); PG8_BAR; PG8_SCHED;
	s_add_i32 s58, s82, s14
	v_lshl_add_u64 v[202:203], v[202:203], 0, s[12:13]
	s_mov_b32 m0, s58
	ds_read_b128 v[182:185], v145 offset:49152
	ds_read_b128 v[186:189], v145 offset:50176
	ds_read_b128 v[190:193], v145 offset:51200
	ds_read_b128 v[194:197], v145 offset:52224
	ds_read_b128 v[198:201], v145 offset:53248
	ds_read_b128 v[212:215], v145 offset:54272
	ds_read_b128 v[216:219], v145 offset:55296
	ds_read_b128 v[220:223], v145 offset:56320
	global_load_lds_dwordx4 v[202:203], off
	s_add_i32 m0, s58, 0x2000
	s_add_u32 s42, s42, 0x20080
	v_lshl_add_u64 v[202:203], v[224:225], 0, s[12:13]
	s_addc_u32 s43, s43, 0
	s_add_i32 s58, s83, s14
	global_load_lds_dwordx4 v[202:203], off
	v_lshl_add_u64 v[202:203], s[42:43], 0, v[136:137]
	s_mov_b32 m0, s58
	s_nop 0
	global_load_lds_dwordx4 v[202:203], off
	v_lshl_add_u64 v[202:203], s[42:43], 0, v[132:133]
	s_add_i32 m0, s58, 0x2000
	s_nop 0
	global_load_lds_dwordx4 v[202:203], off
	v_lshl_add_u64 v[202:203], v[226:227], 0, s[12:13]
	s_mov_b32 m0, s30
	s_nop 0
	global_load_lds_dwordx4 v[202:203], off
	v_lshl_add_u64 v[202:203], v[228:229], 0, s[12:13]
	s_mov_b32 m0, s31
	s_nop 0
	global_load_lds_dwordx4 v[202:203], off
	s_waitcnt vmcnt(8)
	s_waitcnt lgkmcnt(0)
	s_barrier
	s_waitcnt lgkmcnt(0)
	v_mfma_f32_16x16x32_bf16 v[62:65], v[150:153], v[182:185], v[62:65]
	v_mfma_f32_16x16x32_bf16 v[58:61], v[158:161], v[182:185], v[58:61]
	v_mfma_f32_16x16x32_bf16 v[46:49], v[150:153], v[190:193], v[46:49]
	v_mfma_f32_16x16x32_bf16 v[42:45], v[158:161], v[190:193], v[42:45]
	v_mfma_f32_16x16x32_bf16 v[30:33], v[150:153], v[198:201], v[30:33]
	v_mfma_f32_16x16x32_bf16 v[26:29], v[158:161], v[198:201], v[26:29]
	v_mfma_f32_16x16x32_bf16 v[14:17], v[150:153], v[216:219], v[14:17]
	v_mfma_f32_16x16x32_bf16 v[10:13], v[158:161], v[216:219], v[10:13]
	v_mfma_f32_16x16x32_bf16 v[62:65], v[154:157], v[186:189], v[62:65]
	v_mfma_f32_16x16x32_bf16 v[58:61], v[162:165], v[186:189], v[58:61]
	v_mfma_f32_16x16x32_bf16 v[46:49], v[154:157], v[194:197], v[46:49]
	v_mfma_f32_16x16x32_bf16 v[42:45], v[162:165], v[194:197], v[42:45]
	v_mfma_f32_16x16x32_bf16 v[30:33], v[154:157], v[212:215], v[30:33]
	v_mfma_f32_16x16x32_bf16 v[26:29], v[162:165], v[212:215], v[26:29]
	v_mfma_f32_16x16x32_bf16 v[14:17], v[154:157], v[220:223], v[14:17]
	v_mfma_f32_16x16x32_bf16 v[10:13], v[162:165], v[220:223], v[10:13]
	v_mfma_f32_16x16x32_bf16 v[54:57], v[166:169], v[182:185], v[54:57]
	v_mfma_f32_16x16x32_bf16 v[50:53], v[174:177], v[182:185], v[50:53]
	v_mfma_f32_16x16x32_bf16 v[38:41], v[166:169], v[190:193], v[38:41]
	v_mfma_f32_16x16x32_bf16 v[34:37], v[174:177], v[190:193], v[34:37]
	v_mfma_f32_16x16x32_bf16 v[22:25], v[166:169], v[198:201], v[22:25]
	v_mfma_f32_16x16x32_bf16 v[18:21], v[174:177], v[198:201], v[18:21]
	v_mfma_f32_16x16x32_bf16 v[6:9], v[166:169], v[216:219], v[6:9]
	v_mfma_f32_16x16x32_bf16 v[2:5], v[174:177], v[216:219], v[2:5]
	v_mfma_f32_16x16x32_bf16 v[54:57], v[170:173], v[186:189], v[54:57]
	v_mfma_f32_16x16x32_bf16 v[50:53], v[178:181], v[186:189], v[50:53]
	v_mfma_f32_16x16x32_bf16 v[38:41], v[170:173], v[194:197], v[38:41]
	v_mfma_f32_16x16x32_bf16 v[34:37], v[178:181], v[194:197], v[34:37]
	v_mfma_f32_16x16x32_bf16 v[22:25], v[170:173], v[212:215], v[22:25]
	v_mfma_f32_16x16x32_bf16 v[18:21], v[178:181], v[212:215], v[18:21]
	v_mfma_f32_16x16x32_bf16 v[6:9], v[170:173], v[220:223], v[6:9]
	v_mfma_f32_16x16x32_bf16 v[2:5], v[178:181], v[220:223], v[2:5]
	s_barrier
	s_add_u32 s40, s40, 0x100
	s_addc_u32 s41, s41, 0
	s_add_u32 s49, s49, 0x100
	s_addc_u32 s62, s62, 0
	s_cmp_ge_u32 s63, s39
	s_mov_b32 s58, s63
	s_cbranch_scc0 .LBB0_1153
	s_and_b64 vcc, exec, s[4:5]
	s_cbranch_vccz .LBB0_1156
	s_barrier

;     __device__ __forceinline__ bool next(int i, Unit& u) const { u.seg = 0; u.ks = -1; u.nt = ntk; u.koff = 0; return unit(i, u); }
;     __device__ __forceinline__ bool next(int i, Unit& u) const { const int t = i / 3; u.seg = i - 3 * t; u.ks = -1; u.nt = ntk; u.koff = 0; return unit(t, u); }
;     __device__ __forceinline__ bool next(int i, Unit& u) const { if (i > 0 || c < 80 || c >= 144) return false; const int k = c - 80; u.pm = k & 1; u.pn = k >> 1; u.seg = 0; u.ks = -1; u.nt = DM / BK; u.koff = 0; return true; }
; #define PG8_STAGE(bufoff, gbase, voff) do { _Pragma("unroll") for (int _i = 0; _i < 2; ++_i) \
;         __builtin_amdgcn_global_load_lds((const unsigned*)((const char*)(gbase) + (voff)[_i]), (LAS unsigned*)(lds + (bufoff) + ldsw + _i * 8192), 16, 0, 0); } while (0)
; #define PG8_LDA(dst, b, h) do { _Pragma("unroll") for (int m = 0; m < 4; ++m) _Pragma("unroll") for (int k = 0; k < 2; ++k) dst[m][k] = *(const LAS bf16x8*)(lds + PG8_SA(b, h) + aoff + m * 2048 + k * 1024); } while (0)
; template <class Epi, class Sched, bool I8 = false>
; __device__ __forceinline__ void gemm_phase(LAS unsigned char* lds, const Gemm g, const Sched& S, const Epi& E) {
;     ...
;         const bool has_next = S.next(ui + 1, nxt);
;         const char* nA = has_next ? g.A + (size_t)nxt.seg * g.segA + (size_t)nxt.pm * tstepA + nxt.koff : cA; const char* nB = has_next ? g.Bt + (size_t)nxt.seg * g.segB + (size_t)nxt.pn * tstepB + nxt.koff : cB;
;         const int nt = cur.nt;
;         for (int t = 0; t < nt; t += 2) {
;             const bool last = (t == nt - 2);
;             const char* a1 = cA + (size_t)(t + 1) * kstep;
;             const char* a2 = last ? nA : cA + (size_t)(t + 2) * kstep; const char* b2 = last ? nB : cB + (size_t)(t + 2) * kstep;
;             const char* a3 = a2 + kstep; const char* b3 = b2 + kstep;
;             if (PG8_SP2) {
;             PG8_LDB(B0, 0, 0); PG8_LDB(B1, 0, 1); PG8_SCHED; PG8_LDA(At, 0, 0); PG8_STAGE(PG8_SA(1, 1), a1 + hstepA, voffA);
;             PG8_WAIT_V(8); PG8_WAIT_L(0); PG8_BAR; PG8_MMA(0, 0, At, B0); PG8_MMA(0, 1, At, B1); PG8_BAR; PG8_SCHED;
;             PG8_LDA(At, 0, 1); PG8_STAGE(PG8_SB(0, 0), b2, voffB); PG8_STAGE(PG8_SB(0, 1), b2 + hstepB, voffB); PG8_STAGE(PG8_SA(0, 0), a2, voffA);
;             PG8_WAIT_V(8); PG8_WAIT_L(0); PG8_BAR; PG8_MMA(1, 0, At, B0); PG8_MMA(1, 1, At, B1); PG8_BAR; PG8_SCHED;
.LBB0_1336:
	s_add_u32 s40, s0, 0xfffc0080
	s_addc_u32 s41, s1, -1
	s_add_i32 s91, 0, 0x10000
	s_cmp_eq_u32 s90, 12
	s_cselect_b32 s43, s44, s41
	s_cselect_b32 s42, s45, s40
	v_add_u32_e32 v130, s91, v164
	s_cselect_b32 s41, s55, s83
	s_cselect_b32 s40, s57, s82
	s_add_i32 s96, 0, 0x14000
	ds_read_b128 v[114:117], v130
	ds_read_b128 v[118:121], v130 offset:1024
	ds_read_b128 v[126:129], v130 offset:2048
	ds_read_b128 v[136:139], v130 offset:3072
	v_add_u32_e32 v130, s96, v164
	ds_read_b128 v[166:169], v130
	ds_read_b128 v[170:173], v130 offset:1024
	ds_read_b128 v[174:177], v130 offset:2048
	ds_read_b128 v[178:181], v130 offset:3072
	v_lshl_add_u64 v[160:161], s[0:1], 0, v[156:157]
	s_add_i32 m0, s24, 0xc000
	ds_read_b128 v[182:185], v165
	ds_read_b128 v[186:189], v165 offset:1024
	ds_read_b128 v[190:193], v165 offset:2048
	ds_read_b128 v[194:197], v165 offset:3072
	ds_read_b128 v[198:201], v165 offset:4096
	ds_read_b128 v[212:215], v165 offset:5120
	ds_read_b128 v[216:219], v165 offset:6144
	ds_read_b128 v[220:223], v165 offset:7168
	global_load_lds_dwordx4 v[160:161], off
	v_lshl_add_u64 v[160:161], s[0:1], 0, v[158:159]
	s_add_i32 m0, s24, 0xe000
	s_nop 0
	global_load_lds_dwordx4 v[160:161], off
	s_waitcnt vmcnt(8)
	s_waitcnt lgkmcnt(0)
	s_barrier
	s_waitcnt lgkmcnt(0)
	v_mfma_i32_16x16x64_i8 v[144:147], v[114:117], v[182:185], v[144:147]
	v_mfma_i32_16x16x64_i8 v[140:143], v[126:129], v[182:185], v[140:143]
	v_mfma_i32_16x16x64_i8 v[110:113], v[114:117], v[190:193], v[110:113]
	v_mfma_i32_16x16x64_i8 v[106:109], v[126:129], v[190:193], v[106:109]
	v_mfma_i32_16x16x64_i8 v[94:97], v[114:117], v[198:201], v[94:97]
	v_mfma_i32_16x16x64_i8 v[90:93], v[126:129], v[198:201], v[90:93]
	v_mfma_i32_16x16x64_i8 v[78:81], v[114:117], v[216:219], v[78:81]
	v_mfma_i32_16x16x64_i8 v[74:77], v[126:129], v[216:219], v[74:77]
	v_mfma_i32_16x16x64_i8 v[144:147], v[118:121], v[186:189], v[144:147]
	v_mfma_i32_16x16x64_i8 v[140:143], v[136:139], v[186:189], v[140:143]
	v_mfma_i32_16x16x64_i8 v[110:113], v[118:121], v[194:197], v[110:113]
	v_mfma_i32_16x16x64_i8 v[106:109], v[136:139], v[194:197], v[106:109]
	v_mfma_i32_16x16x64_i8 v[94:97], v[118:121], v[212:215], v[94:97]
	v_mfma_i32_16x16x64_i8 v[90:93], v[136:139], v[212:215], v[90:93]
	v_mfma_i32_16x16x64_i8 v[78:81], v[118:121], v[220:223], v[78:81]
	v_mfma_i32_16x16x64_i8 v[74:77], v[136:139], v[220:223], v[74:77]
	v_mfma_i32_16x16x64_i8 v[132:135], v[166:169], v[182:185], v[132:135]
	v_mfma_i32_16x16x64_i8 v[122:125], v[174:177], v[182:185], v[122:125]
	v_mfma_i32_16x16x64_i8 v[102:105], v[166:169], v[190:193], v[102:105]
	v_mfma_i32_16x16x64_i8 v[98:101], v[174:177], v[190:193], v[98:101]
	v_mfma_i32_16x16x64_i8 v[86:89], v[166:169], v[198:201], v[86:89]
	v_mfma_i32_16x16x64_i8 v[82:85], v[174:177], v[198:201], v[82:85]
	v_mfma_i32_16x16x64_i8 v[70:73], v[166:169], v[216:219], v[70:73]
	v_mfma_i32_16x16x64_i8 v[66:69], v[174:177], v[216:219], v[66:69]
	v_mfma_i32_16x16x64_i8 v[132:135], v[170:173], v[186:189], v[132:135]
	v_mfma_i32_16x16x64_i8 v[122:125], v[178:181], v[186:189], v[122:125]
	v_mfma_i32_16x16x64_i8 v[102:105], v[170:173], v[194:197], v[102:105]
	v_mfma_i32_16x16x64_i8 v[98:101], v[178:181], v[194:197], v[98:101]
	v_mfma_i32_16x16x64_i8 v[86:89], v[170:173], v[212:215], v[86:89]
	v_mfma_i32_16x16x64_i8 v[82:85], v[178:181], v[212:215], v[82:85]
	v_mfma_i32_16x16x64_i8 v[70:73], v[170:173], v[220:223], v[70:73]
	v_mfma_i32_16x16x64_i8 v[66:69], v[178:181], v[220:223], v[66:69]
	s_barrier
	s_add_i32 s91, s91, s21
	v_lshl_add_u64 v[160:161], s[40:41], 0, v[152:153]
	s_mov_b32 m0, s91
	ds_read_b128 v[182:185], v165 offset:16384
	ds_read_b128 v[186:189], v165 offset:17408
	ds_read_b128 v[190:193], v165 offset:18432
	ds_read_b128 v[194:197], v165 offset:19456
	ds_read_b128 v[198:201], v165 offset:20480
	ds_read_b128 v[212:215], v165 offset:21504
	ds_read_b128 v[216:219], v165 offset:22528
	ds_read_b128 v[220:223], v165 offset:23552
	global_load_lds_dwordx4 v[160:161], off
	s_add_i32 m0, s91, 0x2000
	s_add_u32 s94, s40, 0x10000
	v_lshl_add_u64 v[202:203], s[40:41], 0, v[148:149]
	s_addc_u32 s95, s41, 0
	s_add_i32 s91, s96, s21
	global_load_lds_dwordx4 v[202:203], off
	v_lshl_add_u64 v[224:225], s[94:95], 0, v[152:153]
	s_mov_b32 m0, s91
	v_lshl_add_u64 v[226:227], s[42:43], 0, v[150:151]
	global_load_lds_dwordx4 v[224:225], off
	v_lshl_add_u64 v[224:225], s[94:95], 0, v[148:149]
	s_add_i32 m0, s91, 0x2000
	s_nop 0
	global_load_lds_dwordx4 v[224:225], off
	v_lshl_add_u64 v[224:225], s[42:43], 0, v[154:155]
	s_mov_b32 m0, s24
	s_nop 0
	global_load_lds_dwordx4 v[224:225], off
	s_mov_b32 m0, s25
	s_nop 0
	global_load_lds_dwordx4 v[226:227], off
	s_waitcnt vmcnt(8)
	s_waitcnt lgkmcnt(0)
	s_barrier
; #define PG8_STAGE(bufoff, gbase, voff) do { _Pragma("unroll") for (int _i = 0; _i < 2; ++_i) \
;         __builtin_amdgcn_global_load_lds((const unsigned*)((const char*)(gbase) + (voff)[_i]), (LAS unsigned*)(lds + (bufoff) + ldsw + _i * 8192), 16, 0, 0); } while (0)
; #define PG8_LDA(dst, b, h) do { _Pragma("unroll") for (int m = 0; m < 4; ++m) _Pragma("unroll") for (int k = 0; k < 2; ++k) dst[m][k] = *(const LAS bf16x8*)(lds + PG8_SA(b, h) + aoff + m * 2048 + k * 1024); } while (0)
; #define PG8_LDB(dst, b, h) do { _Pragma("unroll") for (int n = 0; n < 2; ++n) _Pragma("unroll") for (int k = 0; k < 2; ++k) dst[n][k] = *(const LAS bf16x8*)(lds + PG8_SB(b, h) + boff + n * 2048 + k * 1024); } while (0)
; #define PG8_MMA(ai, bj, At, Bt) do { __builtin_amdgcn_s_setprio(1); _Pragma("unroll") for (int m = 0; m < 4; ++m) _Pragma("unroll") for (int n = 0; n < 2; ++n) _Pragma("unroll") for (int k = 0; k < 2; ++k) \
;         acc[ai][bj][m][n] = mma16<I8>(Bt[n][k], At[m][k], acc[ai][bj][m][n]); __builtin_amdgcn_s_setprio(0); } while (0)
; #define PG8_WAIT_V(n) asm volatile("s_waitcnt vmcnt(" #n ")" ::: "memory")
; #define PG8_WAIT_L(n) asm volatile("s_waitcnt lgkmcnt(" #n ")" ::: "memory")
; #define PG8_BAR __builtin_amdgcn_s_barrier()
; #define PG8_SCHED __builtin_amdgcn_sched_barrier(0)
; template <class Epi, class Sched, bool I8 = false>
; __device__ __forceinline__ void gemm_phase(LAS unsigned char* lds, const Gemm g, const Sched& S, const Epi& E) {
;     ...
;             PG8_WAIT_V(8); PG8_WAIT_L(0); PG8_BAR; PG8_MMA(1, 0, At, B0); PG8_MMA(1, 1, At, B1); PG8_BAR; PG8_SCHED;
;             PG8_LDB(B0, 1, 0); PG8_LDB(B1, 1, 1); PG8_SCHED; PG8_LDA(At, 1, 0); PG8_STAGE(PG8_SA(0, 1), a2 + hstepA, voffA);
;             PG8_WAIT_V(8); PG8_WAIT_L(0); PG8_BAR; PG8_MMA(0, 0, At, B0); PG8_MMA(0, 1, At, B1); PG8_BAR; PG8_SCHED;
	s_waitcnt lgkmcnt(0)
	v_mfma_i32_16x16x64_i8 v[62:65], v[114:117], v[182:185], v[62:65]
	v_mfma_i32_16x16x64_i8 v[58:61], v[126:129], v[182:185], v[58:61]
	v_mfma_i32_16x16x64_i8 v[46:49], v[114:117], v[190:193], v[46:49]
	v_mfma_i32_16x16x64_i8 v[42:45], v[126:129], v[190:193], v[42:45]
	v_mfma_i32_16x16x64_i8 v[30:33], v[114:117], v[198:201], v[30:33]
	v_mfma_i32_16x16x64_i8 v[26:29], v[126:129], v[198:201], v[26:29]
	v_mfma_i32_16x16x64_i8 v[14:17], v[114:117], v[216:219], v[14:17]
	v_mfma_i32_16x16x64_i8 v[10:13], v[126:129], v[216:219], v[10:13]
	v_mfma_i32_16x16x64_i8 v[62:65], v[118:121], v[186:189], v[62:65]
	v_mfma_i32_16x16x64_i8 v[58:61], v[136:139], v[186:189], v[58:61]
	v_mfma_i32_16x16x64_i8 v[46:49], v[118:121], v[194:197], v[46:49]
	v_mfma_i32_16x16x64_i8 v[42:45], v[136:139], v[194:197], v[42:45]
	v_mfma_i32_16x16x64_i8 v[30:33], v[118:121], v[212:215], v[30:33]
	v_mfma_i32_16x16x64_i8 v[26:29], v[136:139], v[212:215], v[26:29]
	v_mfma_i32_16x16x64_i8 v[14:17], v[118:121], v[220:223], v[14:17]
	v_mfma_i32_16x16x64_i8 v[10:13], v[136:139], v[220:223], v[10:13]
	v_mfma_i32_16x16x64_i8 v[54:57], v[166:169], v[182:185], v[54:57]
	v_mfma_i32_16x16x64_i8 v[50:53], v[174:177], v[182:185], v[50:53]
	v_mfma_i32_16x16x64_i8 v[38:41], v[166:169], v[190:193], v[38:41]
	v_mfma_i32_16x16x64_i8 v[34:37], v[174:177], v[190:193], v[34:37]
	v_mfma_i32_16x16x64_i8 v[22:25], v[166:169], v[198:201], v[22:25]
	v_mfma_i32_16x16x64_i8 v[18:21], v[174:177], v[198:201], v[18:21]
	v_mfma_i32_16x16x64_i8 v[6:9], v[166:169], v[216:219], v[6:9]
	v_mfma_i32_16x16x64_i8 v[2:5], v[174:177], v[216:219], v[2:5]
	v_mfma_i32_16x16x64_i8 v[54:57], v[170:173], v[186:189], v[54:57]
	v_mfma_i32_16x16x64_i8 v[50:53], v[178:181], v[186:189], v[50:53]
	v_mfma_i32_16x16x64_i8 v[38:41], v[170:173], v[194:197], v[38:41]
	v_mfma_i32_16x16x64_i8 v[34:37], v[178:181], v[194:197], v[34:37]
	v_mfma_i32_16x16x64_i8 v[22:25], v[170:173], v[212:215], v[22:25]
	v_mfma_i32_16x16x64_i8 v[18:21], v[178:181], v[212:215], v[18:21]
	v_mfma_i32_16x16x64_i8 v[6:9], v[170:173], v[220:223], v[6:9]
	v_mfma_i32_16x16x64_i8 v[2:5], v[178:181], v[220:223], v[2:5]
	s_barrier
	s_add_i32 s91, 0, 0x18000
	v_add_u32_e32 v130, s91, v164
	s_add_i32 s94, 0, 0x1c000
	ds_read_b128 v[114:117], v130
	ds_read_b128 v[118:121], v130 offset:1024
	ds_read_b128 v[126:129], v130 offset:2048
	ds_read_b128 v[136:139], v130 offset:3072
	v_add_u32_e32 v130, s94, v164
	ds_read_b128 v[166:169], v130
	ds_read_b128 v[170:173], v130 offset:1024
	ds_read_b128 v[174:177], v130 offset:2048
	ds_read_b128 v[178:181], v130 offset:3072
	s_add_u32 s42, s42, 0x40000
	s_addc_u32 s43, s43, 0
	s_mov_b32 m0, s29
	v_lshl_add_u64 v[228:229], s[42:43], 0, v[154:155]
	ds_read_b128 v[182:185], v165 offset:32768
	ds_read_b128 v[186:189], v165 offset:33792
	ds_read_b128 v[190:193], v165 offset:34816
	ds_read_b128 v[194:197], v165 offset:35840
	ds_read_b128 v[198:201], v165 offset:36864
	ds_read_b128 v[212:215], v165 offset:37888
	ds_read_b128 v[216:219], v165 offset:38912
	ds_read_b128 v[220:223], v165 offset:39936
	global_load_lds_dwordx4 v[228:229], off
	v_lshl_add_u64 v[228:229], s[42:43], 0, v[150:151]
	s_mov_b32 m0, s30
	s_nop 0
	global_load_lds_dwordx4 v[228:229], off
	s_waitcnt vmcnt(8)
	s_waitcnt lgkmcnt(0)
	s_barrier
	s_waitcnt lgkmcnt(0)
	v_mfma_i32_16x16x64_i8 v[144:147], v[114:117], v[182:185], v[144:147]
	v_mfma_i32_16x16x64_i8 v[140:143], v[126:129], v[182:185], v[140:143]
	v_mfma_i32_16x16x64_i8 v[110:113], v[114:117], v[190:193], v[110:113]
	v_mfma_i32_16x16x64_i8 v[106:109], v[126:129], v[190:193], v[106:109]
	v_mfma_i32_16x16x64_i8 v[94:97], v[114:117], v[198:201], v[94:97]
	v_mfma_i32_16x16x64_i8 v[90:93], v[126:129], v[198:201], v[90:93]
	v_mfma_i32_16x16x64_i8 v[78:81], v[114:117], v[216:219], v[78:81]
	v_mfma_i32_16x16x64_i8 v[74:77], v[126:129], v[216:219], v[74:77]
	v_mfma_i32_16x16x64_i8 v[144:147], v[118:121], v[186:189], v[144:147]
	v_mfma_i32_16x16x64_i8 v[140:143], v[136:139], v[186:189], v[140:143]
	v_mfma_i32_16x16x64_i8 v[110:113], v[118:121], v[194:197], v[110:113]
	v_mfma_i32_16x16x64_i8 v[106:109], v[136:139], v[194:197], v[106:109]
	v_mfma_i32_16x16x64_i8 v[94:97], v[118:121], v[212:215], v[94:97]
	v_mfma_i32_16x16x64_i8 v[90:93], v[136:139], v[212:215], v[90:93]
	v_mfma_i32_16x16x64_i8 v[78:81], v[118:121], v[220:223], v[78:81]
	v_mfma_i32_16x16x64_i8 v[74:77], v[136:139], v[220:223], v[74:77]
	v_mfma_i32_16x16x64_i8 v[132:135], v[166:169], v[182:185], v[132:135]
	v_mfma_i32_16x16x64_i8 v[122:125], v[174:177], v[182:185], v[122:125]
	v_mfma_i32_16x16x64_i8 v[102:105], v[166:169], v[190:193], v[102:105]
	v_mfma_i32_16x16x64_i8 v[98:101], v[174:177], v[190:193], v[98:101]
	v_mfma_i32_16x16x64_i8 v[86:89], v[166:169], v[198:201], v[86:89]
	v_mfma_i32_16x16x64_i8 v[82:85], v[174:177], v[198:201], v[82:85]
	v_mfma_i32_16x16x64_i8 v[70:73], v[166:169], v[216:219], v[70:73]
	v_mfma_i32_16x16x64_i8 v[66:69], v[174:177], v[216:219], v[66:69]
	v_mfma_i32_16x16x64_i8 v[132:135], v[170:173], v[186:189], v[132:135]
	v_mfma_i32_16x16x64_i8 v[122:125], v[178:181], v[186:189], v[122:125]
	v_mfma_i32_16x16x64_i8 v[102:105], v[170:173], v[194:197], v[102:105]
	v_mfma_i32_16x16x64_i8 v[98:101], v[178:181], v[194:197], v[98:101]
	v_mfma_i32_16x16x64_i8 v[86:89], v[170:173], v[212:215], v[86:89]
	v_mfma_i32_16x16x64_i8 v[82:85], v[178:181], v[212:215], v[82:85]
	v_mfma_i32_16x16x64_i8 v[70:73], v[170:173], v[220:223], v[70:73]
	v_mfma_i32_16x16x64_i8 v[66:69], v[178:181], v[220:223], v[66:69]
	s_barrier
; #define PG8_STAGE(bufoff, gbase, voff) do { _Pragma("unroll") for (int _i = 0; _i < 2; ++_i) \
;         __builtin_amdgcn_global_load_lds((const unsigned*)((const char*)(gbase) + (voff)[_i]), (LAS unsigned*)(lds + (bufoff) + ldsw + _i * 8192), 16, 0, 0); } while (0)
; #define PG8_LDA(dst, b, h) do { _Pragma("unroll") for (int m = 0; m < 4; ++m) _Pragma("unroll") for (int k = 0; k < 2; ++k) dst[m][k] = *(const LAS bf16x8*)(lds + PG8_SA(b, h) + aoff + m * 2048 + k * 1024); } while (0)
; #define PG8_MMA(ai, bj, At, Bt) do { __builtin_amdgcn_s_setprio(1); _Pragma("unroll") for (int m = 0; m < 4; ++m) _Pragma("unroll") for (int n = 0; n < 2; ++n) _Pragma("unroll") for (int k = 0; k < 2; ++k) \
;         acc[ai][bj][m][n] = mma16<I8>(Bt[n][k], At[m][k], acc[ai][bj][m][n]); __builtin_amdgcn_s_setprio(0); } while (0)
; #define PG8_WAIT_V(n) asm volatile("s_waitcnt vmcnt(" #n ")" ::: "memory")
; #define PG8_WAIT_L(n) asm volatile("s_waitcnt lgkmcnt(" #n ")" ::: "memory")
; #define PG8_BAR __builtin_amdgcn_s_barrier()
; #define PG8_SCHED __builtin_amdgcn_sched_barrier(0)
; template <class Epi, class Sched, bool I8 = false>
; __device__ __forceinline__ void gemm_phase(LAS unsigned char* lds, const Gemm g, const Sched& S, const Epi& E) {
;     ...
;             PG8_LDA(At, 1, 1); PG8_STAGE(PG8_SB(1, 0), b3, voffB); PG8_STAGE(PG8_SB(1, 1), b3 + hstepB, voffB); PG8_STAGE(PG8_SA(1, 0), a3, voffA);
;             PG8_WAIT_V(8); PG8_WAIT_L(0); PG8_BAR; PG8_MMA(1, 0, At, B0); PG8_MMA(1, 1, At, B1); PG8_BAR; PG8_SCHED;
	s_add_i32 s42, s91, s21
	v_lshl_add_u64 v[160:161], v[160:161], 0, s[12:13]
	s_mov_b32 m0, s42
	ds_read_b128 v[182:185], v165 offset:49152
	ds_read_b128 v[186:189], v165 offset:50176
	ds_read_b128 v[190:193], v165 offset:51200
	ds_read_b128 v[194:197], v165 offset:52224
	ds_read_b128 v[198:201], v165 offset:53248
	ds_read_b128 v[212:215], v165 offset:54272
	ds_read_b128 v[216:219], v165 offset:55296
	ds_read_b128 v[220:223], v165 offset:56320
	global_load_lds_dwordx4 v[160:161], off
	s_add_i32 m0, s42, 0x2000
	s_add_u32 s40, s40, 0x10080
	v_lshl_add_u64 v[160:161], v[202:203], 0, s[12:13]
	s_addc_u32 s41, s41, 0
	s_add_i32 s42, s94, s21
	global_load_lds_dwordx4 v[160:161], off
	v_lshl_add_u64 v[160:161], s[40:41], 0, v[152:153]
	s_mov_b32 m0, s42
	s_nop 0
	global_load_lds_dwordx4 v[160:161], off
	v_lshl_add_u64 v[160:161], s[40:41], 0, v[148:149]
	s_add_i32 m0, s42, 0x2000
	s_nop 0
	global_load_lds_dwordx4 v[160:161], off
	v_lshl_add_u64 v[160:161], v[224:225], 0, s[12:13]
	s_mov_b32 m0, s49
	s_nop 0
	global_load_lds_dwordx4 v[160:161], off
	v_lshl_add_u64 v[160:161], v[226:227], 0, s[12:13]
	s_mov_b32 m0, s80
	s_nop 0
	global_load_lds_dwordx4 v[160:161], off
	s_waitcnt vmcnt(8)
	s_waitcnt lgkmcnt(0)
	s_barrier
	s_waitcnt lgkmcnt(0)
	v_mfma_i32_16x16x64_i8 v[62:65], v[114:117], v[182:185], v[62:65]
	v_mfma_i32_16x16x64_i8 v[58:61], v[126:129], v[182:185], v[58:61]
	v_mfma_i32_16x16x64_i8 v[46:49], v[114:117], v[190:193], v[46:49]
	v_mfma_i32_16x16x64_i8 v[42:45], v[126:129], v[190:193], v[42:45]
	v_mfma_i32_16x16x64_i8 v[30:33], v[114:117], v[198:201], v[30:33]
	v_mfma_i32_16x16x64_i8 v[26:29], v[126:129], v[198:201], v[26:29]
	v_mfma_i32_16x16x64_i8 v[14:17], v[114:117], v[216:219], v[14:17]
	v_mfma_i32_16x16x64_i8 v[10:13], v[126:129], v[216:219], v[10:13]
	v_mfma_i32_16x16x64_i8 v[62:65], v[118:121], v[186:189], v[62:65]
	v_mfma_i32_16x16x64_i8 v[58:61], v[136:139], v[186:189], v[58:61]
	v_mfma_i32_16x16x64_i8 v[46:49], v[118:121], v[194:197], v[46:49]
	v_mfma_i32_16x16x64_i8 v[42:45], v[136:139], v[194:197], v[42:45]
	v_mfma_i32_16x16x64_i8 v[30:33], v[118:121], v[212:215], v[30:33]
	v_mfma_i32_16x16x64_i8 v[26:29], v[136:139], v[212:215], v[26:29]
	v_mfma_i32_16x16x64_i8 v[14:17], v[118:121], v[220:223], v[14:17]
	v_mfma_i32_16x16x64_i8 v[10:13], v[136:139], v[220:223], v[10:13]
	v_mfma_i32_16x16x64_i8 v[54:57], v[166:169], v[182:185], v[54:57]
	v_mfma_i32_16x16x64_i8 v[50:53], v[174:177], v[182:185], v[50:53]
	v_mfma_i32_16x16x64_i8 v[38:41], v[166:169], v[190:193], v[38:41]
	v_mfma_i32_16x16x64_i8 v[34:37], v[174:177], v[190:193], v[34:37]
	v_mfma_i32_16x16x64_i8 v[22:25], v[166:169], v[198:201], v[22:25]
	v_mfma_i32_16x16x64_i8 v[18:21], v[174:177], v[198:201], v[18:21]
	v_mfma_i32_16x16x64_i8 v[6:9], v[166:169], v[216:219], v[6:9]
	v_mfma_i32_16x16x64_i8 v[2:5], v[174:177], v[216:219], v[2:5]
	v_mfma_i32_16x16x64_i8 v[54:57], v[170:173], v[186:189], v[54:57]
	v_mfma_i32_16x16x64_i8 v[50:53], v[178:181], v[186:189], v[50:53]
	v_mfma_i32_16x16x64_i8 v[38:41], v[170:173], v[194:197], v[38:41]
	v_mfma_i32_16x16x64_i8 v[34:37], v[178:181], v[194:197], v[34:37]
	v_mfma_i32_16x16x64_i8 v[22:25], v[170:173], v[212:215], v[22:25]
	v_mfma_i32_16x16x64_i8 v[18:21], v[178:181], v[212:215], v[18:21]
	v_mfma_i32_16x16x64_i8 v[6:9], v[170:173], v[220:223], v[6:9]
	v_mfma_i32_16x16x64_i8 v[2:5], v[178:181], v[220:223], v[2:5]
	s_barrier
	s_add_i32 s90, s90, 2
	s_add_u32 s0, s0, 0x100
	s_addc_u32 s1, s1, 0
	s_add_u32 s82, s82, 0x100
	s_addc_u32 s83, s83, 0
	s_cmp_gt_u32 s90, 13
	s_cbranch_scc0 .LBB0_1336
	s_and_b64 vcc, exec, s[6:7]
	s_cbranch_vccz .LBB0_1339
	s_barrier

;     __device__ __forceinline__ bool next(int i, Unit& u) const { u.seg = 0; u.ks = -1; u.nt = ntk; u.koff = 0; return unit(i, u); }
;     __device__ __forceinline__ bool next(int i, Unit& u) const { const int t = i / 3; u.seg = i - 3 * t; u.ks = -1; u.nt = ntk; u.koff = 0; return unit(t, u); }
;     __device__ __forceinline__ bool next(int i, Unit& u) const { if (i > 0 || c < 80 || c >= 144) return false; const int k = c - 80; u.pm = k & 1; u.pn = k >> 1; u.seg = 0; u.ks = -1; u.nt = DM / BK; u.koff = 0; return true; }
; #define PG8_STAGE(bufoff, gbase, voff) do { _Pragma("unroll") for (int _i = 0; _i < 2; ++_i) \
;         __builtin_amdgcn_global_load_lds((const unsigned*)((const char*)(gbase) + (voff)[_i]), (LAS unsigned*)(lds + (bufoff) + ldsw + _i * 8192), 16, 0, 0); } while (0)
; #define PG8_LDA(dst, b, h) do { _Pragma("unroll") for (int m = 0; m < 4; ++m) _Pragma("unroll") for (int k = 0; k < 2; ++k) dst[m][k] = *(const LAS bf16x8*)(lds + PG8_SA(b, h) + aoff + m * 2048 + k * 1024); } while (0)
; template <class Epi, class Sched, bool I8 = false>
; __device__ __forceinline__ void gemm_phase(LAS unsigned char* lds, const Gemm g, const Sched& S, const Epi& E) {
;     ...
;         const bool has_next = S.next(ui + 1, nxt);
;         const char* nA = has_next ? g.A + (size_t)nxt.seg * g.segA + (size_t)nxt.pm * tstepA + nxt.koff : cA; const char* nB = has_next ? g.Bt + (size_t)nxt.seg * g.segB + (size_t)nxt.pn * tstepB + nxt.koff : cB;
;         const int nt = cur.nt;
;         for (int t = 0; t < nt; t += 2) {
;             const bool last = (t == nt - 2);
;             const char* a1 = cA + (size_t)(t + 1) * kstep;
;             const char* a2 = last ? nA : cA + (size_t)(t + 2) * kstep; const char* b2 = last ? nB : cB + (size_t)(t + 2) * kstep;
;             const char* a3 = a2 + kstep; const char* b3 = b2 + kstep;
;             if (PG8_SP2) {
;             PG8_LDB(B0, 0, 0); PG8_LDB(B1, 0, 1); PG8_SCHED; PG8_LDA(At, 0, 0); PG8_STAGE(PG8_SA(1, 1), a1 + hstepA, voffA);
;             PG8_WAIT_V(8); PG8_WAIT_L(0); PG8_BAR; PG8_MMA(0, 0, At, B0); PG8_MMA(0, 1, At, B1); PG8_BAR; PG8_SCHED;
;             PG8_LDA(At, 0, 1); PG8_STAGE(PG8_SB(0, 0), b2, voffB); PG8_STAGE(PG8_SB(0, 1), b2 + hstepB, voffB); PG8_STAGE(PG8_SA(0, 0), a2, voffA);
;             PG8_WAIT_V(8); PG8_WAIT_L(0); PG8_BAR; PG8_MMA(1, 0, At, B0); PG8_MMA(1, 1, At, B1); PG8_BAR; PG8_SCHED;
.LBB0_1574:
	s_add_i32 s80, s42, 2
	s_add_u32 s40, s0, 0xfff00080
	s_addc_u32 s41, s1, -1
	s_add_i32 s82, 0, 0x10000
	s_cmp_eq_u32 s56, s42
	s_cselect_b32 s43, s23, s41
	s_cselect_b32 s42, s44, s40
	s_cselect_b32 s41, s45, s63
	s_cselect_b32 s40, s46, s57
	s_add_i32 s91, 0, 0x14000
	v_add_u32_e32 v62, s82, v175
	v_add_u32_e32 v78, s91, v175
	ds_read_b128 v[50:53], v62
	ds_read_b128 v[54:57], v62 offset:1024
	ds_read_b128 v[58:61], v62 offset:2048
	ds_read_b128 v[62:65], v62 offset:3072
	ds_read_b128 v[66:69], v78
	ds_read_b128 v[70:73], v78 offset:1024
	ds_read_b128 v[74:77], v78 offset:2048
	ds_read_b128 v[78:81], v78 offset:3072
	v_lshl_add_u64 v[202:203], s[0:1], 0, v[178:179]
	s_add_i32 m0, s34, 0xc000
	ds_read_b128 v[182:185], v177
	ds_read_b128 v[186:189], v177 offset:1024
	ds_read_b128 v[190:193], v177 offset:2048
	ds_read_b128 v[194:197], v177 offset:3072
	ds_read_b128 v[198:201], v177 offset:4096
	ds_read_b128 v[212:215], v177 offset:5120
	ds_read_b128 v[216:219], v177 offset:6144
	ds_read_b128 v[220:223], v177 offset:7168
	global_load_lds_dwordx4 v[202:203], off
	v_lshl_add_u64 v[202:203], s[0:1], 0, v[180:181]
	s_add_i32 m0, s34, 0xe000
	s_nop 0
	global_load_lds_dwordx4 v[202:203], off
	s_waitcnt vmcnt(8)
	s_waitcnt lgkmcnt(0)
	s_barrier
	s_waitcnt lgkmcnt(0)
	v_mfma_i32_16x16x64_i8 v[160:163], v[50:53], v[182:185], v[160:163]
	v_mfma_i32_16x16x64_i8 v[156:159], v[58:61], v[182:185], v[156:159]
	v_mfma_i32_16x16x64_i8 v[144:147], v[50:53], v[190:193], v[144:147]
	v_mfma_i32_16x16x64_i8 v[140:143], v[58:61], v[190:193], v[140:143]
	v_mfma_i32_16x16x64_i8 v[126:129], v[50:53], v[198:201], v[126:129]
	v_mfma_i32_16x16x64_i8 v[122:125], v[58:61], v[198:201], v[122:125]
	v_mfma_i32_16x16x64_i8 v[110:113], v[50:53], v[216:219], v[110:113]
	v_mfma_i32_16x16x64_i8 v[106:109], v[58:61], v[216:219], v[106:109]
	v_mfma_i32_16x16x64_i8 v[160:163], v[54:57], v[186:189], v[160:163]
	v_mfma_i32_16x16x64_i8 v[156:159], v[62:65], v[186:189], v[156:159]
	v_mfma_i32_16x16x64_i8 v[144:147], v[54:57], v[194:197], v[144:147]
	v_mfma_i32_16x16x64_i8 v[140:143], v[62:65], v[194:197], v[140:143]
	v_mfma_i32_16x16x64_i8 v[126:129], v[54:57], v[212:215], v[126:129]
	v_mfma_i32_16x16x64_i8 v[122:125], v[62:65], v[212:215], v[122:125]
	v_mfma_i32_16x16x64_i8 v[110:113], v[54:57], v[220:223], v[110:113]
	v_mfma_i32_16x16x64_i8 v[106:109], v[62:65], v[220:223], v[106:109]
	v_mfma_i32_16x16x64_i8 v[152:155], v[66:69], v[182:185], v[152:155]
	v_mfma_i32_16x16x64_i8 v[148:151], v[74:77], v[182:185], v[148:151]
	v_mfma_i32_16x16x64_i8 v[136:139], v[66:69], v[190:193], v[136:139]
	v_mfma_i32_16x16x64_i8 v[132:135], v[74:77], v[190:193], v[132:135]
	v_mfma_i32_16x16x64_i8 v[118:121], v[66:69], v[198:201], v[118:121]
	v_mfma_i32_16x16x64_i8 v[114:117], v[74:77], v[198:201], v[114:117]
	v_mfma_i32_16x16x64_i8 v[102:105], v[66:69], v[216:219], v[102:105]
	v_mfma_i32_16x16x64_i8 v[98:101], v[74:77], v[216:219], v[98:101]
	v_mfma_i32_16x16x64_i8 v[152:155], v[70:73], v[186:189], v[152:155]
	v_mfma_i32_16x16x64_i8 v[148:151], v[78:81], v[186:189], v[148:151]
	v_mfma_i32_16x16x64_i8 v[136:139], v[70:73], v[194:197], v[136:139]
	v_mfma_i32_16x16x64_i8 v[132:135], v[78:81], v[194:197], v[132:135]
	v_mfma_i32_16x16x64_i8 v[118:121], v[70:73], v[212:215], v[118:121]
	v_mfma_i32_16x16x64_i8 v[114:117], v[78:81], v[212:215], v[114:117]
	v_mfma_i32_16x16x64_i8 v[102:105], v[70:73], v[220:223], v[102:105]
	v_mfma_i32_16x16x64_i8 v[98:101], v[78:81], v[220:223], v[98:101]
	s_barrier
	s_add_i32 s82, s82, s85
	v_lshl_add_u64 v[202:203], s[40:41], 0, v[168:169]
	s_mov_b32 m0, s82
	ds_read_b128 v[182:185], v177 offset:16384
	ds_read_b128 v[186:189], v177 offset:17408
	ds_read_b128 v[190:193], v177 offset:18432
	ds_read_b128 v[194:197], v177 offset:19456
	ds_read_b128 v[198:201], v177 offset:20480
	ds_read_b128 v[212:215], v177 offset:21504
	ds_read_b128 v[216:219], v177 offset:22528
	ds_read_b128 v[220:223], v177 offset:23552
	global_load_lds_dwordx4 v[202:203], off
	s_add_i32 m0, s82, 0x2000
	s_add_u32 s82, s40, 0x40000
	v_lshl_add_u64 v[228:229], s[40:41], 0, v[164:165]
	s_addc_u32 s83, s41, 0
	s_add_i32 s91, s91, s85
	global_load_lds_dwordx4 v[228:229], off
	v_lshl_add_u64 v[224:225], s[82:83], 0, v[168:169]
	s_mov_b32 m0, s91
	v_lshl_add_u64 v[230:231], s[42:43], 0, v[170:171]
	global_load_lds_dwordx4 v[224:225], off
	v_lshl_add_u64 v[224:225], s[82:83], 0, v[164:165]
	s_add_i32 m0, s91, 0x2000
	v_lshl_add_u64 v[232:233], s[42:43], 0, v[166:167]
	global_load_lds_dwordx4 v[224:225], off
	s_mov_b32 m0, s34
	s_nop 0
	global_load_lds_dwordx4 v[230:231], off
	s_mov_b32 m0, s35
	s_nop 0
	global_load_lds_dwordx4 v[232:233], off
	s_waitcnt vmcnt(8)
	s_waitcnt lgkmcnt(0)
	s_barrier
; #define PG8_STAGE(bufoff, gbase, voff) do { _Pragma("unroll") for (int _i = 0; _i < 2; ++_i) \
;         __builtin_amdgcn_global_load_lds((const unsigned*)((const char*)(gbase) + (voff)[_i]), (LAS unsigned*)(lds + (bufoff) + ldsw + _i * 8192), 16, 0, 0); } while (0)
; #define PG8_LDA(dst, b, h) do { _Pragma("unroll") for (int m = 0; m < 4; ++m) _Pragma("unroll") for (int k = 0; k < 2; ++k) dst[m][k] = *(const LAS bf16x8*)(lds + PG8_SA(b, h) + aoff + m * 2048 + k * 1024); } while (0)
; #define PG8_LDB(dst, b, h) do { _Pragma("unroll") for (int n = 0; n < 2; ++n) _Pragma("unroll") for (int k = 0; k < 2; ++k) dst[n][k] = *(const LAS bf16x8*)(lds + PG8_SB(b, h) + boff + n * 2048 + k * 1024); } while (0)
; #define PG8_MMA(ai, bj, At, Bt) do { __builtin_amdgcn_s_setprio(1); _Pragma("unroll") for (int m = 0; m < 4; ++m) _Pragma("unroll") for (int n = 0; n < 2; ++n) _Pragma("unroll") for (int k = 0; k < 2; ++k) \
;         acc[ai][bj][m][n] = mma16<I8>(Bt[n][k], At[m][k], acc[ai][bj][m][n]); __builtin_amdgcn_s_setprio(0); } while (0)
; #define PG8_WAIT_V(n) asm volatile("s_waitcnt vmcnt(" #n ")" ::: "memory")
; #define PG8_WAIT_L(n) asm volatile("s_waitcnt lgkmcnt(" #n ")" ::: "memory")
; template <class Epi, class Sched, bool I8 = false>
; __device__ __forceinline__ void gemm_phase(LAS unsigned char* lds, const Gemm g, const Sched& S, const Epi& E) {
;     ...
;             PG8_LDB(B0, 0, 0); PG8_LDB(B1, 0, 1); PG8_SCHED; PG8_LDA(At, 0, 0); PG8_STAGE(PG8_SA(1, 1), a1 + hstepA, voffA);
;             PG8_WAIT_V(8); PG8_WAIT_L(0); PG8_BAR; PG8_MMA(0, 0, At, B0); PG8_MMA(0, 1, At, B1); PG8_BAR; PG8_SCHED;
;             PG8_LDA(At, 0, 1); PG8_STAGE(PG8_SB(0, 0), b2, voffB); PG8_STAGE(PG8_SB(0, 1), b2 + hstepB, voffB); PG8_STAGE(PG8_SA(0, 0), a2, voffA);
;             PG8_WAIT_V(8); PG8_WAIT_L(0); PG8_BAR; PG8_MMA(1, 0, At, B0); PG8_MMA(1, 1, At, B1); PG8_BAR; PG8_SCHED;
;             PG8_LDB(B0, 1, 0); PG8_LDB(B1, 1, 1); PG8_SCHED; PG8_LDA(At, 1, 0); PG8_STAGE(PG8_SA(0, 1), a2 + hstepA, voffA);
;             PG8_WAIT_V(8); PG8_WAIT_L(0); PG8_BAR; PG8_MMA(0, 0, At, B0); PG8_MMA(0, 1, At, B1); PG8_BAR; PG8_SCHED;
;             PG8_LDA(At, 1, 1); PG8_STAGE(PG8_SB(1, 0), b3, voffB); PG8_STAGE(PG8_SB(1, 1), b3 + hstepB, voffB); PG8_STAGE(PG8_SA(1, 0), a3, voffA);
;             PG8_WAIT_V(8); PG8_WAIT_L(0); PG8_BAR; PG8_MMA(1, 0, At, B0); PG8_MMA(1, 1, At, B1); PG8_BAR; PG8_SCHED;
	s_waitcnt lgkmcnt(0)
	v_mfma_i32_16x16x64_i8 v[94:97], v[50:53], v[182:185], v[94:97]
	v_mfma_i32_16x16x64_i8 v[90:93], v[58:61], v[182:185], v[90:93]
	v_mfma_i32_16x16x64_i8 v[46:49], v[50:53], v[190:193], v[46:49]
	v_mfma_i32_16x16x64_i8 v[42:45], v[58:61], v[190:193], v[42:45]
	v_mfma_i32_16x16x64_i8 v[30:33], v[50:53], v[198:201], v[30:33]
	v_mfma_i32_16x16x64_i8 v[26:29], v[58:61], v[198:201], v[26:29]
	v_mfma_i32_16x16x64_i8 v[14:17], v[50:53], v[216:219], v[14:17]
	v_mfma_i32_16x16x64_i8 v[10:13], v[58:61], v[216:219], v[10:13]
	v_mfma_i32_16x16x64_i8 v[94:97], v[54:57], v[186:189], v[94:97]
	v_mfma_i32_16x16x64_i8 v[90:93], v[62:65], v[186:189], v[90:93]
	v_mfma_i32_16x16x64_i8 v[46:49], v[54:57], v[194:197], v[46:49]
	v_mfma_i32_16x16x64_i8 v[42:45], v[62:65], v[194:197], v[42:45]
	v_mfma_i32_16x16x64_i8 v[30:33], v[54:57], v[212:215], v[30:33]
	v_mfma_i32_16x16x64_i8 v[26:29], v[62:65], v[212:215], v[26:29]
	v_mfma_i32_16x16x64_i8 v[14:17], v[54:57], v[220:223], v[14:17]
	v_mfma_i32_16x16x64_i8 v[10:13], v[62:65], v[220:223], v[10:13]
	v_mfma_i32_16x16x64_i8 v[38:41], v[66:69], v[190:193], v[38:41]
	v_mfma_i32_16x16x64_i8 v[34:37], v[74:77], v[190:193], v[34:37]
	v_mfma_i32_16x16x64_i8 v[22:25], v[66:69], v[198:201], v[22:25]
	v_mfma_i32_16x16x64_i8 v[18:21], v[74:77], v[198:201], v[18:21]
	v_mfma_i32_16x16x64_i8 v[6:9], v[66:69], v[216:219], v[6:9]
	v_mfma_i32_16x16x64_i8 v[2:5], v[74:77], v[216:219], v[2:5]
	v_mfma_i32_16x16x64_i8 v[50:53], v[66:69], v[182:185], v[86:89]
	v_mfma_i32_16x16x64_i8 v[54:57], v[74:77], v[182:185], v[82:85]
	v_mfma_i32_16x16x64_i8 v[38:41], v[70:73], v[194:197], v[38:41]
	v_mfma_i32_16x16x64_i8 v[34:37], v[78:81], v[194:197], v[34:37]
	v_mfma_i32_16x16x64_i8 v[22:25], v[70:73], v[212:215], v[22:25]
	v_mfma_i32_16x16x64_i8 v[18:21], v[78:81], v[212:215], v[18:21]
	v_mfma_i32_16x16x64_i8 v[6:9], v[70:73], v[220:223], v[6:9]
	v_mfma_i32_16x16x64_i8 v[2:5], v[78:81], v[220:223], v[2:5]
	v_mfma_i32_16x16x64_i8 v[50:53], v[70:73], v[186:189], v[50:53]
	v_mfma_i32_16x16x64_i8 v[54:57], v[78:81], v[186:189], v[54:57]
	s_barrier
	s_add_i32 s82, 0, 0x18000
	s_add_i32 s83, 0, 0x1c000
	v_add_u32_e32 v70, s82, v175
	v_add_u32_e32 v82, s83, v175
	ds_read_b128 v[58:61], v70
	ds_read_b128 v[62:65], v70 offset:1024
	ds_read_b128 v[66:69], v70 offset:2048
	ds_read_b128 v[70:73], v70 offset:3072
	ds_read_b128 v[74:77], v82
	ds_read_b128 v[78:81], v82 offset:1024
	ds_read_b128 v[182:185], v82 offset:2048
	ds_read_b128 v[186:189], v82 offset:3072
	s_add_u32 s42, s42, 0x100000
	s_addc_u32 s43, s43, 0
	s_mov_b32 m0, s30
	v_lshl_add_u64 v[224:225], s[42:43], 0, v[170:171]
	ds_read_b128 v[82:85], v177 offset:32768
	ds_read_b128 v[86:89], v177 offset:33792
	ds_read_b128 v[190:193], v177 offset:34816
	ds_read_b128 v[194:197], v177 offset:35840
	ds_read_b128 v[198:201], v177 offset:36864
	ds_read_b128 v[212:215], v177 offset:37888
	ds_read_b128 v[216:219], v177 offset:38912
	ds_read_b128 v[220:223], v177 offset:39936
	global_load_lds_dwordx4 v[224:225], off
	v_lshl_add_u64 v[224:225], s[42:43], 0, v[166:167]
	s_mov_b32 m0, s31
	s_nop 0
	global_load_lds_dwordx4 v[224:225], off
	s_waitcnt vmcnt(8)
	s_waitcnt lgkmcnt(0)
	s_barrier
	s_waitcnt lgkmcnt(0)
	v_mfma_i32_16x16x64_i8 v[160:163], v[58:61], v[82:85], v[160:163]
	v_mfma_i32_16x16x64_i8 v[156:159], v[66:69], v[82:85], v[156:159]
	v_mfma_i32_16x16x64_i8 v[144:147], v[58:61], v[190:193], v[144:147]
	v_mfma_i32_16x16x64_i8 v[140:143], v[66:69], v[190:193], v[140:143]
	v_mfma_i32_16x16x64_i8 v[126:129], v[58:61], v[198:201], v[126:129]
	v_mfma_i32_16x16x64_i8 v[122:125], v[66:69], v[198:201], v[122:125]
	v_mfma_i32_16x16x64_i8 v[110:113], v[58:61], v[216:219], v[110:113]
	v_mfma_i32_16x16x64_i8 v[106:109], v[66:69], v[216:219], v[106:109]
	v_mfma_i32_16x16x64_i8 v[160:163], v[62:65], v[86:89], v[160:163]
	v_mfma_i32_16x16x64_i8 v[156:159], v[70:73], v[86:89], v[156:159]
	v_mfma_i32_16x16x64_i8 v[144:147], v[62:65], v[194:197], v[144:147]
	v_mfma_i32_16x16x64_i8 v[140:143], v[70:73], v[194:197], v[140:143]
	v_mfma_i32_16x16x64_i8 v[126:129], v[62:65], v[212:215], v[126:129]
	v_mfma_i32_16x16x64_i8 v[122:125], v[70:73], v[212:215], v[122:125]
	v_mfma_i32_16x16x64_i8 v[110:113], v[62:65], v[220:223], v[110:113]
	v_mfma_i32_16x16x64_i8 v[106:109], v[70:73], v[220:223], v[106:109]
	v_mfma_i32_16x16x64_i8 v[152:155], v[74:77], v[82:85], v[152:155]
	v_mfma_i32_16x16x64_i8 v[82:85], v[182:185], v[82:85], v[148:151]
	v_mfma_i32_16x16x64_i8 v[148:151], v[186:189], v[86:89], v[82:85]
	v_mfma_i32_16x16x64_i8 v[82:85], v[74:77], v[190:193], v[136:139]
	v_mfma_i32_16x16x64_i8 v[136:139], v[78:81], v[194:197], v[82:85]
	v_mfma_i32_16x16x64_i8 v[82:85], v[182:185], v[190:193], v[132:135]
	v_mfma_i32_16x16x64_i8 v[132:135], v[186:189], v[194:197], v[82:85]
	v_mfma_i32_16x16x64_i8 v[82:85], v[74:77], v[198:201], v[118:121]
	v_mfma_i32_16x16x64_i8 v[118:121], v[78:81], v[212:215], v[82:85]
	v_mfma_i32_16x16x64_i8 v[82:85], v[182:185], v[198:201], v[114:117]
	v_mfma_i32_16x16x64_i8 v[114:117], v[186:189], v[212:215], v[82:85]
	v_mfma_i32_16x16x64_i8 v[82:85], v[74:77], v[216:219], v[102:105]
	v_mfma_i32_16x16x64_i8 v[102:105], v[78:81], v[220:223], v[82:85]
	v_mfma_i32_16x16x64_i8 v[82:85], v[182:185], v[216:219], v[98:101]
	v_mfma_i32_16x16x64_i8 v[152:155], v[78:81], v[86:89], v[152:155]
	v_mfma_i32_16x16x64_i8 v[98:101], v[186:189], v[220:223], v[82:85]
	s_barrier
; #define PG8_STAGE(bufoff, gbase, voff) do { _Pragma("unroll") for (int _i = 0; _i < 2; ++_i) \
;         __builtin_amdgcn_global_load_lds((const unsigned*)((const char*)(gbase) + (voff)[_i]), (LAS unsigned*)(lds + (bufoff) + ldsw + _i * 8192), 16, 0, 0); } while (0)
; #define PG8_LDA(dst, b, h) do { _Pragma("unroll") for (int m = 0; m < 4; ++m) _Pragma("unroll") for (int k = 0; k < 2; ++k) dst[m][k] = *(const LAS bf16x8*)(lds + PG8_SA(b, h) + aoff + m * 2048 + k * 1024); } while (0)
; #define PG8_WAIT_V(n) asm volatile("s_waitcnt vmcnt(" #n ")" ::: "memory")
; #define PG8_BAR __builtin_amdgcn_s_barrier()
; template <class Epi, class Sched, bool I8 = false>
; __device__ __forceinline__ void gemm_phase(LAS unsigned char* lds, const Gemm g, const Sched& S, const Epi& E) {
;     ...
;             PG8_LDA(At, 1, 1); PG8_STAGE(PG8_SB(1, 0), b3, voffB); PG8_STAGE(PG8_SB(1, 1), b3 + hstepB, voffB); PG8_STAGE(PG8_SA(1, 0), a3, voffA);
;             PG8_WAIT_V(8); PG8_WAIT_L(0); PG8_BAR; PG8_MMA(1, 0, At, B0); PG8_MMA(1, 1, At, B1); PG8_BAR; PG8_SCHED;
;             } else {
;             PG8_LDB(B0, 0, 0); PG8_SCHED; PG8_LDA(At, 0, 0); PG8_STAGE(PG8_SA(1, 1), a1 + hstepA, voffA);
;             PG8_WAIT_L(8); PG8_BAR; PG8_WAIT_L(0); PG8_MMA(0, 0, At, B0); PG8_BAR; PG8_SCHED;
;             PG8_LDB(B1, 0, 1); PG8_STAGE(PG8_SB(0, 0), b2, voffB);
;             PG8_BAR; PG8_WAIT_L(0); PG8_MMA(0, 1, At, B1); PG8_BAR;
;             PG8_LDA(At, 0, 1); PG8_STAGE(PG8_SA(0, 0), a2, voffA);
;             PG8_BAR; PG8_WAIT_L(0); PG8_MMA(1, 0, At, B0); PG8_BAR; PG8_SCHED;
;             PG8_STAGE(PG8_SB(0, 1), b2 + hstepB, voffB);
;             PG8_WAIT_V(6); PG8_BAR; PG8_MMA(1, 1, At, B1); PG8_BAR;
;             PG8_LDB(B0, 1, 0); PG8_SCHED; PG8_LDA(At, 1, 0); PG8_STAGE(PG8_SA(0, 1), a2 + hstepA, voffA);
;             PG8_WAIT_L(8); PG8_BAR; PG8_WAIT_L(0); PG8_MMA(0, 0, At, B0); PG8_BAR; PG8_SCHED;
;             PG8_LDB(B1, 1, 1); PG8_STAGE(PG8_SB(1, 0), b3, voffB);
;             PG8_BAR; PG8_WAIT_L(0); PG8_MMA(0, 1, At, B1); PG8_BAR;
;             PG8_LDA(At, 1, 1); PG8_STAGE(PG8_SA(1, 0), a3, voffA);
;             PG8_BAR; PG8_WAIT_L(0); PG8_MMA(1, 0, At, B0); PG8_BAR; PG8_SCHED;
;             PG8_STAGE(PG8_SB(1, 1), b3 + hstepB, voffB);
;             PG8_WAIT_V(6); PG8_BAR; PG8_MMA(1, 1, At, B1); PG8_BAR;
;             }
;         }
;         if (PG8_ALIGN) { if (wr == 0) PG8_BAR; }
	s_add_i32 s42, s82, s85
	v_lshl_add_u64 v[86:87], v[202:203], 0, s[12:13]
	s_mov_b32 m0, s42
	s_nop 0
	ds_read_b128 v[82:85], v177 offset:49152
	ds_read_b128 v[190:193], v177 offset:50176
	ds_read_b128 v[194:197], v177 offset:51200
	ds_read_b128 v[198:201], v177 offset:52224
	ds_read_b128 v[212:215], v177 offset:53248
	ds_read_b128 v[216:219], v177 offset:54272
	ds_read_b128 v[220:223], v177 offset:55296
	ds_read_b128 v[224:227], v177 offset:56320
	global_load_lds_dwordx4 v[86:87], off
	s_add_i32 m0, s42, 0x2000
	s_add_u32 s40, s40, 0x40080
	v_lshl_add_u64 v[86:87], v[228:229], 0, s[12:13]
	s_addc_u32 s41, s41, 0
	s_add_i32 s42, s83, s85
	global_load_lds_dwordx4 v[86:87], off
	v_lshl_add_u64 v[86:87], s[40:41], 0, v[168:169]
	s_mov_b32 m0, s42
	s_nop 0
	global_load_lds_dwordx4 v[86:87], off
	v_lshl_add_u64 v[86:87], s[40:41], 0, v[164:165]
	s_add_i32 m0, s42, 0x2000
	s_nop 0
	global_load_lds_dwordx4 v[86:87], off
	v_lshl_add_u64 v[86:87], v[230:231], 0, s[12:13]
	s_mov_b32 m0, s3
	s_nop 0
	global_load_lds_dwordx4 v[86:87], off
	v_lshl_add_u64 v[86:87], v[232:233], 0, s[12:13]
	s_mov_b32 m0, s2
	s_nop 0
	global_load_lds_dwordx4 v[86:87], off
	s_waitcnt vmcnt(8)
	s_waitcnt lgkmcnt(0)
	s_barrier
	s_waitcnt lgkmcnt(0)
	v_mfma_i32_16x16x64_i8 v[86:89], v[58:61], v[82:85], v[94:97]
	v_mfma_i32_16x16x64_i8 v[94:97], v[62:65], v[190:193], v[86:89]
	v_mfma_i32_16x16x64_i8 v[86:89], v[66:69], v[82:85], v[90:93]
	v_mfma_i32_16x16x64_i8 v[46:49], v[58:61], v[194:197], v[46:49]
	v_mfma_i32_16x16x64_i8 v[42:45], v[66:69], v[194:197], v[42:45]
	v_mfma_i32_16x16x64_i8 v[30:33], v[58:61], v[212:215], v[30:33]
	v_mfma_i32_16x16x64_i8 v[26:29], v[66:69], v[212:215], v[26:29]
	v_mfma_i32_16x16x64_i8 v[14:17], v[58:61], v[220:223], v[14:17]
	v_mfma_i32_16x16x64_i8 v[10:13], v[66:69], v[220:223], v[10:13]
	v_mfma_i32_16x16x64_i8 v[90:93], v[70:73], v[190:193], v[86:89]
	v_mfma_i32_16x16x64_i8 v[46:49], v[62:65], v[198:201], v[46:49]
	v_mfma_i32_16x16x64_i8 v[42:45], v[70:73], v[198:201], v[42:45]
	v_mfma_i32_16x16x64_i8 v[30:33], v[62:65], v[216:219], v[30:33]
	v_mfma_i32_16x16x64_i8 v[26:29], v[70:73], v[216:219], v[26:29]
	v_mfma_i32_16x16x64_i8 v[14:17], v[62:65], v[224:227], v[14:17]
	v_mfma_i32_16x16x64_i8 v[10:13], v[70:73], v[224:227], v[10:13]
	v_mfma_i32_16x16x64_i8 v[50:53], v[74:77], v[82:85], v[50:53]
	v_mfma_i32_16x16x64_i8 v[86:89], v[78:81], v[190:193], v[50:53]
	v_mfma_i32_16x16x64_i8 v[50:53], v[182:185], v[82:85], v[54:57]
	v_mfma_i32_16x16x64_i8 v[38:41], v[74:77], v[194:197], v[38:41]
	v_mfma_i32_16x16x64_i8 v[34:37], v[182:185], v[194:197], v[34:37]
	v_mfma_i32_16x16x64_i8 v[22:25], v[74:77], v[212:215], v[22:25]
	v_mfma_i32_16x16x64_i8 v[18:21], v[182:185], v[212:215], v[18:21]
	v_mfma_i32_16x16x64_i8 v[6:9], v[74:77], v[220:223], v[6:9]
	v_mfma_i32_16x16x64_i8 v[2:5], v[182:185], v[220:223], v[2:5]
	v_mfma_i32_16x16x64_i8 v[82:85], v[186:189], v[190:193], v[50:53]
	v_mfma_i32_16x16x64_i8 v[38:41], v[78:81], v[198:201], v[38:41]
	v_mfma_i32_16x16x64_i8 v[34:37], v[186:189], v[198:201], v[34:37]
	v_mfma_i32_16x16x64_i8 v[22:25], v[78:81], v[216:219], v[22:25]
	v_mfma_i32_16x16x64_i8 v[18:21], v[186:189], v[216:219], v[18:21]
	v_mfma_i32_16x16x64_i8 v[6:9], v[78:81], v[224:227], v[6:9]
	v_mfma_i32_16x16x64_i8 v[2:5], v[186:189], v[224:227], v[2:5]
	s_barrier
	s_add_u32 s0, s0, 0x100
	s_addc_u32 s1, s1, 0
	s_add_u32 s57, s57, 0x100
	s_addc_u32 s63, s63, 0
	s_cmp_ge_u32 s80, s22
	s_mov_b32 s42, s80
	s_cbranch_scc0 .LBB0_1574
	s_and_b64 vcc, exec, s[36:37]
	s_cbranch_vccz .LBB0_1577
	s_barrier
